# GEMM k-loops rotated: taken back-edge moved from the head of the 16-read load segment to the head of the 8-read one
# speedup vs baseline: 1.0051x; 1.0051x over previous
; #define PG8_STAGE(bufoff, gbase, voff) do { _Pragma("unroll") for (int _i = 0; _i < 2; ++_i) \
;         __builtin_amdgcn_global_load_lds((const unsigned*)((const char*)(gbase) + (voff)[_i]), (LAS unsigned*)(lds + (bufoff) + ldsw + _i * 8192), 16, 0, 0); } while (0)
; #define PG8_LDA(dst, b, h) do { _Pragma("unroll") for (int m = 0; m < 4; ++m) _Pragma("unroll") for (int k = 0; k < 2; ++k) dst[m][k] = *(const LAS bf16x8*)(lds + PG8_SA(b, h) + aoff + m * 2048 + k * 1024); } while (0)
; #define PG8_LDB(dst, b, h) do { _Pragma("unroll") for (int n = 0; n < 2; ++n) _Pragma("unroll") for (int k = 0; k < 2; ++k) dst[n][k] = *(const LAS bf16x8*)(lds + PG8_SB(b, h) + boff + n * 2048 + k * 1024); } while (0)
; #define PG8_MMA(ai, bj, At, Bt) do { __builtin_amdgcn_s_setprio(1); _Pragma("unroll") for (int m = 0; m < 4; ++m) _Pragma("unroll") for (int n = 0; n < 2; ++n) _Pragma("unroll") for (int k = 0; k < 2; ++k) \
;         acc[ai][bj][m][n] = __builtin_amdgcn_mfma_f32_16x16x32_bf16(Bt[n][k], At[m][k], acc[ai][bj][m][n], 0, 0, 0); __builtin_amdgcn_s_setprio(0); } while (0)
; #define PG8_WAIT_V(n) asm volatile("s_waitcnt vmcnt(" #n ")" ::: "memory")
; #define PG8_WAIT_L(n) asm volatile("s_waitcnt lgkmcnt(" #n ")" ::: "memory")
; #define PG8_BAR __builtin_amdgcn_s_barrier()
; #define PG8_SCHED __builtin_amdgcn_sched_barrier(0)
; template <class EpiT>
; __device__ __forceinline__ void gemm_phase(LAS unsigned char* lds, const Gemm g, const StaticOrder& S, const EpiT& E) {
;     ...
;             PG8_LDB(B0, 0, 0); PG8_LDB(B1, 0, 1); PG8_SCHED; PG8_LDA(At, 0, 0); PG8_STAGE(PG8_SA(1, 1), a1 + hstepA, voffA);
;             PG8_WAIT_V(8); PG8_WAIT_L(0); PG8_BAR; PG8_MMA(0, 0, At, B0); PG8_MMA(0, 1, At, B1); PG8_BAR; PG8_SCHED;
;             PG8_LDA(At, 0, 1); PG8_STAGE(PG8_SB(0, 0), b2, voffB); PG8_STAGE(PG8_SB(0, 1), b2 + hstepB, voffB); PG8_STAGE(PG8_SA(0, 0), a2, voffA);
.LBB0_100:
	ds_read_b128 v[128:131], v160
	ds_read_b128 v[170:173], v160 offset:1024
	ds_read_b128 v[174:177], v160 offset:2048
	ds_read_b128 v[178:181], v160 offset:3072
	ds_read_b128 v[182:185], v161
	ds_read_b128 v[186:189], v161 offset:1024
	ds_read_b128 v[190:193], v161 offset:2048
	ds_read_b128 v[194:197], v161 offset:3072
	s_add_u32 s18, s16, 0xfff7c080
	s_addc_u32 s19, s17, -1
	s_cmp_eq_u32 s53, 28
	s_cselect_b32 s21, s3, s19
	s_cselect_b32 s20, s2, s18
	s_cselect_b32 s19, s15, s52
	s_cselect_b32 s18, s14, s51
	v_lshl_add_u64 v[158:159], s[16:17], 0, v[150:151]
	s_add_i32 m0, s35, 0xc000
	ds_read_b128 v[198:201], v162
	ds_read_b128 v[202:205], v162 offset:1024
	ds_read_b128 v[206:209], v162 offset:2048
	ds_read_b128 v[210:213], v162 offset:3072
	ds_read_b128 v[214:217], v162 offset:4096
	ds_read_b128 v[218:221], v162 offset:5120
	ds_read_b128 v[222:225], v162 offset:6144
	ds_read_b128 v[226:229], v162 offset:7168
	global_load_lds_dwordx4 v[158:159], off
	v_lshl_add_u64 v[158:159], s[16:17], 0, v[152:153]
	s_add_i32 m0, s35, 0xe000
	s_nop 0
	global_load_lds_dwordx4 v[158:159], off
	s_waitcnt vmcnt(8)
	s_waitcnt lgkmcnt(0)
	s_barrier
	s_setprio 1
	s_waitcnt lgkmcnt(0)
	v_mfma_f32_16x16x32_bf16 v[124:127], v[128:131], v[198:201], v[124:127]
	v_mfma_f32_16x16x32_bf16 v[124:127], v[170:173], v[202:205], v[124:127]
	v_mfma_f32_16x16x32_bf16 v[108:111], v[128:131], v[206:209], v[108:111]
	v_mfma_f32_16x16x32_bf16 v[108:111], v[170:173], v[210:213], v[108:111]
	v_mfma_f32_16x16x32_bf16 v[92:95], v[128:131], v[214:217], v[92:95]
	v_mfma_f32_16x16x32_bf16 v[92:95], v[170:173], v[218:221], v[92:95]
	v_mfma_f32_16x16x32_bf16 v[76:79], v[128:131], v[222:225], v[76:79]
	v_mfma_f32_16x16x32_bf16 v[76:79], v[170:173], v[226:229], v[76:79]
	v_mfma_f32_16x16x32_bf16 v[120:123], v[174:177], v[198:201], v[120:123]
	v_mfma_f32_16x16x32_bf16 v[120:123], v[178:181], v[202:205], v[120:123]
	v_mfma_f32_16x16x32_bf16 v[104:107], v[174:177], v[206:209], v[104:107]
	v_mfma_f32_16x16x32_bf16 v[104:107], v[178:181], v[210:213], v[104:107]
	v_mfma_f32_16x16x32_bf16 v[88:91], v[174:177], v[214:217], v[88:91]
	v_mfma_f32_16x16x32_bf16 v[88:91], v[178:181], v[218:221], v[88:91]
	v_mfma_f32_16x16x32_bf16 v[72:75], v[174:177], v[222:225], v[72:75]
	v_mfma_f32_16x16x32_bf16 v[72:75], v[178:181], v[226:229], v[72:75]
	s_setprio 0
	s_setprio 1
	v_mfma_f32_16x16x32_bf16 v[116:119], v[182:185], v[198:201], v[116:119]
	v_mfma_f32_16x16x32_bf16 v[116:119], v[186:189], v[202:205], v[116:119]
	v_mfma_f32_16x16x32_bf16 v[100:103], v[182:185], v[206:209], v[100:103]
	v_mfma_f32_16x16x32_bf16 v[100:103], v[186:189], v[210:213], v[100:103]
	v_mfma_f32_16x16x32_bf16 v[84:87], v[182:185], v[214:217], v[84:87]
	v_mfma_f32_16x16x32_bf16 v[84:87], v[186:189], v[218:221], v[84:87]
	v_mfma_f32_16x16x32_bf16 v[68:71], v[182:185], v[222:225], v[68:71]
	v_mfma_f32_16x16x32_bf16 v[68:71], v[186:189], v[226:229], v[68:71]
	v_mfma_f32_16x16x32_bf16 v[112:115], v[190:193], v[198:201], v[112:115]
	v_mfma_f32_16x16x32_bf16 v[112:115], v[194:197], v[202:205], v[112:115]
	v_mfma_f32_16x16x32_bf16 v[96:99], v[190:193], v[206:209], v[96:99]
	v_mfma_f32_16x16x32_bf16 v[96:99], v[194:197], v[210:213], v[96:99]
	v_mfma_f32_16x16x32_bf16 v[80:83], v[190:193], v[214:217], v[80:83]
	v_mfma_f32_16x16x32_bf16 v[80:83], v[194:197], v[218:221], v[80:83]
	v_mfma_f32_16x16x32_bf16 v[64:67], v[190:193], v[222:225], v[64:67]
	v_mfma_f32_16x16x32_bf16 v[64:67], v[194:197], v[226:229], v[64:67]
	s_setprio 0
	s_barrier
.Lrot_100:
	s_add_i32 s54, s43, s25
	v_lshl_add_u64 v[158:159], s[18:19], 0, v[136:137]
	s_mov_b32 m0, s54
	ds_read_b128 v[198:201], v162 offset:16384
	ds_read_b128 v[202:205], v162 offset:17408
	ds_read_b128 v[206:209], v162 offset:18432
	ds_read_b128 v[210:213], v162 offset:19456
	ds_read_b128 v[214:217], v162 offset:20480
	ds_read_b128 v[218:221], v162 offset:21504
	ds_read_b128 v[222:225], v162 offset:22528
	ds_read_b128 v[226:229], v162 offset:23552
	global_load_lds_dwordx4 v[158:159], off
	s_add_i32 m0, s54, 0x2000
	s_add_u32 s54, s18, 0x84000
	v_lshl_add_u64 v[166:167], s[18:19], 0, v[132:133]
	s_addc_u32 s55, s19, 0
	s_add_i32 s56, s44, s25
	global_load_lds_dwordx4 v[166:167], off
	v_lshl_add_u64 v[230:231], s[54:55], 0, v[136:137]
	s_mov_b32 m0, s56
	v_lshl_add_u64 v[232:233], s[20:21], 0, v[134:135]
	global_load_lds_dwordx4 v[230:231], off
	v_lshl_add_u64 v[230:231], s[54:55], 0, v[132:133]
	s_add_i32 m0, s56, 0x2000
	s_nop 0
	global_load_lds_dwordx4 v[230:231], off
	v_lshl_add_u64 v[230:231], s[20:21], 0, v[138:139]
	s_mov_b32 m0, s35
	s_nop 0
	global_load_lds_dwordx4 v[230:231], off
	s_mov_b32 m0, s36
	s_nop 0
	global_load_lds_dwordx4 v[232:233], off
	s_waitcnt vmcnt(8)
	s_waitcnt lgkmcnt(0)
	s_barrier
; #define PG8_STAGE(bufoff, gbase, voff) do { _Pragma("unroll") for (int _i = 0; _i < 2; ++_i) \
;         __builtin_amdgcn_global_load_lds((const unsigned*)((const char*)(gbase) + (voff)[_i]), (LAS unsigned*)(lds + (bufoff) + ldsw + _i * 8192), 16, 0, 0); } while (0)
; #define PG8_LDA(dst, b, h) do { _Pragma("unroll") for (int m = 0; m < 4; ++m) _Pragma("unroll") for (int k = 0; k < 2; ++k) dst[m][k] = *(const LAS bf16x8*)(lds + PG8_SA(b, h) + aoff + m * 2048 + k * 1024); } while (0)
; #define PG8_LDB(dst, b, h) do { _Pragma("unroll") for (int n = 0; n < 2; ++n) _Pragma("unroll") for (int k = 0; k < 2; ++k) dst[n][k] = *(const LAS bf16x8*)(lds + PG8_SB(b, h) + boff + n * 2048 + k * 1024); } while (0)
; #define PG8_MMA(ai, bj, At, Bt) do { __builtin_amdgcn_s_setprio(1); _Pragma("unroll") for (int m = 0; m < 4; ++m) _Pragma("unroll") for (int n = 0; n < 2; ++n) _Pragma("unroll") for (int k = 0; k < 2; ++k) \
;         acc[ai][bj][m][n] = __builtin_amdgcn_mfma_f32_16x16x32_bf16(Bt[n][k], At[m][k], acc[ai][bj][m][n], 0, 0, 0); __builtin_amdgcn_s_setprio(0); } while (0)
; #define PG8_WAIT_V(n) asm volatile("s_waitcnt vmcnt(" #n ")" ::: "memory")
; #define PG8_WAIT_L(n) asm volatile("s_waitcnt lgkmcnt(" #n ")" ::: "memory")
; #define PG8_BAR __builtin_amdgcn_s_barrier()
; #define PG8_SCHED __builtin_amdgcn_sched_barrier(0)
; template <class EpiT>
; __device__ __forceinline__ void gemm_phase(LAS unsigned char* lds, const Gemm g, const StaticOrder& S, const EpiT& E) {
;     ...
;             PG8_WAIT_V(8); PG8_WAIT_L(0); PG8_BAR; PG8_MMA(1, 0, At, B0); PG8_MMA(1, 1, At, B1); PG8_BAR; PG8_SCHED;
;             PG8_LDB(B0, 1, 0); PG8_LDB(B1, 1, 1); PG8_SCHED; PG8_LDA(At, 1, 0); PG8_STAGE(PG8_SA(0, 1), a2 + hstepA, voffA);
;             PG8_WAIT_V(8); PG8_WAIT_L(0); PG8_BAR; PG8_MMA(0, 0, At, B0); PG8_MMA(0, 1, At, B1); PG8_BAR; PG8_SCHED;
	s_setprio 1
	s_waitcnt lgkmcnt(0)
	v_mfma_f32_16x16x32_bf16 v[60:63], v[128:131], v[198:201], v[60:63]
	v_mfma_f32_16x16x32_bf16 v[60:63], v[170:173], v[202:205], v[60:63]
	v_mfma_f32_16x16x32_bf16 v[44:47], v[128:131], v[206:209], v[44:47]
	v_mfma_f32_16x16x32_bf16 v[44:47], v[170:173], v[210:213], v[44:47]
	v_mfma_f32_16x16x32_bf16 v[28:31], v[128:131], v[214:217], v[28:31]
	v_mfma_f32_16x16x32_bf16 v[28:31], v[170:173], v[218:221], v[28:31]
	v_mfma_f32_16x16x32_bf16 v[12:15], v[128:131], v[222:225], v[12:15]
	v_mfma_f32_16x16x32_bf16 v[12:15], v[170:173], v[226:229], v[12:15]
	v_mfma_f32_16x16x32_bf16 v[56:59], v[174:177], v[198:201], v[56:59]
	v_mfma_f32_16x16x32_bf16 v[56:59], v[178:181], v[202:205], v[56:59]
	v_mfma_f32_16x16x32_bf16 v[40:43], v[174:177], v[206:209], v[40:43]
	v_mfma_f32_16x16x32_bf16 v[40:43], v[178:181], v[210:213], v[40:43]
	v_mfma_f32_16x16x32_bf16 v[24:27], v[174:177], v[214:217], v[24:27]
	v_mfma_f32_16x16x32_bf16 v[24:27], v[178:181], v[218:221], v[24:27]
	v_mfma_f32_16x16x32_bf16 v[8:11], v[174:177], v[222:225], v[8:11]
	v_mfma_f32_16x16x32_bf16 v[8:11], v[178:181], v[226:229], v[8:11]
	s_setprio 0
	s_setprio 1
	v_mfma_f32_16x16x32_bf16 v[52:55], v[182:185], v[198:201], v[52:55]
	v_mfma_f32_16x16x32_bf16 v[52:55], v[186:189], v[202:205], v[52:55]
	v_mfma_f32_16x16x32_bf16 v[36:39], v[182:185], v[206:209], v[36:39]
	v_mfma_f32_16x16x32_bf16 v[36:39], v[186:189], v[210:213], v[36:39]
	v_mfma_f32_16x16x32_bf16 v[20:23], v[182:185], v[214:217], v[20:23]
	v_mfma_f32_16x16x32_bf16 v[20:23], v[186:189], v[218:221], v[20:23]
	v_mfma_f32_16x16x32_bf16 v[4:7], v[182:185], v[222:225], v[4:7]
	v_mfma_f32_16x16x32_bf16 v[4:7], v[186:189], v[226:229], v[4:7]
	v_mfma_f32_16x16x32_bf16 v[48:51], v[190:193], v[198:201], v[48:51]
	v_mfma_f32_16x16x32_bf16 v[48:51], v[194:197], v[202:205], v[48:51]
	v_mfma_f32_16x16x32_bf16 v[32:35], v[190:193], v[206:209], v[32:35]
	v_mfma_f32_16x16x32_bf16 v[32:35], v[194:197], v[210:213], v[32:35]
	v_mfma_f32_16x16x32_bf16 v[16:19], v[190:193], v[214:217], v[16:19]
	v_mfma_f32_16x16x32_bf16 v[16:19], v[194:197], v[218:221], v[16:19]
	v_mfma_f32_16x16x32_bf16 v[0:3], v[190:193], v[222:225], v[0:3]
	v_mfma_f32_16x16x32_bf16 v[0:3], v[194:197], v[226:229], v[0:3]
	s_setprio 0
	s_barrier
	s_add_i32 s54, 0, 0x18000
	v_add_u32_e32 v140, s54, v145
	s_add_i32 s55, 0, 0x1c000
	ds_read_b128 v[128:131], v140
	ds_read_b128 v[170:173], v140 offset:1024
	ds_read_b128 v[174:177], v140 offset:2048
	ds_read_b128 v[178:181], v140 offset:3072
	v_add_u32_e32 v140, s55, v145
	ds_read_b128 v[182:185], v140
	ds_read_b128 v[186:189], v140 offset:1024
	ds_read_b128 v[190:193], v140 offset:2048
	ds_read_b128 v[194:197], v140 offset:3072
	s_add_u32 s20, s20, 0x84000
	s_addc_u32 s21, s21, 0
	s_mov_b32 m0, s37
	v_lshl_add_u64 v[234:235], s[20:21], 0, v[138:139]
	ds_read_b128 v[198:201], v162 offset:32768
	ds_read_b128 v[202:205], v162 offset:33792
	ds_read_b128 v[206:209], v162 offset:34816
	ds_read_b128 v[210:213], v162 offset:35840
	ds_read_b128 v[214:217], v162 offset:36864
	ds_read_b128 v[218:221], v162 offset:37888
	ds_read_b128 v[222:225], v162 offset:38912
	ds_read_b128 v[226:229], v162 offset:39936
	global_load_lds_dwordx4 v[234:235], off
	v_lshl_add_u64 v[234:235], s[20:21], 0, v[134:135]
	s_mov_b32 m0, s38
	s_nop 0
	global_load_lds_dwordx4 v[234:235], off
	s_waitcnt vmcnt(8)
	s_waitcnt lgkmcnt(0)
	s_barrier
	s_setprio 1
	s_waitcnt lgkmcnt(0)
	v_mfma_f32_16x16x32_bf16 v[124:127], v[128:131], v[198:201], v[124:127]
	v_mfma_f32_16x16x32_bf16 v[124:127], v[170:173], v[202:205], v[124:127]
	v_mfma_f32_16x16x32_bf16 v[108:111], v[128:131], v[206:209], v[108:111]
	v_mfma_f32_16x16x32_bf16 v[108:111], v[170:173], v[210:213], v[108:111]
	v_mfma_f32_16x16x32_bf16 v[92:95], v[128:131], v[214:217], v[92:95]
	v_mfma_f32_16x16x32_bf16 v[92:95], v[170:173], v[218:221], v[92:95]
	v_mfma_f32_16x16x32_bf16 v[76:79], v[128:131], v[222:225], v[76:79]
	v_mfma_f32_16x16x32_bf16 v[76:79], v[170:173], v[226:229], v[76:79]
	v_mfma_f32_16x16x32_bf16 v[120:123], v[174:177], v[198:201], v[120:123]
	v_mfma_f32_16x16x32_bf16 v[120:123], v[178:181], v[202:205], v[120:123]
	v_mfma_f32_16x16x32_bf16 v[104:107], v[174:177], v[206:209], v[104:107]
	v_mfma_f32_16x16x32_bf16 v[104:107], v[178:181], v[210:213], v[104:107]
	v_mfma_f32_16x16x32_bf16 v[88:91], v[174:177], v[214:217], v[88:91]
	v_mfma_f32_16x16x32_bf16 v[88:91], v[178:181], v[218:221], v[88:91]
	v_mfma_f32_16x16x32_bf16 v[72:75], v[174:177], v[222:225], v[72:75]
	v_mfma_f32_16x16x32_bf16 v[72:75], v[178:181], v[226:229], v[72:75]
	s_setprio 0
	s_setprio 1
	v_mfma_f32_16x16x32_bf16 v[116:119], v[182:185], v[198:201], v[116:119]
	v_mfma_f32_16x16x32_bf16 v[116:119], v[186:189], v[202:205], v[116:119]
	v_mfma_f32_16x16x32_bf16 v[100:103], v[182:185], v[206:209], v[100:103]
	v_mfma_f32_16x16x32_bf16 v[100:103], v[186:189], v[210:213], v[100:103]
	v_mfma_f32_16x16x32_bf16 v[84:87], v[182:185], v[214:217], v[84:87]
	v_mfma_f32_16x16x32_bf16 v[84:87], v[186:189], v[218:221], v[84:87]
	v_mfma_f32_16x16x32_bf16 v[68:71], v[182:185], v[222:225], v[68:71]
	v_mfma_f32_16x16x32_bf16 v[68:71], v[186:189], v[226:229], v[68:71]
	v_mfma_f32_16x16x32_bf16 v[112:115], v[190:193], v[198:201], v[112:115]
	v_mfma_f32_16x16x32_bf16 v[112:115], v[194:197], v[202:205], v[112:115]
	v_mfma_f32_16x16x32_bf16 v[96:99], v[190:193], v[206:209], v[96:99]
	v_mfma_f32_16x16x32_bf16 v[96:99], v[194:197], v[210:213], v[96:99]
	v_mfma_f32_16x16x32_bf16 v[80:83], v[190:193], v[214:217], v[80:83]
	v_mfma_f32_16x16x32_bf16 v[80:83], v[194:197], v[218:221], v[80:83]
	v_mfma_f32_16x16x32_bf16 v[64:67], v[190:193], v[222:225], v[64:67]
	v_mfma_f32_16x16x32_bf16 v[64:67], v[194:197], v[226:229], v[64:67]
	s_setprio 0
	s_barrier
; #define PG8_STAGE(bufoff, gbase, voff) do { _Pragma("unroll") for (int _i = 0; _i < 2; ++_i) \
;         __builtin_amdgcn_global_load_lds((const unsigned*)((const char*)(gbase) + (voff)[_i]), (LAS unsigned*)(lds + (bufoff) + ldsw + _i * 8192), 16, 0, 0); } while (0)
; #define PG8_LDA(dst, b, h) do { _Pragma("unroll") for (int m = 0; m < 4; ++m) _Pragma("unroll") for (int k = 0; k < 2; ++k) dst[m][k] = *(const LAS bf16x8*)(lds + PG8_SA(b, h) + aoff + m * 2048 + k * 1024); } while (0)
; #define PG8_MMA(ai, bj, At, Bt) do { __builtin_amdgcn_s_setprio(1); _Pragma("unroll") for (int m = 0; m < 4; ++m) _Pragma("unroll") for (int n = 0; n < 2; ++n) _Pragma("unroll") for (int k = 0; k < 2; ++k) \
;         acc[ai][bj][m][n] = __builtin_amdgcn_mfma_f32_16x16x32_bf16(Bt[n][k], At[m][k], acc[ai][bj][m][n], 0, 0, 0); __builtin_amdgcn_s_setprio(0); } while (0)
; #define PG8_WAIT_V(n) asm volatile("s_waitcnt vmcnt(" #n ")" ::: "memory")
; #define PG8_WAIT_L(n) asm volatile("s_waitcnt lgkmcnt(" #n ")" ::: "memory")
; #define PG8_BAR __builtin_amdgcn_s_barrier()
; #define PG8_SCHED __builtin_amdgcn_sched_barrier(0)
; template <class EpiT>
; __device__ __forceinline__ void gemm_phase(LAS unsigned char* lds, const Gemm g, const StaticOrder& S, const EpiT& E) {
;     ...
;         for (int t = 0; t < nt; t += 2) {
;     ...
;             PG8_LDA(At, 1, 1); PG8_STAGE(PG8_SB(1, 0), b3, voffB); PG8_STAGE(PG8_SB(1, 1), b3 + hstepB, voffB); PG8_STAGE(PG8_SA(1, 0), a3, voffA);
;             PG8_WAIT_V(8); PG8_WAIT_L(0); PG8_BAR; PG8_MMA(1, 0, At, B0); PG8_MMA(1, 1, At, B1); PG8_BAR; PG8_SCHED;
	s_add_i32 s20, s54, s25
	v_lshl_add_u64 v[158:159], v[158:159], 0, s[10:11]
	s_mov_b32 m0, s20
	ds_read_b128 v[198:201], v162 offset:49152
	ds_read_b128 v[202:205], v162 offset:50176
	ds_read_b128 v[206:209], v162 offset:51200
	ds_read_b128 v[210:213], v162 offset:52224
	ds_read_b128 v[214:217], v162 offset:53248
	ds_read_b128 v[218:221], v162 offset:54272
	ds_read_b128 v[222:225], v162 offset:55296
	ds_read_b128 v[226:229], v162 offset:56320
	global_load_lds_dwordx4 v[158:159], off
	s_add_i32 m0, s20, 0x2000
	s_add_u32 s18, s18, 0x84080
	v_lshl_add_u64 v[158:159], v[166:167], 0, s[10:11]
	s_addc_u32 s19, s19, 0
	s_add_i32 s20, s55, s25
	global_load_lds_dwordx4 v[158:159], off
	v_lshl_add_u64 v[158:159], s[18:19], 0, v[136:137]
	s_mov_b32 m0, s20
	s_nop 0
	global_load_lds_dwordx4 v[158:159], off
	v_lshl_add_u64 v[158:159], s[18:19], 0, v[132:133]
	s_add_i32 m0, s20, 0x2000
	s_nop 0
	global_load_lds_dwordx4 v[158:159], off
	v_lshl_add_u64 v[158:159], v[230:231], 0, s[10:11]
	s_mov_b32 m0, s40
	s_nop 0
	global_load_lds_dwordx4 v[158:159], off
	v_lshl_add_u64 v[158:159], v[232:233], 0, s[10:11]
	s_mov_b32 m0, s41
	s_nop 0
	global_load_lds_dwordx4 v[158:159], off
	s_waitcnt vmcnt(8)
	s_waitcnt lgkmcnt(0)
	s_barrier
	s_setprio 1
	s_waitcnt lgkmcnt(0)
	v_mfma_f32_16x16x32_bf16 v[60:63], v[128:131], v[198:201], v[60:63]
	v_mfma_f32_16x16x32_bf16 v[60:63], v[170:173], v[202:205], v[60:63]
	v_mfma_f32_16x16x32_bf16 v[44:47], v[128:131], v[206:209], v[44:47]
	v_mfma_f32_16x16x32_bf16 v[44:47], v[170:173], v[210:213], v[44:47]
	v_mfma_f32_16x16x32_bf16 v[28:31], v[128:131], v[214:217], v[28:31]
	v_mfma_f32_16x16x32_bf16 v[28:31], v[170:173], v[218:221], v[28:31]
	v_mfma_f32_16x16x32_bf16 v[12:15], v[128:131], v[222:225], v[12:15]
	v_mfma_f32_16x16x32_bf16 v[12:15], v[170:173], v[226:229], v[12:15]
	v_mfma_f32_16x16x32_bf16 v[56:59], v[174:177], v[198:201], v[56:59]
	v_mfma_f32_16x16x32_bf16 v[56:59], v[178:181], v[202:205], v[56:59]
	v_mfma_f32_16x16x32_bf16 v[40:43], v[174:177], v[206:209], v[40:43]
	v_mfma_f32_16x16x32_bf16 v[40:43], v[178:181], v[210:213], v[40:43]
	v_mfma_f32_16x16x32_bf16 v[24:27], v[174:177], v[214:217], v[24:27]
	v_mfma_f32_16x16x32_bf16 v[24:27], v[178:181], v[218:221], v[24:27]
	v_mfma_f32_16x16x32_bf16 v[8:11], v[174:177], v[222:225], v[8:11]
	v_mfma_f32_16x16x32_bf16 v[8:11], v[178:181], v[226:229], v[8:11]
	s_setprio 0
	s_setprio 1
	v_mfma_f32_16x16x32_bf16 v[52:55], v[182:185], v[198:201], v[52:55]
	v_mfma_f32_16x16x32_bf16 v[52:55], v[186:189], v[202:205], v[52:55]
	v_mfma_f32_16x16x32_bf16 v[36:39], v[182:185], v[206:209], v[36:39]
	v_mfma_f32_16x16x32_bf16 v[36:39], v[186:189], v[210:213], v[36:39]
	v_mfma_f32_16x16x32_bf16 v[20:23], v[182:185], v[214:217], v[20:23]
	v_mfma_f32_16x16x32_bf16 v[20:23], v[186:189], v[218:221], v[20:23]
	v_mfma_f32_16x16x32_bf16 v[4:7], v[182:185], v[222:225], v[4:7]
	v_mfma_f32_16x16x32_bf16 v[4:7], v[186:189], v[226:229], v[4:7]
	v_mfma_f32_16x16x32_bf16 v[48:51], v[190:193], v[198:201], v[48:51]
	v_mfma_f32_16x16x32_bf16 v[48:51], v[194:197], v[202:205], v[48:51]
	v_mfma_f32_16x16x32_bf16 v[32:35], v[190:193], v[206:209], v[32:35]
	v_mfma_f32_16x16x32_bf16 v[32:35], v[194:197], v[210:213], v[32:35]
	v_mfma_f32_16x16x32_bf16 v[16:19], v[190:193], v[214:217], v[16:19]
	v_mfma_f32_16x16x32_bf16 v[16:19], v[194:197], v[218:221], v[16:19]
	v_mfma_f32_16x16x32_bf16 v[0:3], v[190:193], v[222:225], v[0:3]
	v_mfma_f32_16x16x32_bf16 v[0:3], v[194:197], v[226:229], v[0:3]
	s_setprio 0
	s_barrier
	s_add_i32 s53, s53, 2
	s_add_u32 s16, s16, 0x100
	s_addc_u32 s17, s17, 0
	s_add_u32 s51, s51, 0x100
	s_addc_u32 s52, s52, 0
	s_cmp_gt_u32 s53, 29
	s_cbranch_scc1 .Lrot_done_100
; #define PG8_STAGE(bufoff, gbase, voff) do { _Pragma("unroll") for (int _i = 0; _i < 2; ++_i) \
;         __builtin_amdgcn_global_load_lds((const unsigned*)((const char*)(gbase) + (voff)[_i]), (LAS unsigned*)(lds + (bufoff) + ldsw + _i * 8192), 16, 0, 0); } while (0)
; #define PG8_LDA(dst, b, h) do { _Pragma("unroll") for (int m = 0; m < 4; ++m) _Pragma("unroll") for (int k = 0; k < 2; ++k) dst[m][k] = *(const LAS bf16x8*)(lds + PG8_SA(b, h) + aoff + m * 2048 + k * 1024); } while (0)
; #define PG8_LDB(dst, b, h) do { _Pragma("unroll") for (int n = 0; n < 2; ++n) _Pragma("unroll") for (int k = 0; k < 2; ++k) dst[n][k] = *(const LAS bf16x8*)(lds + PG8_SB(b, h) + boff + n * 2048 + k * 1024); } while (0)
; #define PG8_MMA(ai, bj, At, Bt) do { __builtin_amdgcn_s_setprio(1); _Pragma("unroll") for (int m = 0; m < 4; ++m) _Pragma("unroll") for (int n = 0; n < 2; ++n) _Pragma("unroll") for (int k = 0; k < 2; ++k) \
;         acc[ai][bj][m][n] = __builtin_amdgcn_mfma_f32_16x16x32_bf16(Bt[n][k], At[m][k], acc[ai][bj][m][n], 0, 0, 0); __builtin_amdgcn_s_setprio(0); } while (0)
; #define PG8_WAIT_V(n) asm volatile("s_waitcnt vmcnt(" #n ")" ::: "memory")
; #define PG8_WAIT_L(n) asm volatile("s_waitcnt lgkmcnt(" #n ")" ::: "memory")
; #define PG8_BAR __builtin_amdgcn_s_barrier()
; #define PG8_SCHED __builtin_amdgcn_sched_barrier(0)
; template <class EpiT>
; __device__ __forceinline__ void gemm_phase(LAS unsigned char* lds, const Gemm g, const StaticOrder& S, const EpiT& E) {
;     ...
;             PG8_LDB(B0, 0, 0); PG8_LDB(B1, 0, 1); PG8_SCHED; PG8_LDA(At, 0, 0); PG8_STAGE(PG8_SA(1, 1), a1 + hstepA, voffA);
;             PG8_WAIT_V(8); PG8_WAIT_L(0); PG8_BAR; PG8_MMA(0, 0, At, B0); PG8_MMA(0, 1, At, B1); PG8_BAR; PG8_SCHED;
	ds_read_b128 v[128:131], v160
	ds_read_b128 v[170:173], v160 offset:1024
	ds_read_b128 v[174:177], v160 offset:2048
	ds_read_b128 v[178:181], v160 offset:3072
	ds_read_b128 v[182:185], v161
	ds_read_b128 v[186:189], v161 offset:1024
	ds_read_b128 v[190:193], v161 offset:2048
	ds_read_b128 v[194:197], v161 offset:3072
	s_add_u32 s18, s16, 0xfff7c080
	s_addc_u32 s19, s17, -1
	s_cmp_eq_u32 s53, 28
	s_cselect_b32 s21, s3, s19
	s_cselect_b32 s20, s2, s18
	s_cselect_b32 s19, s15, s52
	s_cselect_b32 s18, s14, s51
	v_lshl_add_u64 v[158:159], s[16:17], 0, v[150:151]
	s_add_i32 m0, s35, 0xc000
	ds_read_b128 v[198:201], v162
	ds_read_b128 v[202:205], v162 offset:1024
	ds_read_b128 v[206:209], v162 offset:2048
	ds_read_b128 v[210:213], v162 offset:3072
	ds_read_b128 v[214:217], v162 offset:4096
	ds_read_b128 v[218:221], v162 offset:5120
	ds_read_b128 v[222:225], v162 offset:6144
	ds_read_b128 v[226:229], v162 offset:7168
	global_load_lds_dwordx4 v[158:159], off
	v_lshl_add_u64 v[158:159], s[16:17], 0, v[152:153]
	s_add_i32 m0, s35, 0xe000
	s_nop 0
	global_load_lds_dwordx4 v[158:159], off
	s_waitcnt vmcnt(8)
	s_waitcnt lgkmcnt(0)
	s_barrier
	s_setprio 1
	s_waitcnt lgkmcnt(0)
	v_mfma_f32_16x16x32_bf16 v[124:127], v[128:131], v[198:201], v[124:127]
	v_mfma_f32_16x16x32_bf16 v[124:127], v[170:173], v[202:205], v[124:127]
	v_mfma_f32_16x16x32_bf16 v[108:111], v[128:131], v[206:209], v[108:111]
	v_mfma_f32_16x16x32_bf16 v[108:111], v[170:173], v[210:213], v[108:111]
	v_mfma_f32_16x16x32_bf16 v[92:95], v[128:131], v[214:217], v[92:95]
	v_mfma_f32_16x16x32_bf16 v[92:95], v[170:173], v[218:221], v[92:95]
	v_mfma_f32_16x16x32_bf16 v[76:79], v[128:131], v[222:225], v[76:79]
	v_mfma_f32_16x16x32_bf16 v[76:79], v[170:173], v[226:229], v[76:79]
	v_mfma_f32_16x16x32_bf16 v[120:123], v[174:177], v[198:201], v[120:123]
	v_mfma_f32_16x16x32_bf16 v[120:123], v[178:181], v[202:205], v[120:123]
	v_mfma_f32_16x16x32_bf16 v[104:107], v[174:177], v[206:209], v[104:107]
	v_mfma_f32_16x16x32_bf16 v[104:107], v[178:181], v[210:213], v[104:107]
	v_mfma_f32_16x16x32_bf16 v[88:91], v[174:177], v[214:217], v[88:91]
	v_mfma_f32_16x16x32_bf16 v[88:91], v[178:181], v[218:221], v[88:91]
	v_mfma_f32_16x16x32_bf16 v[72:75], v[174:177], v[222:225], v[72:75]
	v_mfma_f32_16x16x32_bf16 v[72:75], v[178:181], v[226:229], v[72:75]
	s_setprio 0
	s_setprio 1
	v_mfma_f32_16x16x32_bf16 v[116:119], v[182:185], v[198:201], v[116:119]
	v_mfma_f32_16x16x32_bf16 v[116:119], v[186:189], v[202:205], v[116:119]
	v_mfma_f32_16x16x32_bf16 v[100:103], v[182:185], v[206:209], v[100:103]
	v_mfma_f32_16x16x32_bf16 v[100:103], v[186:189], v[210:213], v[100:103]
	v_mfma_f32_16x16x32_bf16 v[84:87], v[182:185], v[214:217], v[84:87]
	v_mfma_f32_16x16x32_bf16 v[84:87], v[186:189], v[218:221], v[84:87]
	v_mfma_f32_16x16x32_bf16 v[68:71], v[182:185], v[222:225], v[68:71]
	v_mfma_f32_16x16x32_bf16 v[68:71], v[186:189], v[226:229], v[68:71]
	v_mfma_f32_16x16x32_bf16 v[112:115], v[190:193], v[198:201], v[112:115]
	v_mfma_f32_16x16x32_bf16 v[112:115], v[194:197], v[202:205], v[112:115]
	v_mfma_f32_16x16x32_bf16 v[96:99], v[190:193], v[206:209], v[96:99]
	v_mfma_f32_16x16x32_bf16 v[96:99], v[194:197], v[210:213], v[96:99]
	v_mfma_f32_16x16x32_bf16 v[80:83], v[190:193], v[214:217], v[80:83]
	v_mfma_f32_16x16x32_bf16 v[80:83], v[194:197], v[218:221], v[80:83]
	v_mfma_f32_16x16x32_bf16 v[64:67], v[190:193], v[222:225], v[64:67]
	v_mfma_f32_16x16x32_bf16 v[64:67], v[194:197], v[226:229], v[64:67]
	s_setprio 0
	s_barrier
	s_branch .Lrot_100

; #define PG8_STAGE(bufoff, gbase, voff) do { _Pragma("unroll") for (int _i = 0; _i < 2; ++_i) \
;         __builtin_amdgcn_global_load_lds((const unsigned*)((const char*)(gbase) + (voff)[_i]), (LAS unsigned*)(lds + (bufoff) + ldsw + _i * 8192), 16, 0, 0); } while (0)
; #define PG8_LDA(dst, b, h) do { _Pragma("unroll") for (int m = 0; m < 4; ++m) _Pragma("unroll") for (int k = 0; k < 2; ++k) dst[m][k] = *(const LAS bf16x8*)(lds + PG8_SA(b, h) + aoff + m * 2048 + k * 1024); } while (0)
; #define PG8_LDB(dst, b, h) do { _Pragma("unroll") for (int n = 0; n < 2; ++n) _Pragma("unroll") for (int k = 0; k < 2; ++k) dst[n][k] = *(const LAS bf16x8*)(lds + PG8_SB(b, h) + boff + n * 2048 + k * 1024); } while (0)
; #define PG8_MMA(ai, bj, At, Bt) do { __builtin_amdgcn_s_setprio(1); _Pragma("unroll") for (int m = 0; m < 4; ++m) _Pragma("unroll") for (int n = 0; n < 2; ++n) _Pragma("unroll") for (int k = 0; k < 2; ++k) \
;         acc[ai][bj][m][n] = __builtin_amdgcn_mfma_f32_16x16x32_bf16(Bt[n][k], At[m][k], acc[ai][bj][m][n], 0, 0, 0); __builtin_amdgcn_s_setprio(0); } while (0)
; #define PG8_WAIT_V(n) asm volatile("s_waitcnt vmcnt(" #n ")" ::: "memory")
; #define PG8_WAIT_L(n) asm volatile("s_waitcnt lgkmcnt(" #n ")" ::: "memory")
; #define PG8_BAR __builtin_amdgcn_s_barrier()
; #define PG8_SCHED __builtin_amdgcn_sched_barrier(0)
; template <class EpiT>
; __device__ __forceinline__ void gemm_phase(LAS unsigned char* lds, const Gemm g, const StaticOrder& S, const EpiT& E) {
;     ...
;             PG8_LDB(B0, 0, 0); PG8_LDB(B1, 0, 1); PG8_SCHED; PG8_LDA(At, 0, 0); PG8_STAGE(PG8_SA(1, 1), a1 + hstepA, voffA);
;             PG8_WAIT_V(8); PG8_WAIT_L(0); PG8_BAR; PG8_MMA(0, 0, At, B0); PG8_MMA(0, 1, At, B1); PG8_BAR; PG8_SCHED;
;             PG8_LDA(At, 0, 1); PG8_STAGE(PG8_SB(0, 0), b2, voffB); PG8_STAGE(PG8_SB(0, 1), b2 + hstepB, voffB); PG8_STAGE(PG8_SA(0, 0), a2, voffA);
.LBB0_392:
	ds_read_b128 v[154:157], v149
	ds_read_b128 v[158:161], v149 offset:1024
	ds_read_b128 v[170:173], v149 offset:2048
	ds_read_b128 v[174:177], v149 offset:3072
	ds_read_b128 v[178:181], v150
	ds_read_b128 v[182:185], v150 offset:1024
	ds_read_b128 v[186:189], v150 offset:2048
	ds_read_b128 v[190:193], v150 offset:3072
	s_add_u32 s20, s18, 0xfff7c080
	s_addc_u32 s21, s19, -1
	s_cmp_eq_u32 s53, 28
	s_cselect_b32 s23, s5, s21
	s_cselect_b32 s22, s4, s20
	s_cselect_b32 s21, s17, s52
	s_cselect_b32 s20, s16, s51
	v_lshl_add_u64 v[162:163], s[18:19], 0, v[138:139]
	s_add_i32 m0, s35, 0xc000
	ds_read_b128 v[194:197], v151
	ds_read_b128 v[198:201], v151 offset:1024
	ds_read_b128 v[202:205], v151 offset:2048
	ds_read_b128 v[206:209], v151 offset:3072
	ds_read_b128 v[210:213], v151 offset:4096
	ds_read_b128 v[214:217], v151 offset:5120
	ds_read_b128 v[218:221], v151 offset:6144
	ds_read_b128 v[222:225], v151 offset:7168
	global_load_lds_dwordx4 v[162:163], off
	v_lshl_add_u64 v[162:163], s[18:19], 0, v[140:141]
	s_add_i32 m0, s35, 0xe000
	s_nop 0
	global_load_lds_dwordx4 v[162:163], off
	s_waitcnt vmcnt(8)
	s_waitcnt lgkmcnt(0)
	s_barrier
	s_setprio 1
	s_waitcnt lgkmcnt(0)
	v_mfma_f32_16x16x32_bf16 v[124:127], v[154:157], v[194:197], v[124:127]
	v_mfma_f32_16x16x32_bf16 v[124:127], v[158:161], v[198:201], v[124:127]
	v_mfma_f32_16x16x32_bf16 v[108:111], v[154:157], v[202:205], v[108:111]
	v_mfma_f32_16x16x32_bf16 v[108:111], v[158:161], v[206:209], v[108:111]
	v_mfma_f32_16x16x32_bf16 v[92:95], v[154:157], v[210:213], v[92:95]
	v_mfma_f32_16x16x32_bf16 v[92:95], v[158:161], v[214:217], v[92:95]
	v_mfma_f32_16x16x32_bf16 v[76:79], v[154:157], v[218:221], v[76:79]
	v_mfma_f32_16x16x32_bf16 v[76:79], v[158:161], v[222:225], v[76:79]
	v_mfma_f32_16x16x32_bf16 v[120:123], v[170:173], v[194:197], v[120:123]
	v_mfma_f32_16x16x32_bf16 v[120:123], v[174:177], v[198:201], v[120:123]
	v_mfma_f32_16x16x32_bf16 v[104:107], v[170:173], v[202:205], v[104:107]
	v_mfma_f32_16x16x32_bf16 v[104:107], v[174:177], v[206:209], v[104:107]
	v_mfma_f32_16x16x32_bf16 v[88:91], v[170:173], v[210:213], v[88:91]
	v_mfma_f32_16x16x32_bf16 v[88:91], v[174:177], v[214:217], v[88:91]
	v_mfma_f32_16x16x32_bf16 v[72:75], v[170:173], v[218:221], v[72:75]
	v_mfma_f32_16x16x32_bf16 v[72:75], v[174:177], v[222:225], v[72:75]
	s_setprio 0
	s_setprio 1
	v_mfma_f32_16x16x32_bf16 v[116:119], v[178:181], v[194:197], v[116:119]
	v_mfma_f32_16x16x32_bf16 v[116:119], v[182:185], v[198:201], v[116:119]
	v_mfma_f32_16x16x32_bf16 v[100:103], v[178:181], v[202:205], v[100:103]
	v_mfma_f32_16x16x32_bf16 v[100:103], v[182:185], v[206:209], v[100:103]
	v_mfma_f32_16x16x32_bf16 v[84:87], v[178:181], v[210:213], v[84:87]
	v_mfma_f32_16x16x32_bf16 v[84:87], v[182:185], v[214:217], v[84:87]
	v_mfma_f32_16x16x32_bf16 v[68:71], v[178:181], v[218:221], v[68:71]
	v_mfma_f32_16x16x32_bf16 v[68:71], v[182:185], v[222:225], v[68:71]
	v_mfma_f32_16x16x32_bf16 v[112:115], v[186:189], v[194:197], v[112:115]
	v_mfma_f32_16x16x32_bf16 v[112:115], v[190:193], v[198:201], v[112:115]
	v_mfma_f32_16x16x32_bf16 v[96:99], v[186:189], v[202:205], v[96:99]
	v_mfma_f32_16x16x32_bf16 v[96:99], v[190:193], v[206:209], v[96:99]
	v_mfma_f32_16x16x32_bf16 v[80:83], v[186:189], v[210:213], v[80:83]
	v_mfma_f32_16x16x32_bf16 v[80:83], v[190:193], v[214:217], v[80:83]
	v_mfma_f32_16x16x32_bf16 v[64:67], v[186:189], v[218:221], v[64:67]
	v_mfma_f32_16x16x32_bf16 v[64:67], v[190:193], v[222:225], v[64:67]
	s_setprio 0
	s_barrier
.Lrot_392:
	s_add_i32 s54, s44, s33
	v_lshl_add_u64 v[162:163], s[20:21], 0, v[130:131]
	s_mov_b32 m0, s54
	ds_read_b128 v[194:197], v151 offset:16384
	ds_read_b128 v[198:201], v151 offset:17408
	ds_read_b128 v[202:205], v151 offset:18432
	ds_read_b128 v[206:209], v151 offset:19456
	ds_read_b128 v[210:213], v151 offset:20480
	ds_read_b128 v[214:217], v151 offset:21504
	ds_read_b128 v[218:221], v151 offset:22528
	ds_read_b128 v[222:225], v151 offset:23552
	global_load_lds_dwordx4 v[162:163], off
	s_add_i32 m0, s54, 0x2000
	s_add_u32 s54, s20, 0x84000
	v_lshl_add_u64 v[166:167], s[20:21], 0, v[134:135]
	s_addc_u32 s55, s21, 0
	s_add_i32 s56, s45, s33
	global_load_lds_dwordx4 v[166:167], off
	v_lshl_add_u64 v[226:227], s[54:55], 0, v[130:131]
	s_mov_b32 m0, s56
	v_lshl_add_u64 v[228:229], s[22:23], 0, v[132:133]
	global_load_lds_dwordx4 v[226:227], off
	v_lshl_add_u64 v[226:227], s[54:55], 0, v[134:135]
	s_add_i32 m0, s56, 0x2000
	s_nop 0
	global_load_lds_dwordx4 v[226:227], off
	v_lshl_add_u64 v[226:227], s[22:23], 0, v[128:129]
	s_mov_b32 m0, s35
	s_nop 0
	global_load_lds_dwordx4 v[226:227], off
	s_mov_b32 m0, s36
	s_nop 0
	global_load_lds_dwordx4 v[228:229], off
	s_waitcnt vmcnt(8)
	s_waitcnt lgkmcnt(0)
	s_barrier
; #define PG8_STAGE(bufoff, gbase, voff) do { _Pragma("unroll") for (int _i = 0; _i < 2; ++_i) \
;         __builtin_amdgcn_global_load_lds((const unsigned*)((const char*)(gbase) + (voff)[_i]), (LAS unsigned*)(lds + (bufoff) + ldsw + _i * 8192), 16, 0, 0); } while (0)
; #define PG8_LDA(dst, b, h) do { _Pragma("unroll") for (int m = 0; m < 4; ++m) _Pragma("unroll") for (int k = 0; k < 2; ++k) dst[m][k] = *(const LAS bf16x8*)(lds + PG8_SA(b, h) + aoff + m * 2048 + k * 1024); } while (0)
; #define PG8_LDB(dst, b, h) do { _Pragma("unroll") for (int n = 0; n < 2; ++n) _Pragma("unroll") for (int k = 0; k < 2; ++k) dst[n][k] = *(const LAS bf16x8*)(lds + PG8_SB(b, h) + boff + n * 2048 + k * 1024); } while (0)
; #define PG8_MMA(ai, bj, At, Bt) do { __builtin_amdgcn_s_setprio(1); _Pragma("unroll") for (int m = 0; m < 4; ++m) _Pragma("unroll") for (int n = 0; n < 2; ++n) _Pragma("unroll") for (int k = 0; k < 2; ++k) \
;         acc[ai][bj][m][n] = __builtin_amdgcn_mfma_f32_16x16x32_bf16(Bt[n][k], At[m][k], acc[ai][bj][m][n], 0, 0, 0); __builtin_amdgcn_s_setprio(0); } while (0)
; #define PG8_WAIT_V(n) asm volatile("s_waitcnt vmcnt(" #n ")" ::: "memory")
; #define PG8_WAIT_L(n) asm volatile("s_waitcnt lgkmcnt(" #n ")" ::: "memory")
; #define PG8_BAR __builtin_amdgcn_s_barrier()
; #define PG8_SCHED __builtin_amdgcn_sched_barrier(0)
; template <class EpiT>
; __device__ __forceinline__ void gemm_phase(LAS unsigned char* lds, const Gemm g, const StaticOrder& S, const EpiT& E) {
;     ...
;             PG8_WAIT_V(8); PG8_WAIT_L(0); PG8_BAR; PG8_MMA(1, 0, At, B0); PG8_MMA(1, 1, At, B1); PG8_BAR; PG8_SCHED;
;             PG8_LDB(B0, 1, 0); PG8_LDB(B1, 1, 1); PG8_SCHED; PG8_LDA(At, 1, 0); PG8_STAGE(PG8_SA(0, 1), a2 + hstepA, voffA);
;             PG8_WAIT_V(8); PG8_WAIT_L(0); PG8_BAR; PG8_MMA(0, 0, At, B0); PG8_MMA(0, 1, At, B1); PG8_BAR; PG8_SCHED;
	s_setprio 1
	s_waitcnt lgkmcnt(0)
	v_mfma_f32_16x16x32_bf16 v[60:63], v[154:157], v[194:197], v[60:63]
	v_mfma_f32_16x16x32_bf16 v[60:63], v[158:161], v[198:201], v[60:63]
	v_mfma_f32_16x16x32_bf16 v[44:47], v[154:157], v[202:205], v[44:47]
	v_mfma_f32_16x16x32_bf16 v[44:47], v[158:161], v[206:209], v[44:47]
	v_mfma_f32_16x16x32_bf16 v[28:31], v[154:157], v[210:213], v[28:31]
	v_mfma_f32_16x16x32_bf16 v[28:31], v[158:161], v[214:217], v[28:31]
	v_mfma_f32_16x16x32_bf16 v[12:15], v[154:157], v[218:221], v[12:15]
	v_mfma_f32_16x16x32_bf16 v[12:15], v[158:161], v[222:225], v[12:15]
	v_mfma_f32_16x16x32_bf16 v[56:59], v[170:173], v[194:197], v[56:59]
	v_mfma_f32_16x16x32_bf16 v[56:59], v[174:177], v[198:201], v[56:59]
	v_mfma_f32_16x16x32_bf16 v[40:43], v[170:173], v[202:205], v[40:43]
	v_mfma_f32_16x16x32_bf16 v[40:43], v[174:177], v[206:209], v[40:43]
	v_mfma_f32_16x16x32_bf16 v[24:27], v[170:173], v[210:213], v[24:27]
	v_mfma_f32_16x16x32_bf16 v[24:27], v[174:177], v[214:217], v[24:27]
	v_mfma_f32_16x16x32_bf16 v[8:11], v[170:173], v[218:221], v[8:11]
	v_mfma_f32_16x16x32_bf16 v[8:11], v[174:177], v[222:225], v[8:11]
	s_setprio 0
	s_setprio 1
	v_mfma_f32_16x16x32_bf16 v[52:55], v[178:181], v[194:197], v[52:55]
	v_mfma_f32_16x16x32_bf16 v[52:55], v[182:185], v[198:201], v[52:55]
	v_mfma_f32_16x16x32_bf16 v[36:39], v[178:181], v[202:205], v[36:39]
	v_mfma_f32_16x16x32_bf16 v[36:39], v[182:185], v[206:209], v[36:39]
	v_mfma_f32_16x16x32_bf16 v[20:23], v[178:181], v[210:213], v[20:23]
	v_mfma_f32_16x16x32_bf16 v[20:23], v[182:185], v[214:217], v[20:23]
	v_mfma_f32_16x16x32_bf16 v[4:7], v[178:181], v[218:221], v[4:7]
	v_mfma_f32_16x16x32_bf16 v[4:7], v[182:185], v[222:225], v[4:7]
	v_mfma_f32_16x16x32_bf16 v[48:51], v[186:189], v[194:197], v[48:51]
	v_mfma_f32_16x16x32_bf16 v[48:51], v[190:193], v[198:201], v[48:51]
	v_mfma_f32_16x16x32_bf16 v[32:35], v[186:189], v[202:205], v[32:35]
	v_mfma_f32_16x16x32_bf16 v[32:35], v[190:193], v[206:209], v[32:35]
	v_mfma_f32_16x16x32_bf16 v[16:19], v[186:189], v[210:213], v[16:19]
	v_mfma_f32_16x16x32_bf16 v[16:19], v[190:193], v[214:217], v[16:19]
	v_mfma_f32_16x16x32_bf16 v[0:3], v[186:189], v[218:221], v[0:3]
	v_mfma_f32_16x16x32_bf16 v[0:3], v[190:193], v[222:225], v[0:3]
	s_setprio 0
	s_barrier
	s_add_i32 s54, 0, 0x18000
	v_add_u32_e32 v153, s54, v146
	s_add_i32 s55, 0, 0x1c000
	ds_read_b128 v[154:157], v153
	ds_read_b128 v[158:161], v153 offset:1024
	ds_read_b128 v[170:173], v153 offset:2048
	ds_read_b128 v[174:177], v153 offset:3072
	v_add_u32_e32 v153, s55, v146
	ds_read_b128 v[178:181], v153
	ds_read_b128 v[182:185], v153 offset:1024
	ds_read_b128 v[186:189], v153 offset:2048
	ds_read_b128 v[190:193], v153 offset:3072
	s_add_u32 s22, s22, 0x84000
	s_addc_u32 s23, s23, 0
	s_mov_b32 m0, s37
	v_lshl_add_u64 v[230:231], s[22:23], 0, v[128:129]
	ds_read_b128 v[194:197], v151 offset:32768
	ds_read_b128 v[198:201], v151 offset:33792
	ds_read_b128 v[202:205], v151 offset:34816
	ds_read_b128 v[206:209], v151 offset:35840
	ds_read_b128 v[210:213], v151 offset:36864
	ds_read_b128 v[214:217], v151 offset:37888
	ds_read_b128 v[218:221], v151 offset:38912
	ds_read_b128 v[222:225], v151 offset:39936
	global_load_lds_dwordx4 v[230:231], off
	v_lshl_add_u64 v[230:231], s[22:23], 0, v[132:133]
	s_mov_b32 m0, s38
	s_nop 0
	global_load_lds_dwordx4 v[230:231], off
	s_waitcnt vmcnt(8)
	s_waitcnt lgkmcnt(0)
	s_barrier
	s_setprio 1
	s_waitcnt lgkmcnt(0)
	v_mfma_f32_16x16x32_bf16 v[124:127], v[154:157], v[194:197], v[124:127]
	v_mfma_f32_16x16x32_bf16 v[124:127], v[158:161], v[198:201], v[124:127]
	v_mfma_f32_16x16x32_bf16 v[108:111], v[154:157], v[202:205], v[108:111]
	v_mfma_f32_16x16x32_bf16 v[108:111], v[158:161], v[206:209], v[108:111]
	v_mfma_f32_16x16x32_bf16 v[92:95], v[154:157], v[210:213], v[92:95]
	v_mfma_f32_16x16x32_bf16 v[92:95], v[158:161], v[214:217], v[92:95]
	v_mfma_f32_16x16x32_bf16 v[76:79], v[154:157], v[218:221], v[76:79]
	v_mfma_f32_16x16x32_bf16 v[76:79], v[158:161], v[222:225], v[76:79]
	v_mfma_f32_16x16x32_bf16 v[120:123], v[170:173], v[194:197], v[120:123]
	v_mfma_f32_16x16x32_bf16 v[120:123], v[174:177], v[198:201], v[120:123]
	v_mfma_f32_16x16x32_bf16 v[104:107], v[170:173], v[202:205], v[104:107]
	v_mfma_f32_16x16x32_bf16 v[104:107], v[174:177], v[206:209], v[104:107]
	v_mfma_f32_16x16x32_bf16 v[88:91], v[170:173], v[210:213], v[88:91]
	v_mfma_f32_16x16x32_bf16 v[88:91], v[174:177], v[214:217], v[88:91]
	v_mfma_f32_16x16x32_bf16 v[72:75], v[170:173], v[218:221], v[72:75]
	v_mfma_f32_16x16x32_bf16 v[72:75], v[174:177], v[222:225], v[72:75]
	s_setprio 0
	s_setprio 1
	v_mfma_f32_16x16x32_bf16 v[116:119], v[178:181], v[194:197], v[116:119]
	v_mfma_f32_16x16x32_bf16 v[116:119], v[182:185], v[198:201], v[116:119]
	v_mfma_f32_16x16x32_bf16 v[100:103], v[178:181], v[202:205], v[100:103]
	v_mfma_f32_16x16x32_bf16 v[100:103], v[182:185], v[206:209], v[100:103]
	v_mfma_f32_16x16x32_bf16 v[84:87], v[178:181], v[210:213], v[84:87]
	v_mfma_f32_16x16x32_bf16 v[84:87], v[182:185], v[214:217], v[84:87]
	v_mfma_f32_16x16x32_bf16 v[68:71], v[178:181], v[218:221], v[68:71]
	v_mfma_f32_16x16x32_bf16 v[68:71], v[182:185], v[222:225], v[68:71]
	v_mfma_f32_16x16x32_bf16 v[112:115], v[186:189], v[194:197], v[112:115]
	v_mfma_f32_16x16x32_bf16 v[112:115], v[190:193], v[198:201], v[112:115]
	v_mfma_f32_16x16x32_bf16 v[96:99], v[186:189], v[202:205], v[96:99]
	v_mfma_f32_16x16x32_bf16 v[96:99], v[190:193], v[206:209], v[96:99]
	v_mfma_f32_16x16x32_bf16 v[80:83], v[186:189], v[210:213], v[80:83]
	v_mfma_f32_16x16x32_bf16 v[80:83], v[190:193], v[214:217], v[80:83]
	v_mfma_f32_16x16x32_bf16 v[64:67], v[186:189], v[218:221], v[64:67]
	v_mfma_f32_16x16x32_bf16 v[64:67], v[190:193], v[222:225], v[64:67]
	s_setprio 0
	s_barrier
; #define PG8_STAGE(bufoff, gbase, voff) do { _Pragma("unroll") for (int _i = 0; _i < 2; ++_i) \
;         __builtin_amdgcn_global_load_lds((const unsigned*)((const char*)(gbase) + (voff)[_i]), (LAS unsigned*)(lds + (bufoff) + ldsw + _i * 8192), 16, 0, 0); } while (0)
; #define PG8_LDA(dst, b, h) do { _Pragma("unroll") for (int m = 0; m < 4; ++m) _Pragma("unroll") for (int k = 0; k < 2; ++k) dst[m][k] = *(const LAS bf16x8*)(lds + PG8_SA(b, h) + aoff + m * 2048 + k * 1024); } while (0)
; #define PG8_MMA(ai, bj, At, Bt) do { __builtin_amdgcn_s_setprio(1); _Pragma("unroll") for (int m = 0; m < 4; ++m) _Pragma("unroll") for (int n = 0; n < 2; ++n) _Pragma("unroll") for (int k = 0; k < 2; ++k) \
;         acc[ai][bj][m][n] = __builtin_amdgcn_mfma_f32_16x16x32_bf16(Bt[n][k], At[m][k], acc[ai][bj][m][n], 0, 0, 0); __builtin_amdgcn_s_setprio(0); } while (0)
; #define PG8_WAIT_V(n) asm volatile("s_waitcnt vmcnt(" #n ")" ::: "memory")
; #define PG8_WAIT_L(n) asm volatile("s_waitcnt lgkmcnt(" #n ")" ::: "memory")
; #define PG8_BAR __builtin_amdgcn_s_barrier()
; #define PG8_SCHED __builtin_amdgcn_sched_barrier(0)
; template <class EpiT>
; __device__ __forceinline__ void gemm_phase(LAS unsigned char* lds, const Gemm g, const StaticOrder& S, const EpiT& E) {
;     ...
;         for (int t = 0; t < nt; t += 2) {
;     ...
;             PG8_LDA(At, 1, 1); PG8_STAGE(PG8_SB(1, 0), b3, voffB); PG8_STAGE(PG8_SB(1, 1), b3 + hstepB, voffB); PG8_STAGE(PG8_SA(1, 0), a3, voffA);
;             PG8_WAIT_V(8); PG8_WAIT_L(0); PG8_BAR; PG8_MMA(1, 0, At, B0); PG8_MMA(1, 1, At, B1); PG8_BAR; PG8_SCHED;
	s_add_i32 s22, s54, s33
	v_lshl_add_u64 v[162:163], v[162:163], 0, s[12:13]
	s_mov_b32 m0, s22
	ds_read_b128 v[194:197], v151 offset:49152
	ds_read_b128 v[198:201], v151 offset:50176
	ds_read_b128 v[202:205], v151 offset:51200
	ds_read_b128 v[206:209], v151 offset:52224
	ds_read_b128 v[210:213], v151 offset:53248
	ds_read_b128 v[214:217], v151 offset:54272
	ds_read_b128 v[218:221], v151 offset:55296
	ds_read_b128 v[222:225], v151 offset:56320
	global_load_lds_dwordx4 v[162:163], off
	s_add_i32 m0, s22, 0x2000
	s_add_u32 s20, s20, 0x84080
	v_lshl_add_u64 v[162:163], v[166:167], 0, s[12:13]
	s_addc_u32 s21, s21, 0
	s_add_i32 s22, s55, s33
	global_load_lds_dwordx4 v[162:163], off
	v_lshl_add_u64 v[162:163], s[20:21], 0, v[130:131]
	s_mov_b32 m0, s22
	s_nop 0
	global_load_lds_dwordx4 v[162:163], off
	v_lshl_add_u64 v[162:163], s[20:21], 0, v[134:135]
	s_add_i32 m0, s22, 0x2000
	s_nop 0
	global_load_lds_dwordx4 v[162:163], off
	v_lshl_add_u64 v[162:163], v[226:227], 0, s[12:13]
	s_mov_b32 m0, s40
	s_nop 0
	global_load_lds_dwordx4 v[162:163], off
	v_lshl_add_u64 v[162:163], v[228:229], 0, s[12:13]
	s_mov_b32 m0, s41
	s_nop 0
	global_load_lds_dwordx4 v[162:163], off
	s_waitcnt vmcnt(8)
	s_waitcnt lgkmcnt(0)
	s_barrier
	s_setprio 1
	s_waitcnt lgkmcnt(0)
	v_mfma_f32_16x16x32_bf16 v[60:63], v[154:157], v[194:197], v[60:63]
	v_mfma_f32_16x16x32_bf16 v[60:63], v[158:161], v[198:201], v[60:63]
	v_mfma_f32_16x16x32_bf16 v[44:47], v[154:157], v[202:205], v[44:47]
	v_mfma_f32_16x16x32_bf16 v[44:47], v[158:161], v[206:209], v[44:47]
	v_mfma_f32_16x16x32_bf16 v[28:31], v[154:157], v[210:213], v[28:31]
	v_mfma_f32_16x16x32_bf16 v[28:31], v[158:161], v[214:217], v[28:31]
	v_mfma_f32_16x16x32_bf16 v[12:15], v[154:157], v[218:221], v[12:15]
	v_mfma_f32_16x16x32_bf16 v[12:15], v[158:161], v[222:225], v[12:15]
	v_mfma_f32_16x16x32_bf16 v[56:59], v[170:173], v[194:197], v[56:59]
	v_mfma_f32_16x16x32_bf16 v[56:59], v[174:177], v[198:201], v[56:59]
	v_mfma_f32_16x16x32_bf16 v[40:43], v[170:173], v[202:205], v[40:43]
	v_mfma_f32_16x16x32_bf16 v[40:43], v[174:177], v[206:209], v[40:43]
	v_mfma_f32_16x16x32_bf16 v[24:27], v[170:173], v[210:213], v[24:27]
	v_mfma_f32_16x16x32_bf16 v[24:27], v[174:177], v[214:217], v[24:27]
	v_mfma_f32_16x16x32_bf16 v[8:11], v[170:173], v[218:221], v[8:11]
	v_mfma_f32_16x16x32_bf16 v[8:11], v[174:177], v[222:225], v[8:11]
	s_setprio 0
	s_setprio 1
	v_mfma_f32_16x16x32_bf16 v[52:55], v[178:181], v[194:197], v[52:55]
	v_mfma_f32_16x16x32_bf16 v[52:55], v[182:185], v[198:201], v[52:55]
	v_mfma_f32_16x16x32_bf16 v[36:39], v[178:181], v[202:205], v[36:39]
	v_mfma_f32_16x16x32_bf16 v[36:39], v[182:185], v[206:209], v[36:39]
	v_mfma_f32_16x16x32_bf16 v[20:23], v[178:181], v[210:213], v[20:23]
	v_mfma_f32_16x16x32_bf16 v[20:23], v[182:185], v[214:217], v[20:23]
	v_mfma_f32_16x16x32_bf16 v[4:7], v[178:181], v[218:221], v[4:7]
	v_mfma_f32_16x16x32_bf16 v[4:7], v[182:185], v[222:225], v[4:7]
	v_mfma_f32_16x16x32_bf16 v[48:51], v[186:189], v[194:197], v[48:51]
	v_mfma_f32_16x16x32_bf16 v[48:51], v[190:193], v[198:201], v[48:51]
	v_mfma_f32_16x16x32_bf16 v[32:35], v[186:189], v[202:205], v[32:35]
	v_mfma_f32_16x16x32_bf16 v[32:35], v[190:193], v[206:209], v[32:35]
	v_mfma_f32_16x16x32_bf16 v[16:19], v[186:189], v[210:213], v[16:19]
	v_mfma_f32_16x16x32_bf16 v[16:19], v[190:193], v[214:217], v[16:19]
	v_mfma_f32_16x16x32_bf16 v[0:3], v[186:189], v[218:221], v[0:3]
	v_mfma_f32_16x16x32_bf16 v[0:3], v[190:193], v[222:225], v[0:3]
	s_setprio 0
	s_barrier
	s_add_i32 s53, s53, 2
	s_add_u32 s18, s18, 0x100
	s_addc_u32 s19, s19, 0
	s_add_u32 s51, s51, 0x100
	s_addc_u32 s52, s52, 0
	s_cmp_gt_u32 s53, 29
	s_cbranch_scc1 .Lrot_done_392
; #define PG8_STAGE(bufoff, gbase, voff) do { _Pragma("unroll") for (int _i = 0; _i < 2; ++_i) \
;         __builtin_amdgcn_global_load_lds((const unsigned*)((const char*)(gbase) + (voff)[_i]), (LAS unsigned*)(lds + (bufoff) + ldsw + _i * 8192), 16, 0, 0); } while (0)
; #define PG8_LDA(dst, b, h) do { _Pragma("unroll") for (int m = 0; m < 4; ++m) _Pragma("unroll") for (int k = 0; k < 2; ++k) dst[m][k] = *(const LAS bf16x8*)(lds + PG8_SA(b, h) + aoff + m * 2048 + k * 1024); } while (0)
; #define PG8_LDB(dst, b, h) do { _Pragma("unroll") for (int n = 0; n < 2; ++n) _Pragma("unroll") for (int k = 0; k < 2; ++k) dst[n][k] = *(const LAS bf16x8*)(lds + PG8_SB(b, h) + boff + n * 2048 + k * 1024); } while (0)
; #define PG8_MMA(ai, bj, At, Bt) do { __builtin_amdgcn_s_setprio(1); _Pragma("unroll") for (int m = 0; m < 4; ++m) _Pragma("unroll") for (int n = 0; n < 2; ++n) _Pragma("unroll") for (int k = 0; k < 2; ++k) \
;         acc[ai][bj][m][n] = __builtin_amdgcn_mfma_f32_16x16x32_bf16(Bt[n][k], At[m][k], acc[ai][bj][m][n], 0, 0, 0); __builtin_amdgcn_s_setprio(0); } while (0)
; #define PG8_WAIT_V(n) asm volatile("s_waitcnt vmcnt(" #n ")" ::: "memory")
; #define PG8_WAIT_L(n) asm volatile("s_waitcnt lgkmcnt(" #n ")" ::: "memory")
; #define PG8_BAR __builtin_amdgcn_s_barrier()
; #define PG8_SCHED __builtin_amdgcn_sched_barrier(0)
; template <class EpiT>
; __device__ __forceinline__ void gemm_phase(LAS unsigned char* lds, const Gemm g, const StaticOrder& S, const EpiT& E) {
;     ...
;             PG8_LDB(B0, 0, 0); PG8_LDB(B1, 0, 1); PG8_SCHED; PG8_LDA(At, 0, 0); PG8_STAGE(PG8_SA(1, 1), a1 + hstepA, voffA);
;             PG8_WAIT_V(8); PG8_WAIT_L(0); PG8_BAR; PG8_MMA(0, 0, At, B0); PG8_MMA(0, 1, At, B1); PG8_BAR; PG8_SCHED;
	ds_read_b128 v[154:157], v149
	ds_read_b128 v[158:161], v149 offset:1024
	ds_read_b128 v[170:173], v149 offset:2048
	ds_read_b128 v[174:177], v149 offset:3072
	ds_read_b128 v[178:181], v150
	ds_read_b128 v[182:185], v150 offset:1024
	ds_read_b128 v[186:189], v150 offset:2048
	ds_read_b128 v[190:193], v150 offset:3072
	s_add_u32 s20, s18, 0xfff7c080
	s_addc_u32 s21, s19, -1
	s_cmp_eq_u32 s53, 28
	s_cselect_b32 s23, s5, s21
	s_cselect_b32 s22, s4, s20
	s_cselect_b32 s21, s17, s52
	s_cselect_b32 s20, s16, s51
	v_lshl_add_u64 v[162:163], s[18:19], 0, v[138:139]
	s_add_i32 m0, s35, 0xc000
	ds_read_b128 v[194:197], v151
	ds_read_b128 v[198:201], v151 offset:1024
	ds_read_b128 v[202:205], v151 offset:2048
	ds_read_b128 v[206:209], v151 offset:3072
	ds_read_b128 v[210:213], v151 offset:4096
	ds_read_b128 v[214:217], v151 offset:5120
	ds_read_b128 v[218:221], v151 offset:6144
	ds_read_b128 v[222:225], v151 offset:7168
	global_load_lds_dwordx4 v[162:163], off
	v_lshl_add_u64 v[162:163], s[18:19], 0, v[140:141]
	s_add_i32 m0, s35, 0xe000
	s_nop 0
	global_load_lds_dwordx4 v[162:163], off
	s_waitcnt vmcnt(8)
	s_waitcnt lgkmcnt(0)
	s_barrier
	s_setprio 1
	s_waitcnt lgkmcnt(0)
	v_mfma_f32_16x16x32_bf16 v[124:127], v[154:157], v[194:197], v[124:127]
	v_mfma_f32_16x16x32_bf16 v[124:127], v[158:161], v[198:201], v[124:127]
	v_mfma_f32_16x16x32_bf16 v[108:111], v[154:157], v[202:205], v[108:111]
	v_mfma_f32_16x16x32_bf16 v[108:111], v[158:161], v[206:209], v[108:111]
	v_mfma_f32_16x16x32_bf16 v[92:95], v[154:157], v[210:213], v[92:95]
	v_mfma_f32_16x16x32_bf16 v[92:95], v[158:161], v[214:217], v[92:95]
	v_mfma_f32_16x16x32_bf16 v[76:79], v[154:157], v[218:221], v[76:79]
	v_mfma_f32_16x16x32_bf16 v[76:79], v[158:161], v[222:225], v[76:79]
	v_mfma_f32_16x16x32_bf16 v[120:123], v[170:173], v[194:197], v[120:123]
	v_mfma_f32_16x16x32_bf16 v[120:123], v[174:177], v[198:201], v[120:123]
	v_mfma_f32_16x16x32_bf16 v[104:107], v[170:173], v[202:205], v[104:107]
	v_mfma_f32_16x16x32_bf16 v[104:107], v[174:177], v[206:209], v[104:107]
	v_mfma_f32_16x16x32_bf16 v[88:91], v[170:173], v[210:213], v[88:91]
	v_mfma_f32_16x16x32_bf16 v[88:91], v[174:177], v[214:217], v[88:91]
	v_mfma_f32_16x16x32_bf16 v[72:75], v[170:173], v[218:221], v[72:75]
	v_mfma_f32_16x16x32_bf16 v[72:75], v[174:177], v[222:225], v[72:75]
	s_setprio 0
	s_setprio 1
	v_mfma_f32_16x16x32_bf16 v[116:119], v[178:181], v[194:197], v[116:119]
	v_mfma_f32_16x16x32_bf16 v[116:119], v[182:185], v[198:201], v[116:119]
	v_mfma_f32_16x16x32_bf16 v[100:103], v[178:181], v[202:205], v[100:103]
	v_mfma_f32_16x16x32_bf16 v[100:103], v[182:185], v[206:209], v[100:103]
	v_mfma_f32_16x16x32_bf16 v[84:87], v[178:181], v[210:213], v[84:87]
	v_mfma_f32_16x16x32_bf16 v[84:87], v[182:185], v[214:217], v[84:87]
	v_mfma_f32_16x16x32_bf16 v[68:71], v[178:181], v[218:221], v[68:71]
	v_mfma_f32_16x16x32_bf16 v[68:71], v[182:185], v[222:225], v[68:71]
	v_mfma_f32_16x16x32_bf16 v[112:115], v[186:189], v[194:197], v[112:115]
	v_mfma_f32_16x16x32_bf16 v[112:115], v[190:193], v[198:201], v[112:115]
	v_mfma_f32_16x16x32_bf16 v[96:99], v[186:189], v[202:205], v[96:99]
	v_mfma_f32_16x16x32_bf16 v[96:99], v[190:193], v[206:209], v[96:99]
	v_mfma_f32_16x16x32_bf16 v[80:83], v[186:189], v[210:213], v[80:83]
	v_mfma_f32_16x16x32_bf16 v[80:83], v[190:193], v[214:217], v[80:83]
	v_mfma_f32_16x16x32_bf16 v[64:67], v[186:189], v[218:221], v[64:67]
	v_mfma_f32_16x16x32_bf16 v[64:67], v[190:193], v[222:225], v[64:67]
	s_setprio 0
	s_barrier
	s_branch .Lrot_392

; #define PG8_STAGE(bufoff, gbase, voff) do { _Pragma("unroll") for (int _i = 0; _i < 2; ++_i) \
;         __builtin_amdgcn_global_load_lds((const unsigned*)((const char*)(gbase) + (voff)[_i]), (LAS unsigned*)(lds + (bufoff) + ldsw + _i * 8192), 16, 0, 0); } while (0)
; #define PG8_LDA(dst, b, h) do { _Pragma("unroll") for (int m = 0; m < 4; ++m) _Pragma("unroll") for (int k = 0; k < 2; ++k) dst[m][k] = *(const LAS bf16x8*)(lds + PG8_SA(b, h) + aoff + m * 2048 + k * 1024); } while (0)
; #define PG8_LDB(dst, b, h) do { _Pragma("unroll") for (int n = 0; n < 2; ++n) _Pragma("unroll") for (int k = 0; k < 2; ++k) dst[n][k] = *(const LAS bf16x8*)(lds + PG8_SB(b, h) + boff + n * 2048 + k * 1024); } while (0)
; #define PG8_MMA(ai, bj, At, Bt) do { __builtin_amdgcn_s_setprio(1); _Pragma("unroll") for (int m = 0; m < 4; ++m) _Pragma("unroll") for (int n = 0; n < 2; ++n) _Pragma("unroll") for (int k = 0; k < 2; ++k) \
;         acc[ai][bj][m][n] = __builtin_amdgcn_mfma_f32_16x16x32_bf16(Bt[n][k], At[m][k], acc[ai][bj][m][n], 0, 0, 0); __builtin_amdgcn_s_setprio(0); } while (0)
; #define PG8_WAIT_V(n) asm volatile("s_waitcnt vmcnt(" #n ")" ::: "memory")
; #define PG8_WAIT_L(n) asm volatile("s_waitcnt lgkmcnt(" #n ")" ::: "memory")
; #define PG8_BAR __builtin_amdgcn_s_barrier()
; #define PG8_SCHED __builtin_amdgcn_sched_barrier(0)
; template <class EpiT>
; __device__ __forceinline__ void gemm_phase(LAS unsigned char* lds, const Gemm g, const StaticOrder& S, const EpiT& E) {
;     ...
;             PG8_LDB(B0, 0, 0); PG8_LDB(B1, 0, 1); PG8_SCHED; PG8_LDA(At, 0, 0); PG8_STAGE(PG8_SA(1, 1), a1 + hstepA, voffA);
;             PG8_WAIT_V(8); PG8_WAIT_L(0); PG8_BAR; PG8_MMA(0, 0, At, B0); PG8_MMA(0, 1, At, B1); PG8_BAR; PG8_SCHED;
;             PG8_LDA(At, 0, 1); PG8_STAGE(PG8_SB(0, 0), b2, voffB); PG8_STAGE(PG8_SB(0, 1), b2 + hstepB, voffB); PG8_STAGE(PG8_SA(0, 0), a2, voffA);
.LBB0_516:
	ds_read_b128 v[154:157], v150
	ds_read_b128 v[158:161], v150 offset:1024
	ds_read_b128 v[170:173], v150 offset:2048
	ds_read_b128 v[174:177], v150 offset:3072
	ds_read_b128 v[178:181], v151
	ds_read_b128 v[182:185], v151 offset:1024
	ds_read_b128 v[186:189], v151 offset:2048
	ds_read_b128 v[190:193], v151 offset:3072
	s_add_u32 s18, s16, 0xfff7c080
	s_addc_u32 s19, s17, -1
	s_cmp_eq_u32 s53, 28
	s_cselect_b32 s21, s3, s19
	s_cselect_b32 s20, s2, s18
	s_cselect_b32 s19, s15, s52
	s_cselect_b32 s18, s14, s51
	v_lshl_add_u64 v[144:145], s[16:17], 0, v[136:137]
	s_add_i32 m0, s36, 0xc000
	ds_read_b128 v[194:197], v152
	ds_read_b128 v[198:201], v152 offset:1024
	ds_read_b128 v[202:205], v152 offset:2048
	ds_read_b128 v[206:209], v152 offset:3072
	ds_read_b128 v[210:213], v152 offset:4096
	ds_read_b128 v[214:217], v152 offset:5120
	ds_read_b128 v[218:221], v152 offset:6144
	ds_read_b128 v[222:225], v152 offset:7168
	global_load_lds_dwordx4 v[144:145], off
	v_lshl_add_u64 v[144:145], s[16:17], 0, v[138:139]
	s_add_i32 m0, s36, 0xe000
	s_nop 0
	global_load_lds_dwordx4 v[144:145], off
	s_waitcnt vmcnt(8)
	s_waitcnt lgkmcnt(0)
	s_barrier
	s_setprio 1
	s_waitcnt lgkmcnt(0)
	v_mfma_f32_16x16x32_bf16 v[124:127], v[154:157], v[194:197], v[124:127]
	v_mfma_f32_16x16x32_bf16 v[124:127], v[158:161], v[198:201], v[124:127]
	v_mfma_f32_16x16x32_bf16 v[108:111], v[154:157], v[202:205], v[108:111]
	v_mfma_f32_16x16x32_bf16 v[108:111], v[158:161], v[206:209], v[108:111]
	v_mfma_f32_16x16x32_bf16 v[92:95], v[154:157], v[210:213], v[92:95]
	v_mfma_f32_16x16x32_bf16 v[92:95], v[158:161], v[214:217], v[92:95]
	v_mfma_f32_16x16x32_bf16 v[76:79], v[154:157], v[218:221], v[76:79]
	v_mfma_f32_16x16x32_bf16 v[76:79], v[158:161], v[222:225], v[76:79]
	v_mfma_f32_16x16x32_bf16 v[120:123], v[170:173], v[194:197], v[120:123]
	v_mfma_f32_16x16x32_bf16 v[120:123], v[174:177], v[198:201], v[120:123]
	v_mfma_f32_16x16x32_bf16 v[104:107], v[170:173], v[202:205], v[104:107]
	v_mfma_f32_16x16x32_bf16 v[104:107], v[174:177], v[206:209], v[104:107]
	v_mfma_f32_16x16x32_bf16 v[88:91], v[170:173], v[210:213], v[88:91]
	v_mfma_f32_16x16x32_bf16 v[88:91], v[174:177], v[214:217], v[88:91]
	v_mfma_f32_16x16x32_bf16 v[72:75], v[170:173], v[218:221], v[72:75]
	v_mfma_f32_16x16x32_bf16 v[72:75], v[174:177], v[222:225], v[72:75]
	s_setprio 0
	s_setprio 1
	v_mfma_f32_16x16x32_bf16 v[116:119], v[178:181], v[194:197], v[116:119]
	v_mfma_f32_16x16x32_bf16 v[116:119], v[182:185], v[198:201], v[116:119]
	v_mfma_f32_16x16x32_bf16 v[100:103], v[178:181], v[202:205], v[100:103]
	v_mfma_f32_16x16x32_bf16 v[100:103], v[182:185], v[206:209], v[100:103]
	v_mfma_f32_16x16x32_bf16 v[84:87], v[178:181], v[210:213], v[84:87]
	v_mfma_f32_16x16x32_bf16 v[84:87], v[182:185], v[214:217], v[84:87]
	v_mfma_f32_16x16x32_bf16 v[68:71], v[178:181], v[218:221], v[68:71]
	v_mfma_f32_16x16x32_bf16 v[68:71], v[182:185], v[222:225], v[68:71]
	v_mfma_f32_16x16x32_bf16 v[112:115], v[186:189], v[194:197], v[112:115]
	v_mfma_f32_16x16x32_bf16 v[112:115], v[190:193], v[198:201], v[112:115]
	v_mfma_f32_16x16x32_bf16 v[96:99], v[186:189], v[202:205], v[96:99]
	v_mfma_f32_16x16x32_bf16 v[96:99], v[190:193], v[206:209], v[96:99]
	v_mfma_f32_16x16x32_bf16 v[80:83], v[186:189], v[210:213], v[80:83]
	v_mfma_f32_16x16x32_bf16 v[80:83], v[190:193], v[214:217], v[80:83]
	v_mfma_f32_16x16x32_bf16 v[64:67], v[186:189], v[218:221], v[64:67]
	v_mfma_f32_16x16x32_bf16 v[64:67], v[190:193], v[222:225], v[64:67]
	s_setprio 0
	s_barrier
.Lrot_516:
	s_add_i32 s54, s44, s27
	v_lshl_add_u64 v[144:145], s[18:19], 0, v[132:133]
	s_mov_b32 m0, s54
	ds_read_b128 v[194:197], v152 offset:16384
	ds_read_b128 v[198:201], v152 offset:17408
	ds_read_b128 v[202:205], v152 offset:18432
	ds_read_b128 v[206:209], v152 offset:19456
	ds_read_b128 v[210:213], v152 offset:20480
	ds_read_b128 v[214:217], v152 offset:21504
	ds_read_b128 v[218:221], v152 offset:22528
	ds_read_b128 v[222:225], v152 offset:23552
	global_load_lds_dwordx4 v[144:145], off
	s_add_i32 m0, s54, 0x2000
	s_add_u32 s54, s18, 0x84000
	v_lshl_add_u64 v[162:163], s[18:19], 0, v[128:129]
	s_addc_u32 s55, s19, 0
	s_add_i32 s56, s45, s27
	global_load_lds_dwordx4 v[162:163], off
	v_lshl_add_u64 v[166:167], s[54:55], 0, v[132:133]
	s_mov_b32 m0, s56
	v_lshl_add_u64 v[226:227], s[20:21], 0, v[130:131]
	global_load_lds_dwordx4 v[166:167], off
	v_lshl_add_u64 v[166:167], s[54:55], 0, v[128:129]
	s_add_i32 m0, s56, 0x2000
	s_nop 0
	global_load_lds_dwordx4 v[166:167], off
	v_lshl_add_u64 v[166:167], s[20:21], 0, v[134:135]
	s_mov_b32 m0, s36
	s_nop 0
	global_load_lds_dwordx4 v[166:167], off
	s_mov_b32 m0, s37
	s_nop 0
	global_load_lds_dwordx4 v[226:227], off
	s_waitcnt vmcnt(8)
	s_waitcnt lgkmcnt(0)
	s_barrier
; #define PG8_STAGE(bufoff, gbase, voff) do { _Pragma("unroll") for (int _i = 0; _i < 2; ++_i) \
;         __builtin_amdgcn_global_load_lds((const unsigned*)((const char*)(gbase) + (voff)[_i]), (LAS unsigned*)(lds + (bufoff) + ldsw + _i * 8192), 16, 0, 0); } while (0)
; #define PG8_LDA(dst, b, h) do { _Pragma("unroll") for (int m = 0; m < 4; ++m) _Pragma("unroll") for (int k = 0; k < 2; ++k) dst[m][k] = *(const LAS bf16x8*)(lds + PG8_SA(b, h) + aoff + m * 2048 + k * 1024); } while (0)
; #define PG8_LDB(dst, b, h) do { _Pragma("unroll") for (int n = 0; n < 2; ++n) _Pragma("unroll") for (int k = 0; k < 2; ++k) dst[n][k] = *(const LAS bf16x8*)(lds + PG8_SB(b, h) + boff + n * 2048 + k * 1024); } while (0)
; #define PG8_MMA(ai, bj, At, Bt) do { __builtin_amdgcn_s_setprio(1); _Pragma("unroll") for (int m = 0; m < 4; ++m) _Pragma("unroll") for (int n = 0; n < 2; ++n) _Pragma("unroll") for (int k = 0; k < 2; ++k) \
;         acc[ai][bj][m][n] = __builtin_amdgcn_mfma_f32_16x16x32_bf16(Bt[n][k], At[m][k], acc[ai][bj][m][n], 0, 0, 0); __builtin_amdgcn_s_setprio(0); } while (0)
; #define PG8_WAIT_V(n) asm volatile("s_waitcnt vmcnt(" #n ")" ::: "memory")
; #define PG8_WAIT_L(n) asm volatile("s_waitcnt lgkmcnt(" #n ")" ::: "memory")
; #define PG8_BAR __builtin_amdgcn_s_barrier()
; #define PG8_SCHED __builtin_amdgcn_sched_barrier(0)
; template <class EpiT>
; __device__ __forceinline__ void gemm_phase(LAS unsigned char* lds, const Gemm g, const StaticOrder& S, const EpiT& E) {
;     ...
;             PG8_WAIT_V(8); PG8_WAIT_L(0); PG8_BAR; PG8_MMA(1, 0, At, B0); PG8_MMA(1, 1, At, B1); PG8_BAR; PG8_SCHED;
;             PG8_LDB(B0, 1, 0); PG8_LDB(B1, 1, 1); PG8_SCHED; PG8_LDA(At, 1, 0); PG8_STAGE(PG8_SA(0, 1), a2 + hstepA, voffA);
;             PG8_WAIT_V(8); PG8_WAIT_L(0); PG8_BAR; PG8_MMA(0, 0, At, B0); PG8_MMA(0, 1, At, B1); PG8_BAR; PG8_SCHED;
	s_setprio 1
	s_waitcnt lgkmcnt(0)
	v_mfma_f32_16x16x32_bf16 v[60:63], v[154:157], v[194:197], v[60:63]
	v_mfma_f32_16x16x32_bf16 v[60:63], v[158:161], v[198:201], v[60:63]
	v_mfma_f32_16x16x32_bf16 v[44:47], v[154:157], v[202:205], v[44:47]
	v_mfma_f32_16x16x32_bf16 v[44:47], v[158:161], v[206:209], v[44:47]
	v_mfma_f32_16x16x32_bf16 v[28:31], v[154:157], v[210:213], v[28:31]
	v_mfma_f32_16x16x32_bf16 v[28:31], v[158:161], v[214:217], v[28:31]
	v_mfma_f32_16x16x32_bf16 v[12:15], v[154:157], v[218:221], v[12:15]
	v_mfma_f32_16x16x32_bf16 v[12:15], v[158:161], v[222:225], v[12:15]
	v_mfma_f32_16x16x32_bf16 v[56:59], v[170:173], v[194:197], v[56:59]
	v_mfma_f32_16x16x32_bf16 v[56:59], v[174:177], v[198:201], v[56:59]
	v_mfma_f32_16x16x32_bf16 v[40:43], v[170:173], v[202:205], v[40:43]
	v_mfma_f32_16x16x32_bf16 v[40:43], v[174:177], v[206:209], v[40:43]
	v_mfma_f32_16x16x32_bf16 v[24:27], v[170:173], v[210:213], v[24:27]
	v_mfma_f32_16x16x32_bf16 v[24:27], v[174:177], v[214:217], v[24:27]
	v_mfma_f32_16x16x32_bf16 v[8:11], v[170:173], v[218:221], v[8:11]
	v_mfma_f32_16x16x32_bf16 v[8:11], v[174:177], v[222:225], v[8:11]
	s_setprio 0
	s_setprio 1
	v_mfma_f32_16x16x32_bf16 v[52:55], v[178:181], v[194:197], v[52:55]
	v_mfma_f32_16x16x32_bf16 v[52:55], v[182:185], v[198:201], v[52:55]
	v_mfma_f32_16x16x32_bf16 v[36:39], v[178:181], v[202:205], v[36:39]
	v_mfma_f32_16x16x32_bf16 v[36:39], v[182:185], v[206:209], v[36:39]
	v_mfma_f32_16x16x32_bf16 v[20:23], v[178:181], v[210:213], v[20:23]
	v_mfma_f32_16x16x32_bf16 v[20:23], v[182:185], v[214:217], v[20:23]
	v_mfma_f32_16x16x32_bf16 v[4:7], v[178:181], v[218:221], v[4:7]
	v_mfma_f32_16x16x32_bf16 v[4:7], v[182:185], v[222:225], v[4:7]
	v_mfma_f32_16x16x32_bf16 v[48:51], v[186:189], v[194:197], v[48:51]
	v_mfma_f32_16x16x32_bf16 v[48:51], v[190:193], v[198:201], v[48:51]
	v_mfma_f32_16x16x32_bf16 v[32:35], v[186:189], v[202:205], v[32:35]
	v_mfma_f32_16x16x32_bf16 v[32:35], v[190:193], v[206:209], v[32:35]
	v_mfma_f32_16x16x32_bf16 v[16:19], v[186:189], v[210:213], v[16:19]
	v_mfma_f32_16x16x32_bf16 v[16:19], v[190:193], v[214:217], v[16:19]
	v_mfma_f32_16x16x32_bf16 v[0:3], v[186:189], v[218:221], v[0:3]
	v_mfma_f32_16x16x32_bf16 v[0:3], v[190:193], v[222:225], v[0:3]
	s_setprio 0
	s_barrier
	s_add_i32 s54, 0, 0x18000
	v_add_u32_e32 v153, s54, v147
	s_add_i32 s55, 0, 0x1c000
	ds_read_b128 v[154:157], v153
	ds_read_b128 v[158:161], v153 offset:1024
	ds_read_b128 v[170:173], v153 offset:2048
	ds_read_b128 v[174:177], v153 offset:3072
	v_add_u32_e32 v153, s55, v147
	ds_read_b128 v[178:181], v153
	ds_read_b128 v[182:185], v153 offset:1024
	ds_read_b128 v[186:189], v153 offset:2048
	ds_read_b128 v[190:193], v153 offset:3072
	s_add_u32 s20, s20, 0x84000
	s_addc_u32 s21, s21, 0
	s_mov_b32 m0, s38
	v_lshl_add_u64 v[228:229], s[20:21], 0, v[134:135]
	ds_read_b128 v[194:197], v152 offset:32768
	ds_read_b128 v[198:201], v152 offset:33792
	ds_read_b128 v[202:205], v152 offset:34816
	ds_read_b128 v[206:209], v152 offset:35840
	ds_read_b128 v[210:213], v152 offset:36864
	ds_read_b128 v[214:217], v152 offset:37888
	ds_read_b128 v[218:221], v152 offset:38912
	ds_read_b128 v[222:225], v152 offset:39936
	global_load_lds_dwordx4 v[228:229], off
	v_lshl_add_u64 v[228:229], s[20:21], 0, v[130:131]
	s_mov_b32 m0, s39
	s_nop 0
	global_load_lds_dwordx4 v[228:229], off
	s_waitcnt vmcnt(8)
	s_waitcnt lgkmcnt(0)
	s_barrier
	s_setprio 1
	s_waitcnt lgkmcnt(0)
	v_mfma_f32_16x16x32_bf16 v[124:127], v[154:157], v[194:197], v[124:127]
	v_mfma_f32_16x16x32_bf16 v[124:127], v[158:161], v[198:201], v[124:127]
	v_mfma_f32_16x16x32_bf16 v[108:111], v[154:157], v[202:205], v[108:111]
	v_mfma_f32_16x16x32_bf16 v[108:111], v[158:161], v[206:209], v[108:111]
	v_mfma_f32_16x16x32_bf16 v[92:95], v[154:157], v[210:213], v[92:95]
	v_mfma_f32_16x16x32_bf16 v[92:95], v[158:161], v[214:217], v[92:95]
	v_mfma_f32_16x16x32_bf16 v[76:79], v[154:157], v[218:221], v[76:79]
	v_mfma_f32_16x16x32_bf16 v[76:79], v[158:161], v[222:225], v[76:79]
	v_mfma_f32_16x16x32_bf16 v[120:123], v[170:173], v[194:197], v[120:123]
	v_mfma_f32_16x16x32_bf16 v[120:123], v[174:177], v[198:201], v[120:123]
	v_mfma_f32_16x16x32_bf16 v[104:107], v[170:173], v[202:205], v[104:107]
	v_mfma_f32_16x16x32_bf16 v[104:107], v[174:177], v[206:209], v[104:107]
	v_mfma_f32_16x16x32_bf16 v[88:91], v[170:173], v[210:213], v[88:91]
	v_mfma_f32_16x16x32_bf16 v[88:91], v[174:177], v[214:217], v[88:91]
	v_mfma_f32_16x16x32_bf16 v[72:75], v[170:173], v[218:221], v[72:75]
	v_mfma_f32_16x16x32_bf16 v[72:75], v[174:177], v[222:225], v[72:75]
	s_setprio 0
	s_setprio 1
	v_mfma_f32_16x16x32_bf16 v[116:119], v[178:181], v[194:197], v[116:119]
	v_mfma_f32_16x16x32_bf16 v[116:119], v[182:185], v[198:201], v[116:119]
	v_mfma_f32_16x16x32_bf16 v[100:103], v[178:181], v[202:205], v[100:103]
	v_mfma_f32_16x16x32_bf16 v[100:103], v[182:185], v[206:209], v[100:103]
	v_mfma_f32_16x16x32_bf16 v[84:87], v[178:181], v[210:213], v[84:87]
	v_mfma_f32_16x16x32_bf16 v[84:87], v[182:185], v[214:217], v[84:87]
	v_mfma_f32_16x16x32_bf16 v[68:71], v[178:181], v[218:221], v[68:71]
	v_mfma_f32_16x16x32_bf16 v[68:71], v[182:185], v[222:225], v[68:71]
	v_mfma_f32_16x16x32_bf16 v[112:115], v[186:189], v[194:197], v[112:115]
	v_mfma_f32_16x16x32_bf16 v[112:115], v[190:193], v[198:201], v[112:115]
	v_mfma_f32_16x16x32_bf16 v[96:99], v[186:189], v[202:205], v[96:99]
	v_mfma_f32_16x16x32_bf16 v[96:99], v[190:193], v[206:209], v[96:99]
	v_mfma_f32_16x16x32_bf16 v[80:83], v[186:189], v[210:213], v[80:83]
	v_mfma_f32_16x16x32_bf16 v[80:83], v[190:193], v[214:217], v[80:83]
	v_mfma_f32_16x16x32_bf16 v[64:67], v[186:189], v[218:221], v[64:67]
	v_mfma_f32_16x16x32_bf16 v[64:67], v[190:193], v[222:225], v[64:67]
	s_setprio 0
	s_barrier
; #define PG8_STAGE(bufoff, gbase, voff) do { _Pragma("unroll") for (int _i = 0; _i < 2; ++_i) \
;         __builtin_amdgcn_global_load_lds((const unsigned*)((const char*)(gbase) + (voff)[_i]), (LAS unsigned*)(lds + (bufoff) + ldsw + _i * 8192), 16, 0, 0); } while (0)
; #define PG8_LDA(dst, b, h) do { _Pragma("unroll") for (int m = 0; m < 4; ++m) _Pragma("unroll") for (int k = 0; k < 2; ++k) dst[m][k] = *(const LAS bf16x8*)(lds + PG8_SA(b, h) + aoff + m * 2048 + k * 1024); } while (0)
; #define PG8_MMA(ai, bj, At, Bt) do { __builtin_amdgcn_s_setprio(1); _Pragma("unroll") for (int m = 0; m < 4; ++m) _Pragma("unroll") for (int n = 0; n < 2; ++n) _Pragma("unroll") for (int k = 0; k < 2; ++k) \
;         acc[ai][bj][m][n] = __builtin_amdgcn_mfma_f32_16x16x32_bf16(Bt[n][k], At[m][k], acc[ai][bj][m][n], 0, 0, 0); __builtin_amdgcn_s_setprio(0); } while (0)
; #define PG8_WAIT_V(n) asm volatile("s_waitcnt vmcnt(" #n ")" ::: "memory")
; #define PG8_WAIT_L(n) asm volatile("s_waitcnt lgkmcnt(" #n ")" ::: "memory")
; #define PG8_BAR __builtin_amdgcn_s_barrier()
; #define PG8_SCHED __builtin_amdgcn_sched_barrier(0)
; template <class EpiT>
; __device__ __forceinline__ void gemm_phase(LAS unsigned char* lds, const Gemm g, const StaticOrder& S, const EpiT& E) {
;     ...
;         for (int t = 0; t < nt; t += 2) {
;     ...
;             PG8_LDA(At, 1, 1); PG8_STAGE(PG8_SB(1, 0), b3, voffB); PG8_STAGE(PG8_SB(1, 1), b3 + hstepB, voffB); PG8_STAGE(PG8_SA(1, 0), a3, voffA);
;             PG8_WAIT_V(8); PG8_WAIT_L(0); PG8_BAR; PG8_MMA(1, 0, At, B0); PG8_MMA(1, 1, At, B1); PG8_BAR; PG8_SCHED;
	s_add_i32 s20, s54, s27
	v_lshl_add_u64 v[144:145], v[144:145], 0, s[10:11]
	s_mov_b32 m0, s20
	ds_read_b128 v[194:197], v152 offset:49152
	ds_read_b128 v[198:201], v152 offset:50176
	ds_read_b128 v[202:205], v152 offset:51200
	ds_read_b128 v[206:209], v152 offset:52224
	ds_read_b128 v[210:213], v152 offset:53248
	ds_read_b128 v[214:217], v152 offset:54272
	ds_read_b128 v[218:221], v152 offset:55296
	ds_read_b128 v[222:225], v152 offset:56320
	global_load_lds_dwordx4 v[144:145], off
	s_add_i32 m0, s20, 0x2000
	s_add_u32 s18, s18, 0x84080
	v_lshl_add_u64 v[144:145], v[162:163], 0, s[10:11]
	s_addc_u32 s19, s19, 0
	s_add_i32 s20, s55, s27
	global_load_lds_dwordx4 v[144:145], off
	v_lshl_add_u64 v[144:145], s[18:19], 0, v[132:133]
	s_mov_b32 m0, s20
	s_nop 0
	global_load_lds_dwordx4 v[144:145], off
	v_lshl_add_u64 v[144:145], s[18:19], 0, v[128:129]
	s_add_i32 m0, s20, 0x2000
	s_nop 0
	global_load_lds_dwordx4 v[144:145], off
	v_lshl_add_u64 v[144:145], v[166:167], 0, s[10:11]
	s_mov_b32 m0, s41
	s_nop 0
	global_load_lds_dwordx4 v[144:145], off
	v_lshl_add_u64 v[144:145], v[226:227], 0, s[10:11]
	s_mov_b32 m0, s42
	s_nop 0
	global_load_lds_dwordx4 v[144:145], off
	s_waitcnt vmcnt(8)
	s_waitcnt lgkmcnt(0)
	s_barrier
	s_setprio 1
	s_waitcnt lgkmcnt(0)
	v_mfma_f32_16x16x32_bf16 v[60:63], v[154:157], v[194:197], v[60:63]
	v_mfma_f32_16x16x32_bf16 v[60:63], v[158:161], v[198:201], v[60:63]
	v_mfma_f32_16x16x32_bf16 v[44:47], v[154:157], v[202:205], v[44:47]
	v_mfma_f32_16x16x32_bf16 v[44:47], v[158:161], v[206:209], v[44:47]
	v_mfma_f32_16x16x32_bf16 v[28:31], v[154:157], v[210:213], v[28:31]
	v_mfma_f32_16x16x32_bf16 v[28:31], v[158:161], v[214:217], v[28:31]
	v_mfma_f32_16x16x32_bf16 v[12:15], v[154:157], v[218:221], v[12:15]
	v_mfma_f32_16x16x32_bf16 v[12:15], v[158:161], v[222:225], v[12:15]
	v_mfma_f32_16x16x32_bf16 v[56:59], v[170:173], v[194:197], v[56:59]
	v_mfma_f32_16x16x32_bf16 v[56:59], v[174:177], v[198:201], v[56:59]
	v_mfma_f32_16x16x32_bf16 v[40:43], v[170:173], v[202:205], v[40:43]
	v_mfma_f32_16x16x32_bf16 v[40:43], v[174:177], v[206:209], v[40:43]
	v_mfma_f32_16x16x32_bf16 v[24:27], v[170:173], v[210:213], v[24:27]
	v_mfma_f32_16x16x32_bf16 v[24:27], v[174:177], v[214:217], v[24:27]
	v_mfma_f32_16x16x32_bf16 v[8:11], v[170:173], v[218:221], v[8:11]
	v_mfma_f32_16x16x32_bf16 v[8:11], v[174:177], v[222:225], v[8:11]
	s_setprio 0
	s_setprio 1
	v_mfma_f32_16x16x32_bf16 v[52:55], v[178:181], v[194:197], v[52:55]
	v_mfma_f32_16x16x32_bf16 v[52:55], v[182:185], v[198:201], v[52:55]
	v_mfma_f32_16x16x32_bf16 v[36:39], v[178:181], v[202:205], v[36:39]
	v_mfma_f32_16x16x32_bf16 v[36:39], v[182:185], v[206:209], v[36:39]
	v_mfma_f32_16x16x32_bf16 v[20:23], v[178:181], v[210:213], v[20:23]
	v_mfma_f32_16x16x32_bf16 v[20:23], v[182:185], v[214:217], v[20:23]
	v_mfma_f32_16x16x32_bf16 v[4:7], v[178:181], v[218:221], v[4:7]
	v_mfma_f32_16x16x32_bf16 v[4:7], v[182:185], v[222:225], v[4:7]
	v_mfma_f32_16x16x32_bf16 v[48:51], v[186:189], v[194:197], v[48:51]
	v_mfma_f32_16x16x32_bf16 v[48:51], v[190:193], v[198:201], v[48:51]
	v_mfma_f32_16x16x32_bf16 v[32:35], v[186:189], v[202:205], v[32:35]
	v_mfma_f32_16x16x32_bf16 v[32:35], v[190:193], v[206:209], v[32:35]
	v_mfma_f32_16x16x32_bf16 v[16:19], v[186:189], v[210:213], v[16:19]
	v_mfma_f32_16x16x32_bf16 v[16:19], v[190:193], v[214:217], v[16:19]
	v_mfma_f32_16x16x32_bf16 v[0:3], v[186:189], v[218:221], v[0:3]
	v_mfma_f32_16x16x32_bf16 v[0:3], v[190:193], v[222:225], v[0:3]
	s_setprio 0
	s_barrier
	s_add_i32 s53, s53, 2
	s_add_u32 s16, s16, 0x100
	s_addc_u32 s17, s17, 0
	s_add_u32 s51, s51, 0x100
	s_addc_u32 s52, s52, 0
	s_cmp_gt_u32 s53, 29
	s_cbranch_scc1 .Lrot_done_516
; #define PG8_STAGE(bufoff, gbase, voff) do { _Pragma("unroll") for (int _i = 0; _i < 2; ++_i) \
;         __builtin_amdgcn_global_load_lds((const unsigned*)((const char*)(gbase) + (voff)[_i]), (LAS unsigned*)(lds + (bufoff) + ldsw + _i * 8192), 16, 0, 0); } while (0)
; #define PG8_LDA(dst, b, h) do { _Pragma("unroll") for (int m = 0; m < 4; ++m) _Pragma("unroll") for (int k = 0; k < 2; ++k) dst[m][k] = *(const LAS bf16x8*)(lds + PG8_SA(b, h) + aoff + m * 2048 + k * 1024); } while (0)
; #define PG8_LDB(dst, b, h) do { _Pragma("unroll") for (int n = 0; n < 2; ++n) _Pragma("unroll") for (int k = 0; k < 2; ++k) dst[n][k] = *(const LAS bf16x8*)(lds + PG8_SB(b, h) + boff + n * 2048 + k * 1024); } while (0)
; #define PG8_MMA(ai, bj, At, Bt) do { __builtin_amdgcn_s_setprio(1); _Pragma("unroll") for (int m = 0; m < 4; ++m) _Pragma("unroll") for (int n = 0; n < 2; ++n) _Pragma("unroll") for (int k = 0; k < 2; ++k) \
;         acc[ai][bj][m][n] = __builtin_amdgcn_mfma_f32_16x16x32_bf16(Bt[n][k], At[m][k], acc[ai][bj][m][n], 0, 0, 0); __builtin_amdgcn_s_setprio(0); } while (0)
; #define PG8_WAIT_V(n) asm volatile("s_waitcnt vmcnt(" #n ")" ::: "memory")
; #define PG8_WAIT_L(n) asm volatile("s_waitcnt lgkmcnt(" #n ")" ::: "memory")
; #define PG8_BAR __builtin_amdgcn_s_barrier()
; #define PG8_SCHED __builtin_amdgcn_sched_barrier(0)
; template <class EpiT>
; __device__ __forceinline__ void gemm_phase(LAS unsigned char* lds, const Gemm g, const StaticOrder& S, const EpiT& E) {
;     ...
;             PG8_LDB(B0, 0, 0); PG8_LDB(B1, 0, 1); PG8_SCHED; PG8_LDA(At, 0, 0); PG8_STAGE(PG8_SA(1, 1), a1 + hstepA, voffA);
;             PG8_WAIT_V(8); PG8_WAIT_L(0); PG8_BAR; PG8_MMA(0, 0, At, B0); PG8_MMA(0, 1, At, B1); PG8_BAR; PG8_SCHED;
	ds_read_b128 v[154:157], v150
	ds_read_b128 v[158:161], v150 offset:1024
	ds_read_b128 v[170:173], v150 offset:2048
	ds_read_b128 v[174:177], v150 offset:3072
	ds_read_b128 v[178:181], v151
	ds_read_b128 v[182:185], v151 offset:1024
	ds_read_b128 v[186:189], v151 offset:2048
	ds_read_b128 v[190:193], v151 offset:3072
	s_add_u32 s18, s16, 0xfff7c080
	s_addc_u32 s19, s17, -1
	s_cmp_eq_u32 s53, 28
	s_cselect_b32 s21, s3, s19
	s_cselect_b32 s20, s2, s18
	s_cselect_b32 s19, s15, s52
	s_cselect_b32 s18, s14, s51
	v_lshl_add_u64 v[144:145], s[16:17], 0, v[136:137]
	s_add_i32 m0, s36, 0xc000
	ds_read_b128 v[194:197], v152
	ds_read_b128 v[198:201], v152 offset:1024
	ds_read_b128 v[202:205], v152 offset:2048
	ds_read_b128 v[206:209], v152 offset:3072
	ds_read_b128 v[210:213], v152 offset:4096
	ds_read_b128 v[214:217], v152 offset:5120
	ds_read_b128 v[218:221], v152 offset:6144
	ds_read_b128 v[222:225], v152 offset:7168
	global_load_lds_dwordx4 v[144:145], off
	v_lshl_add_u64 v[144:145], s[16:17], 0, v[138:139]
	s_add_i32 m0, s36, 0xe000
	s_nop 0
	global_load_lds_dwordx4 v[144:145], off
	s_waitcnt vmcnt(8)
	s_waitcnt lgkmcnt(0)
	s_barrier
	s_setprio 1
	s_waitcnt lgkmcnt(0)
	v_mfma_f32_16x16x32_bf16 v[124:127], v[154:157], v[194:197], v[124:127]
	v_mfma_f32_16x16x32_bf16 v[124:127], v[158:161], v[198:201], v[124:127]
	v_mfma_f32_16x16x32_bf16 v[108:111], v[154:157], v[202:205], v[108:111]
	v_mfma_f32_16x16x32_bf16 v[108:111], v[158:161], v[206:209], v[108:111]
	v_mfma_f32_16x16x32_bf16 v[92:95], v[154:157], v[210:213], v[92:95]
	v_mfma_f32_16x16x32_bf16 v[92:95], v[158:161], v[214:217], v[92:95]
	v_mfma_f32_16x16x32_bf16 v[76:79], v[154:157], v[218:221], v[76:79]
	v_mfma_f32_16x16x32_bf16 v[76:79], v[158:161], v[222:225], v[76:79]
	v_mfma_f32_16x16x32_bf16 v[120:123], v[170:173], v[194:197], v[120:123]
	v_mfma_f32_16x16x32_bf16 v[120:123], v[174:177], v[198:201], v[120:123]
	v_mfma_f32_16x16x32_bf16 v[104:107], v[170:173], v[202:205], v[104:107]
	v_mfma_f32_16x16x32_bf16 v[104:107], v[174:177], v[206:209], v[104:107]
	v_mfma_f32_16x16x32_bf16 v[88:91], v[170:173], v[210:213], v[88:91]
	v_mfma_f32_16x16x32_bf16 v[88:91], v[174:177], v[214:217], v[88:91]
	v_mfma_f32_16x16x32_bf16 v[72:75], v[170:173], v[218:221], v[72:75]
	v_mfma_f32_16x16x32_bf16 v[72:75], v[174:177], v[222:225], v[72:75]
	s_setprio 0
	s_setprio 1
	v_mfma_f32_16x16x32_bf16 v[116:119], v[178:181], v[194:197], v[116:119]
	v_mfma_f32_16x16x32_bf16 v[116:119], v[182:185], v[198:201], v[116:119]
	v_mfma_f32_16x16x32_bf16 v[100:103], v[178:181], v[202:205], v[100:103]
	v_mfma_f32_16x16x32_bf16 v[100:103], v[182:185], v[206:209], v[100:103]
	v_mfma_f32_16x16x32_bf16 v[84:87], v[178:181], v[210:213], v[84:87]
	v_mfma_f32_16x16x32_bf16 v[84:87], v[182:185], v[214:217], v[84:87]
	v_mfma_f32_16x16x32_bf16 v[68:71], v[178:181], v[218:221], v[68:71]
	v_mfma_f32_16x16x32_bf16 v[68:71], v[182:185], v[222:225], v[68:71]
	v_mfma_f32_16x16x32_bf16 v[112:115], v[186:189], v[194:197], v[112:115]
	v_mfma_f32_16x16x32_bf16 v[112:115], v[190:193], v[198:201], v[112:115]
	v_mfma_f32_16x16x32_bf16 v[96:99], v[186:189], v[202:205], v[96:99]
	v_mfma_f32_16x16x32_bf16 v[96:99], v[190:193], v[206:209], v[96:99]
	v_mfma_f32_16x16x32_bf16 v[80:83], v[186:189], v[210:213], v[80:83]
	v_mfma_f32_16x16x32_bf16 v[80:83], v[190:193], v[214:217], v[80:83]
	v_mfma_f32_16x16x32_bf16 v[64:67], v[186:189], v[218:221], v[64:67]
	v_mfma_f32_16x16x32_bf16 v[64:67], v[190:193], v[222:225], v[64:67]
	s_setprio 0
	s_barrier
	s_branch .Lrot_516

; #define PG8_STAGE(bufoff, gbase, voff) do { _Pragma("unroll") for (int _i = 0; _i < 2; ++_i) \
;         __builtin_amdgcn_global_load_lds((const unsigned*)((const char*)(gbase) + (voff)[_i]), (LAS unsigned*)(lds + (bufoff) + ldsw + _i * 8192), 16, 0, 0); } while (0)
; #define PG8_LDA(dst, b, h) do { _Pragma("unroll") for (int m = 0; m < 4; ++m) _Pragma("unroll") for (int k = 0; k < 2; ++k) dst[m][k] = *(const LAS bf16x8*)(lds + PG8_SA(b, h) + aoff + m * 2048 + k * 1024); } while (0)
; #define PG8_LDB(dst, b, h) do { _Pragma("unroll") for (int n = 0; n < 2; ++n) _Pragma("unroll") for (int k = 0; k < 2; ++k) dst[n][k] = *(const LAS bf16x8*)(lds + PG8_SB(b, h) + boff + n * 2048 + k * 1024); } while (0)
; #define PG8_MMA(ai, bj, At, Bt) do { __builtin_amdgcn_s_setprio(1); _Pragma("unroll") for (int m = 0; m < 4; ++m) _Pragma("unroll") for (int n = 0; n < 2; ++n) _Pragma("unroll") for (int k = 0; k < 2; ++k) \
;         acc[ai][bj][m][n] = __builtin_amdgcn_mfma_f32_16x16x32_bf16(Bt[n][k], At[m][k], acc[ai][bj][m][n], 0, 0, 0); __builtin_amdgcn_s_setprio(0); } while (0)
; #define PG8_WAIT_V(n) asm volatile("s_waitcnt vmcnt(" #n ")" ::: "memory")
; #define PG8_WAIT_L(n) asm volatile("s_waitcnt lgkmcnt(" #n ")" ::: "memory")
; #define PG8_BAR __builtin_amdgcn_s_barrier()
; #define PG8_SCHED __builtin_amdgcn_sched_barrier(0)
; template <class EpiT>
; __device__ __forceinline__ void gemm_phase(LAS unsigned char* lds, const Gemm g, const StaticOrder& S, const EpiT& E) {
;     ...
;             PG8_LDB(B0, 0, 0); PG8_LDB(B1, 0, 1); PG8_SCHED; PG8_LDA(At, 0, 0); PG8_STAGE(PG8_SA(1, 1), a1 + hstepA, voffA);
;             PG8_WAIT_V(8); PG8_WAIT_L(0); PG8_BAR; PG8_MMA(0, 0, At, B0); PG8_MMA(0, 1, At, B1); PG8_BAR; PG8_SCHED;
;             PG8_LDA(At, 0, 1); PG8_STAGE(PG8_SB(0, 0), b2, voffB); PG8_STAGE(PG8_SB(0, 1), b2 + hstepB, voffB); PG8_STAGE(PG8_SA(0, 0), a2, voffA);
.LBB0_595:
	ds_read_b128 v[154:157], v150
	ds_read_b128 v[158:161], v150 offset:1024
	ds_read_b128 v[170:173], v150 offset:2048
	ds_read_b128 v[174:177], v150 offset:3072
	ds_read_b128 v[178:181], v151
	ds_read_b128 v[182:185], v151 offset:1024
	ds_read_b128 v[186:189], v151 offset:2048
	ds_read_b128 v[190:193], v151 offset:3072
	s_add_u32 s20, s18, 0xffe9c080
	s_addc_u32 s21, s19, -1
	s_cmpk_eq_i32 s55, 0x54
	s_cselect_b32 s23, s5, s21
	s_cselect_b32 s22, s4, s20
	s_cselect_b32 s21, s17, s54
	s_cselect_b32 s20, s16, s53
	v_lshl_add_u64 v[162:163], s[18:19], 0, v[138:139]
	s_add_i32 m0, s37, 0xc000
	ds_read_b128 v[194:197], v152
	ds_read_b128 v[198:201], v152 offset:1024
	ds_read_b128 v[202:205], v152 offset:2048
	ds_read_b128 v[206:209], v152 offset:3072
	ds_read_b128 v[210:213], v152 offset:4096
	ds_read_b128 v[214:217], v152 offset:5120
	ds_read_b128 v[218:221], v152 offset:6144
	ds_read_b128 v[222:225], v152 offset:7168
	global_load_lds_dwordx4 v[162:163], off
	v_lshl_add_u64 v[162:163], s[18:19], 0, v[140:141]
	s_add_i32 m0, s37, 0xe000
	s_nop 0
	global_load_lds_dwordx4 v[162:163], off
	s_waitcnt vmcnt(8)
	s_waitcnt lgkmcnt(0)
	s_barrier
	s_setprio 1
	s_waitcnt lgkmcnt(0)
	v_mfma_f32_16x16x32_bf16 v[124:127], v[154:157], v[194:197], v[124:127]
	v_mfma_f32_16x16x32_bf16 v[124:127], v[158:161], v[198:201], v[124:127]
	v_mfma_f32_16x16x32_bf16 v[108:111], v[154:157], v[202:205], v[108:111]
	v_mfma_f32_16x16x32_bf16 v[108:111], v[158:161], v[206:209], v[108:111]
	v_mfma_f32_16x16x32_bf16 v[92:95], v[154:157], v[210:213], v[92:95]
	v_mfma_f32_16x16x32_bf16 v[92:95], v[158:161], v[214:217], v[92:95]
	v_mfma_f32_16x16x32_bf16 v[76:79], v[154:157], v[218:221], v[76:79]
	v_mfma_f32_16x16x32_bf16 v[76:79], v[158:161], v[222:225], v[76:79]
	v_mfma_f32_16x16x32_bf16 v[120:123], v[170:173], v[194:197], v[120:123]
	v_mfma_f32_16x16x32_bf16 v[120:123], v[174:177], v[198:201], v[120:123]
	v_mfma_f32_16x16x32_bf16 v[104:107], v[170:173], v[202:205], v[104:107]
	v_mfma_f32_16x16x32_bf16 v[104:107], v[174:177], v[206:209], v[104:107]
	v_mfma_f32_16x16x32_bf16 v[88:91], v[170:173], v[210:213], v[88:91]
	v_mfma_f32_16x16x32_bf16 v[88:91], v[174:177], v[214:217], v[88:91]
	v_mfma_f32_16x16x32_bf16 v[72:75], v[170:173], v[218:221], v[72:75]
	v_mfma_f32_16x16x32_bf16 v[72:75], v[174:177], v[222:225], v[72:75]
	s_setprio 0
	s_setprio 1
	v_mfma_f32_16x16x32_bf16 v[116:119], v[178:181], v[194:197], v[116:119]
	v_mfma_f32_16x16x32_bf16 v[116:119], v[182:185], v[198:201], v[116:119]
	v_mfma_f32_16x16x32_bf16 v[100:103], v[178:181], v[202:205], v[100:103]
	v_mfma_f32_16x16x32_bf16 v[100:103], v[182:185], v[206:209], v[100:103]
	v_mfma_f32_16x16x32_bf16 v[84:87], v[178:181], v[210:213], v[84:87]
	v_mfma_f32_16x16x32_bf16 v[84:87], v[182:185], v[214:217], v[84:87]
	v_mfma_f32_16x16x32_bf16 v[68:71], v[178:181], v[218:221], v[68:71]
	v_mfma_f32_16x16x32_bf16 v[68:71], v[182:185], v[222:225], v[68:71]
	v_mfma_f32_16x16x32_bf16 v[112:115], v[186:189], v[194:197], v[112:115]
	v_mfma_f32_16x16x32_bf16 v[112:115], v[190:193], v[198:201], v[112:115]
	v_mfma_f32_16x16x32_bf16 v[96:99], v[186:189], v[202:205], v[96:99]
	v_mfma_f32_16x16x32_bf16 v[96:99], v[190:193], v[206:209], v[96:99]
	v_mfma_f32_16x16x32_bf16 v[80:83], v[186:189], v[210:213], v[80:83]
	v_mfma_f32_16x16x32_bf16 v[80:83], v[190:193], v[214:217], v[80:83]
	v_mfma_f32_16x16x32_bf16 v[64:67], v[186:189], v[218:221], v[64:67]
	v_mfma_f32_16x16x32_bf16 v[64:67], v[190:193], v[222:225], v[64:67]
	s_setprio 0
	s_barrier
.Lrot_595:
	s_add_i32 s56, s46, s36
	v_lshl_add_u64 v[162:163], s[20:21], 0, v[130:131]
	s_mov_b32 m0, s56
	ds_read_b128 v[194:197], v152 offset:16384
	ds_read_b128 v[198:201], v152 offset:17408
	ds_read_b128 v[202:205], v152 offset:18432
	ds_read_b128 v[206:209], v152 offset:19456
	ds_read_b128 v[210:213], v152 offset:20480
	ds_read_b128 v[214:217], v152 offset:21504
	ds_read_b128 v[218:221], v152 offset:22528
	ds_read_b128 v[222:225], v152 offset:23552
	global_load_lds_dwordx4 v[162:163], off
	s_add_i32 m0, s56, 0x2000
	s_add_u32 s56, s20, 0x164000
	v_lshl_add_u64 v[166:167], s[20:21], 0, v[134:135]
	s_addc_u32 s57, s21, 0
	s_add_i32 s58, s47, s36
	global_load_lds_dwordx4 v[166:167], off
	v_lshl_add_u64 v[226:227], s[56:57], 0, v[130:131]
	s_mov_b32 m0, s58
	v_lshl_add_u64 v[228:229], s[22:23], 0, v[132:133]
	global_load_lds_dwordx4 v[226:227], off
	v_lshl_add_u64 v[226:227], s[56:57], 0, v[134:135]
	s_add_i32 m0, s58, 0x2000
	s_nop 0
	global_load_lds_dwordx4 v[226:227], off
	v_lshl_add_u64 v[226:227], s[22:23], 0, v[128:129]
	s_mov_b32 m0, s37
	s_nop 0
	global_load_lds_dwordx4 v[226:227], off
	s_mov_b32 m0, s38
	s_nop 0
	global_load_lds_dwordx4 v[228:229], off
	s_waitcnt vmcnt(8)
	s_waitcnt lgkmcnt(0)
	s_barrier
; #define PG8_STAGE(bufoff, gbase, voff) do { _Pragma("unroll") for (int _i = 0; _i < 2; ++_i) \
;         __builtin_amdgcn_global_load_lds((const unsigned*)((const char*)(gbase) + (voff)[_i]), (LAS unsigned*)(lds + (bufoff) + ldsw + _i * 8192), 16, 0, 0); } while (0)
; #define PG8_LDA(dst, b, h) do { _Pragma("unroll") for (int m = 0; m < 4; ++m) _Pragma("unroll") for (int k = 0; k < 2; ++k) dst[m][k] = *(const LAS bf16x8*)(lds + PG8_SA(b, h) + aoff + m * 2048 + k * 1024); } while (0)
; #define PG8_LDB(dst, b, h) do { _Pragma("unroll") for (int n = 0; n < 2; ++n) _Pragma("unroll") for (int k = 0; k < 2; ++k) dst[n][k] = *(const LAS bf16x8*)(lds + PG8_SB(b, h) + boff + n * 2048 + k * 1024); } while (0)
; #define PG8_MMA(ai, bj, At, Bt) do { __builtin_amdgcn_s_setprio(1); _Pragma("unroll") for (int m = 0; m < 4; ++m) _Pragma("unroll") for (int n = 0; n < 2; ++n) _Pragma("unroll") for (int k = 0; k < 2; ++k) \
;         acc[ai][bj][m][n] = __builtin_amdgcn_mfma_f32_16x16x32_bf16(Bt[n][k], At[m][k], acc[ai][bj][m][n], 0, 0, 0); __builtin_amdgcn_s_setprio(0); } while (0)
; #define PG8_WAIT_V(n) asm volatile("s_waitcnt vmcnt(" #n ")" ::: "memory")
; #define PG8_WAIT_L(n) asm volatile("s_waitcnt lgkmcnt(" #n ")" ::: "memory")
; #define PG8_BAR __builtin_amdgcn_s_barrier()
; #define PG8_SCHED __builtin_amdgcn_sched_barrier(0)
; template <class EpiT>
; __device__ __forceinline__ void gemm_phase(LAS unsigned char* lds, const Gemm g, const StaticOrder& S, const EpiT& E) {
;     ...
;             PG8_WAIT_V(8); PG8_WAIT_L(0); PG8_BAR; PG8_MMA(1, 0, At, B0); PG8_MMA(1, 1, At, B1); PG8_BAR; PG8_SCHED;
;             PG8_LDB(B0, 1, 0); PG8_LDB(B1, 1, 1); PG8_SCHED; PG8_LDA(At, 1, 0); PG8_STAGE(PG8_SA(0, 1), a2 + hstepA, voffA);
;             PG8_WAIT_V(8); PG8_WAIT_L(0); PG8_BAR; PG8_MMA(0, 0, At, B0); PG8_MMA(0, 1, At, B1); PG8_BAR; PG8_SCHED;
	s_setprio 1
	s_waitcnt lgkmcnt(0)
	v_mfma_f32_16x16x32_bf16 v[60:63], v[154:157], v[194:197], v[60:63]
	v_mfma_f32_16x16x32_bf16 v[60:63], v[158:161], v[198:201], v[60:63]
	v_mfma_f32_16x16x32_bf16 v[44:47], v[154:157], v[202:205], v[44:47]
	v_mfma_f32_16x16x32_bf16 v[44:47], v[158:161], v[206:209], v[44:47]
	v_mfma_f32_16x16x32_bf16 v[28:31], v[154:157], v[210:213], v[28:31]
	v_mfma_f32_16x16x32_bf16 v[28:31], v[158:161], v[214:217], v[28:31]
	v_mfma_f32_16x16x32_bf16 v[12:15], v[154:157], v[218:221], v[12:15]
	v_mfma_f32_16x16x32_bf16 v[12:15], v[158:161], v[222:225], v[12:15]
	v_mfma_f32_16x16x32_bf16 v[56:59], v[170:173], v[194:197], v[56:59]
	v_mfma_f32_16x16x32_bf16 v[56:59], v[174:177], v[198:201], v[56:59]
	v_mfma_f32_16x16x32_bf16 v[40:43], v[170:173], v[202:205], v[40:43]
	v_mfma_f32_16x16x32_bf16 v[40:43], v[174:177], v[206:209], v[40:43]
	v_mfma_f32_16x16x32_bf16 v[24:27], v[170:173], v[210:213], v[24:27]
	v_mfma_f32_16x16x32_bf16 v[24:27], v[174:177], v[214:217], v[24:27]
	v_mfma_f32_16x16x32_bf16 v[8:11], v[170:173], v[218:221], v[8:11]
	v_mfma_f32_16x16x32_bf16 v[8:11], v[174:177], v[222:225], v[8:11]
	s_setprio 0
	s_setprio 1
	v_mfma_f32_16x16x32_bf16 v[52:55], v[178:181], v[194:197], v[52:55]
	v_mfma_f32_16x16x32_bf16 v[52:55], v[182:185], v[198:201], v[52:55]
	v_mfma_f32_16x16x32_bf16 v[36:39], v[178:181], v[202:205], v[36:39]
	v_mfma_f32_16x16x32_bf16 v[36:39], v[182:185], v[206:209], v[36:39]
	v_mfma_f32_16x16x32_bf16 v[20:23], v[178:181], v[210:213], v[20:23]
	v_mfma_f32_16x16x32_bf16 v[20:23], v[182:185], v[214:217], v[20:23]
	v_mfma_f32_16x16x32_bf16 v[4:7], v[178:181], v[218:221], v[4:7]
	v_mfma_f32_16x16x32_bf16 v[4:7], v[182:185], v[222:225], v[4:7]
	v_mfma_f32_16x16x32_bf16 v[48:51], v[186:189], v[194:197], v[48:51]
	v_mfma_f32_16x16x32_bf16 v[48:51], v[190:193], v[198:201], v[48:51]
	v_mfma_f32_16x16x32_bf16 v[32:35], v[186:189], v[202:205], v[32:35]
	v_mfma_f32_16x16x32_bf16 v[32:35], v[190:193], v[206:209], v[32:35]
	v_mfma_f32_16x16x32_bf16 v[16:19], v[186:189], v[210:213], v[16:19]
	v_mfma_f32_16x16x32_bf16 v[16:19], v[190:193], v[214:217], v[16:19]
	v_mfma_f32_16x16x32_bf16 v[0:3], v[186:189], v[218:221], v[0:3]
	v_mfma_f32_16x16x32_bf16 v[0:3], v[190:193], v[222:225], v[0:3]
	s_setprio 0
	s_barrier
	s_add_i32 s56, 0, 0x18000
	v_add_u32_e32 v165, s56, v146
	s_add_i32 s57, 0, 0x1c000
	ds_read_b128 v[154:157], v165
	ds_read_b128 v[158:161], v165 offset:1024
	ds_read_b128 v[170:173], v165 offset:2048
	ds_read_b128 v[174:177], v165 offset:3072
	v_add_u32_e32 v165, s57, v146
	ds_read_b128 v[178:181], v165
	ds_read_b128 v[182:185], v165 offset:1024
	ds_read_b128 v[186:189], v165 offset:2048
	ds_read_b128 v[190:193], v165 offset:3072
	s_add_u32 s22, s22, 0x164000
	s_addc_u32 s23, s23, 0
	s_mov_b32 m0, s39
	v_lshl_add_u64 v[230:231], s[22:23], 0, v[128:129]
	ds_read_b128 v[194:197], v152 offset:32768
	ds_read_b128 v[198:201], v152 offset:33792
	ds_read_b128 v[202:205], v152 offset:34816
	ds_read_b128 v[206:209], v152 offset:35840
	ds_read_b128 v[210:213], v152 offset:36864
	ds_read_b128 v[214:217], v152 offset:37888
	ds_read_b128 v[218:221], v152 offset:38912
	ds_read_b128 v[222:225], v152 offset:39936
	global_load_lds_dwordx4 v[230:231], off
	v_lshl_add_u64 v[230:231], s[22:23], 0, v[132:133]
	s_mov_b32 m0, s40
	s_nop 0
	global_load_lds_dwordx4 v[230:231], off
	s_waitcnt vmcnt(8)
	s_waitcnt lgkmcnt(0)
	s_barrier
	s_setprio 1
	s_waitcnt lgkmcnt(0)
	v_mfma_f32_16x16x32_bf16 v[124:127], v[154:157], v[194:197], v[124:127]
	v_mfma_f32_16x16x32_bf16 v[124:127], v[158:161], v[198:201], v[124:127]
	v_mfma_f32_16x16x32_bf16 v[108:111], v[154:157], v[202:205], v[108:111]
	v_mfma_f32_16x16x32_bf16 v[108:111], v[158:161], v[206:209], v[108:111]
	v_mfma_f32_16x16x32_bf16 v[92:95], v[154:157], v[210:213], v[92:95]
	v_mfma_f32_16x16x32_bf16 v[92:95], v[158:161], v[214:217], v[92:95]
	v_mfma_f32_16x16x32_bf16 v[76:79], v[154:157], v[218:221], v[76:79]
	v_mfma_f32_16x16x32_bf16 v[76:79], v[158:161], v[222:225], v[76:79]
	v_mfma_f32_16x16x32_bf16 v[120:123], v[170:173], v[194:197], v[120:123]
	v_mfma_f32_16x16x32_bf16 v[120:123], v[174:177], v[198:201], v[120:123]
	v_mfma_f32_16x16x32_bf16 v[104:107], v[170:173], v[202:205], v[104:107]
	v_mfma_f32_16x16x32_bf16 v[104:107], v[174:177], v[206:209], v[104:107]
	v_mfma_f32_16x16x32_bf16 v[88:91], v[170:173], v[210:213], v[88:91]
	v_mfma_f32_16x16x32_bf16 v[88:91], v[174:177], v[214:217], v[88:91]
	v_mfma_f32_16x16x32_bf16 v[72:75], v[170:173], v[218:221], v[72:75]
	v_mfma_f32_16x16x32_bf16 v[72:75], v[174:177], v[222:225], v[72:75]
	s_setprio 0
	s_setprio 1
	v_mfma_f32_16x16x32_bf16 v[116:119], v[178:181], v[194:197], v[116:119]
	v_mfma_f32_16x16x32_bf16 v[116:119], v[182:185], v[198:201], v[116:119]
	v_mfma_f32_16x16x32_bf16 v[100:103], v[178:181], v[202:205], v[100:103]
	v_mfma_f32_16x16x32_bf16 v[100:103], v[182:185], v[206:209], v[100:103]
	v_mfma_f32_16x16x32_bf16 v[84:87], v[178:181], v[210:213], v[84:87]
	v_mfma_f32_16x16x32_bf16 v[84:87], v[182:185], v[214:217], v[84:87]
	v_mfma_f32_16x16x32_bf16 v[68:71], v[178:181], v[218:221], v[68:71]
	v_mfma_f32_16x16x32_bf16 v[68:71], v[182:185], v[222:225], v[68:71]
	v_mfma_f32_16x16x32_bf16 v[112:115], v[186:189], v[194:197], v[112:115]
	v_mfma_f32_16x16x32_bf16 v[112:115], v[190:193], v[198:201], v[112:115]
	v_mfma_f32_16x16x32_bf16 v[96:99], v[186:189], v[202:205], v[96:99]
	v_mfma_f32_16x16x32_bf16 v[96:99], v[190:193], v[206:209], v[96:99]
	v_mfma_f32_16x16x32_bf16 v[80:83], v[186:189], v[210:213], v[80:83]
	v_mfma_f32_16x16x32_bf16 v[80:83], v[190:193], v[214:217], v[80:83]
	v_mfma_f32_16x16x32_bf16 v[64:67], v[186:189], v[218:221], v[64:67]
	v_mfma_f32_16x16x32_bf16 v[64:67], v[190:193], v[222:225], v[64:67]
	s_setprio 0
	s_barrier
; #define PG8_STAGE(bufoff, gbase, voff) do { _Pragma("unroll") for (int _i = 0; _i < 2; ++_i) \
;         __builtin_amdgcn_global_load_lds((const unsigned*)((const char*)(gbase) + (voff)[_i]), (LAS unsigned*)(lds + (bufoff) + ldsw + _i * 8192), 16, 0, 0); } while (0)
; #define PG8_LDA(dst, b, h) do { _Pragma("unroll") for (int m = 0; m < 4; ++m) _Pragma("unroll") for (int k = 0; k < 2; ++k) dst[m][k] = *(const LAS bf16x8*)(lds + PG8_SA(b, h) + aoff + m * 2048 + k * 1024); } while (0)
; #define PG8_MMA(ai, bj, At, Bt) do { __builtin_amdgcn_s_setprio(1); _Pragma("unroll") for (int m = 0; m < 4; ++m) _Pragma("unroll") for (int n = 0; n < 2; ++n) _Pragma("unroll") for (int k = 0; k < 2; ++k) \
;         acc[ai][bj][m][n] = __builtin_amdgcn_mfma_f32_16x16x32_bf16(Bt[n][k], At[m][k], acc[ai][bj][m][n], 0, 0, 0); __builtin_amdgcn_s_setprio(0); } while (0)
; #define PG8_WAIT_V(n) asm volatile("s_waitcnt vmcnt(" #n ")" ::: "memory")
; #define PG8_WAIT_L(n) asm volatile("s_waitcnt lgkmcnt(" #n ")" ::: "memory")
; #define PG8_BAR __builtin_amdgcn_s_barrier()
; #define PG8_SCHED __builtin_amdgcn_sched_barrier(0)
; template <class EpiT>
; __device__ __forceinline__ void gemm_phase(LAS unsigned char* lds, const Gemm g, const StaticOrder& S, const EpiT& E) {
;     ...
;         for (int t = 0; t < nt; t += 2) {
;     ...
;             PG8_LDA(At, 1, 1); PG8_STAGE(PG8_SB(1, 0), b3, voffB); PG8_STAGE(PG8_SB(1, 1), b3 + hstepB, voffB); PG8_STAGE(PG8_SA(1, 0), a3, voffA);
;             PG8_WAIT_V(8); PG8_WAIT_L(0); PG8_BAR; PG8_MMA(1, 0, At, B0); PG8_MMA(1, 1, At, B1); PG8_BAR; PG8_SCHED;
	s_add_i32 s22, s56, s36
	v_lshl_add_u64 v[162:163], v[162:163], 0, s[12:13]
	s_mov_b32 m0, s22
	ds_read_b128 v[194:197], v152 offset:49152
	ds_read_b128 v[198:201], v152 offset:50176
	ds_read_b128 v[202:205], v152 offset:51200
	ds_read_b128 v[206:209], v152 offset:52224
	ds_read_b128 v[210:213], v152 offset:53248
	ds_read_b128 v[214:217], v152 offset:54272
	ds_read_b128 v[218:221], v152 offset:55296
	ds_read_b128 v[222:225], v152 offset:56320
	global_load_lds_dwordx4 v[162:163], off
	s_add_i32 m0, s22, 0x2000
	s_add_u32 s20, s20, 0x164080
	v_lshl_add_u64 v[162:163], v[166:167], 0, s[12:13]
	s_addc_u32 s21, s21, 0
	s_add_i32 s22, s57, s36
	global_load_lds_dwordx4 v[162:163], off
	v_lshl_add_u64 v[162:163], s[20:21], 0, v[130:131]
	s_mov_b32 m0, s22
	s_nop 0
	global_load_lds_dwordx4 v[162:163], off
	v_lshl_add_u64 v[162:163], s[20:21], 0, v[134:135]
	s_add_i32 m0, s22, 0x2000
	s_nop 0
	global_load_lds_dwordx4 v[162:163], off
	v_lshl_add_u64 v[162:163], v[226:227], 0, s[12:13]
	s_mov_b32 m0, s42
	s_nop 0
	global_load_lds_dwordx4 v[162:163], off
	v_lshl_add_u64 v[162:163], v[228:229], 0, s[12:13]
	s_mov_b32 m0, s43
	s_nop 0
	global_load_lds_dwordx4 v[162:163], off
	s_waitcnt vmcnt(8)
	s_waitcnt lgkmcnt(0)
	s_barrier
	s_setprio 1
	s_waitcnt lgkmcnt(0)
	v_mfma_f32_16x16x32_bf16 v[60:63], v[154:157], v[194:197], v[60:63]
	v_mfma_f32_16x16x32_bf16 v[60:63], v[158:161], v[198:201], v[60:63]
	v_mfma_f32_16x16x32_bf16 v[44:47], v[154:157], v[202:205], v[44:47]
	v_mfma_f32_16x16x32_bf16 v[44:47], v[158:161], v[206:209], v[44:47]
	v_mfma_f32_16x16x32_bf16 v[28:31], v[154:157], v[210:213], v[28:31]
	v_mfma_f32_16x16x32_bf16 v[28:31], v[158:161], v[214:217], v[28:31]
	v_mfma_f32_16x16x32_bf16 v[12:15], v[154:157], v[218:221], v[12:15]
	v_mfma_f32_16x16x32_bf16 v[12:15], v[158:161], v[222:225], v[12:15]
	v_mfma_f32_16x16x32_bf16 v[56:59], v[170:173], v[194:197], v[56:59]
	v_mfma_f32_16x16x32_bf16 v[56:59], v[174:177], v[198:201], v[56:59]
	v_mfma_f32_16x16x32_bf16 v[40:43], v[170:173], v[202:205], v[40:43]
	v_mfma_f32_16x16x32_bf16 v[40:43], v[174:177], v[206:209], v[40:43]
	v_mfma_f32_16x16x32_bf16 v[24:27], v[170:173], v[210:213], v[24:27]
	v_mfma_f32_16x16x32_bf16 v[24:27], v[174:177], v[214:217], v[24:27]
	v_mfma_f32_16x16x32_bf16 v[8:11], v[170:173], v[218:221], v[8:11]
	v_mfma_f32_16x16x32_bf16 v[8:11], v[174:177], v[222:225], v[8:11]
	s_setprio 0
	s_setprio 1
	v_mfma_f32_16x16x32_bf16 v[52:55], v[178:181], v[194:197], v[52:55]
	v_mfma_f32_16x16x32_bf16 v[52:55], v[182:185], v[198:201], v[52:55]
	v_mfma_f32_16x16x32_bf16 v[36:39], v[178:181], v[202:205], v[36:39]
	v_mfma_f32_16x16x32_bf16 v[36:39], v[182:185], v[206:209], v[36:39]
	v_mfma_f32_16x16x32_bf16 v[20:23], v[178:181], v[210:213], v[20:23]
	v_mfma_f32_16x16x32_bf16 v[20:23], v[182:185], v[214:217], v[20:23]
	v_mfma_f32_16x16x32_bf16 v[4:7], v[178:181], v[218:221], v[4:7]
	v_mfma_f32_16x16x32_bf16 v[4:7], v[182:185], v[222:225], v[4:7]
	v_mfma_f32_16x16x32_bf16 v[48:51], v[186:189], v[194:197], v[48:51]
	v_mfma_f32_16x16x32_bf16 v[48:51], v[190:193], v[198:201], v[48:51]
	v_mfma_f32_16x16x32_bf16 v[32:35], v[186:189], v[202:205], v[32:35]
	v_mfma_f32_16x16x32_bf16 v[32:35], v[190:193], v[206:209], v[32:35]
	v_mfma_f32_16x16x32_bf16 v[16:19], v[186:189], v[210:213], v[16:19]
	v_mfma_f32_16x16x32_bf16 v[16:19], v[190:193], v[214:217], v[16:19]
	v_mfma_f32_16x16x32_bf16 v[0:3], v[186:189], v[218:221], v[0:3]
	v_mfma_f32_16x16x32_bf16 v[0:3], v[190:193], v[222:225], v[0:3]
	s_setprio 0
	s_barrier
	s_add_i32 s55, s55, 2
	s_add_u32 s18, s18, 0x100
	s_addc_u32 s19, s19, 0
	s_add_u32 s53, s53, 0x100
	s_addc_u32 s54, s54, 0
	s_cmpk_gt_u32 s55, 0x55
	s_cbranch_scc1 .Lrot_done_595
; #define PG8_STAGE(bufoff, gbase, voff) do { _Pragma("unroll") for (int _i = 0; _i < 2; ++_i) \
;         __builtin_amdgcn_global_load_lds((const unsigned*)((const char*)(gbase) + (voff)[_i]), (LAS unsigned*)(lds + (bufoff) + ldsw + _i * 8192), 16, 0, 0); } while (0)
; #define PG8_LDA(dst, b, h) do { _Pragma("unroll") for (int m = 0; m < 4; ++m) _Pragma("unroll") for (int k = 0; k < 2; ++k) dst[m][k] = *(const LAS bf16x8*)(lds + PG8_SA(b, h) + aoff + m * 2048 + k * 1024); } while (0)
; #define PG8_LDB(dst, b, h) do { _Pragma("unroll") for (int n = 0; n < 2; ++n) _Pragma("unroll") for (int k = 0; k < 2; ++k) dst[n][k] = *(const LAS bf16x8*)(lds + PG8_SB(b, h) + boff + n * 2048 + k * 1024); } while (0)
; #define PG8_MMA(ai, bj, At, Bt) do { __builtin_amdgcn_s_setprio(1); _Pragma("unroll") for (int m = 0; m < 4; ++m) _Pragma("unroll") for (int n = 0; n < 2; ++n) _Pragma("unroll") for (int k = 0; k < 2; ++k) \
;         acc[ai][bj][m][n] = __builtin_amdgcn_mfma_f32_16x16x32_bf16(Bt[n][k], At[m][k], acc[ai][bj][m][n], 0, 0, 0); __builtin_amdgcn_s_setprio(0); } while (0)
; #define PG8_WAIT_V(n) asm volatile("s_waitcnt vmcnt(" #n ")" ::: "memory")
; #define PG8_WAIT_L(n) asm volatile("s_waitcnt lgkmcnt(" #n ")" ::: "memory")
; #define PG8_BAR __builtin_amdgcn_s_barrier()
; #define PG8_SCHED __builtin_amdgcn_sched_barrier(0)
; template <class EpiT>
; __device__ __forceinline__ void gemm_phase(LAS unsigned char* lds, const Gemm g, const StaticOrder& S, const EpiT& E) {
;     ...
;             PG8_LDB(B0, 0, 0); PG8_LDB(B1, 0, 1); PG8_SCHED; PG8_LDA(At, 0, 0); PG8_STAGE(PG8_SA(1, 1), a1 + hstepA, voffA);
;             PG8_WAIT_V(8); PG8_WAIT_L(0); PG8_BAR; PG8_MMA(0, 0, At, B0); PG8_MMA(0, 1, At, B1); PG8_BAR; PG8_SCHED;
	ds_read_b128 v[154:157], v150
	ds_read_b128 v[158:161], v150 offset:1024
	ds_read_b128 v[170:173], v150 offset:2048
	ds_read_b128 v[174:177], v150 offset:3072
	ds_read_b128 v[178:181], v151
	ds_read_b128 v[182:185], v151 offset:1024
	ds_read_b128 v[186:189], v151 offset:2048
	ds_read_b128 v[190:193], v151 offset:3072
	s_add_u32 s20, s18, 0xffe9c080
	s_addc_u32 s21, s19, -1
	s_cmpk_eq_i32 s55, 0x54
	s_cselect_b32 s23, s5, s21
	s_cselect_b32 s22, s4, s20
	s_cselect_b32 s21, s17, s54
	s_cselect_b32 s20, s16, s53
	v_lshl_add_u64 v[162:163], s[18:19], 0, v[138:139]
	s_add_i32 m0, s37, 0xc000
	ds_read_b128 v[194:197], v152
	ds_read_b128 v[198:201], v152 offset:1024
	ds_read_b128 v[202:205], v152 offset:2048
	ds_read_b128 v[206:209], v152 offset:3072
	ds_read_b128 v[210:213], v152 offset:4096
	ds_read_b128 v[214:217], v152 offset:5120
	ds_read_b128 v[218:221], v152 offset:6144
	ds_read_b128 v[222:225], v152 offset:7168
	global_load_lds_dwordx4 v[162:163], off
	v_lshl_add_u64 v[162:163], s[18:19], 0, v[140:141]
	s_add_i32 m0, s37, 0xe000
	s_nop 0
	global_load_lds_dwordx4 v[162:163], off
	s_waitcnt vmcnt(8)
	s_waitcnt lgkmcnt(0)
	s_barrier
	s_setprio 1
	s_waitcnt lgkmcnt(0)
	v_mfma_f32_16x16x32_bf16 v[124:127], v[154:157], v[194:197], v[124:127]
	v_mfma_f32_16x16x32_bf16 v[124:127], v[158:161], v[198:201], v[124:127]
	v_mfma_f32_16x16x32_bf16 v[108:111], v[154:157], v[202:205], v[108:111]
	v_mfma_f32_16x16x32_bf16 v[108:111], v[158:161], v[206:209], v[108:111]
	v_mfma_f32_16x16x32_bf16 v[92:95], v[154:157], v[210:213], v[92:95]
	v_mfma_f32_16x16x32_bf16 v[92:95], v[158:161], v[214:217], v[92:95]
	v_mfma_f32_16x16x32_bf16 v[76:79], v[154:157], v[218:221], v[76:79]
	v_mfma_f32_16x16x32_bf16 v[76:79], v[158:161], v[222:225], v[76:79]
	v_mfma_f32_16x16x32_bf16 v[120:123], v[170:173], v[194:197], v[120:123]
	v_mfma_f32_16x16x32_bf16 v[120:123], v[174:177], v[198:201], v[120:123]
	v_mfma_f32_16x16x32_bf16 v[104:107], v[170:173], v[202:205], v[104:107]
	v_mfma_f32_16x16x32_bf16 v[104:107], v[174:177], v[206:209], v[104:107]
	v_mfma_f32_16x16x32_bf16 v[88:91], v[170:173], v[210:213], v[88:91]
	v_mfma_f32_16x16x32_bf16 v[88:91], v[174:177], v[214:217], v[88:91]
	v_mfma_f32_16x16x32_bf16 v[72:75], v[170:173], v[218:221], v[72:75]
	v_mfma_f32_16x16x32_bf16 v[72:75], v[174:177], v[222:225], v[72:75]
	s_setprio 0
	s_setprio 1
	v_mfma_f32_16x16x32_bf16 v[116:119], v[178:181], v[194:197], v[116:119]
	v_mfma_f32_16x16x32_bf16 v[116:119], v[182:185], v[198:201], v[116:119]
	v_mfma_f32_16x16x32_bf16 v[100:103], v[178:181], v[202:205], v[100:103]
	v_mfma_f32_16x16x32_bf16 v[100:103], v[182:185], v[206:209], v[100:103]
	v_mfma_f32_16x16x32_bf16 v[84:87], v[178:181], v[210:213], v[84:87]
	v_mfma_f32_16x16x32_bf16 v[84:87], v[182:185], v[214:217], v[84:87]
	v_mfma_f32_16x16x32_bf16 v[68:71], v[178:181], v[218:221], v[68:71]
	v_mfma_f32_16x16x32_bf16 v[68:71], v[182:185], v[222:225], v[68:71]
	v_mfma_f32_16x16x32_bf16 v[112:115], v[186:189], v[194:197], v[112:115]
	v_mfma_f32_16x16x32_bf16 v[112:115], v[190:193], v[198:201], v[112:115]
	v_mfma_f32_16x16x32_bf16 v[96:99], v[186:189], v[202:205], v[96:99]
	v_mfma_f32_16x16x32_bf16 v[96:99], v[190:193], v[206:209], v[96:99]
	v_mfma_f32_16x16x32_bf16 v[80:83], v[186:189], v[210:213], v[80:83]
	v_mfma_f32_16x16x32_bf16 v[80:83], v[190:193], v[214:217], v[80:83]
	v_mfma_f32_16x16x32_bf16 v[64:67], v[186:189], v[218:221], v[64:67]
	v_mfma_f32_16x16x32_bf16 v[64:67], v[190:193], v[222:225], v[64:67]
	s_setprio 0
	s_barrier
	s_branch .Lrot_595

; #define PG8_STAGE(bufoff, gbase, voff) do { _Pragma("unroll") for (int _i = 0; _i < 2; ++_i) \
;         __builtin_amdgcn_global_load_lds((const unsigned*)((const char*)(gbase) + (voff)[_i]), (LAS unsigned*)(lds + (bufoff) + ldsw + _i * 8192), 16, 0, 0); } while (0)
; #define PG8_LDA(dst, b, h) do { _Pragma("unroll") for (int m = 0; m < 4; ++m) _Pragma("unroll") for (int k = 0; k < 2; ++k) dst[m][k] = *(const LAS bf16x8*)(lds + PG8_SA(b, h) + aoff + m * 2048 + k * 1024); } while (0)
; #define PG8_LDB(dst, b, h) do { _Pragma("unroll") for (int n = 0; n < 2; ++n) _Pragma("unroll") for (int k = 0; k < 2; ++k) dst[n][k] = *(const LAS bf16x8*)(lds + PG8_SB(b, h) + boff + n * 2048 + k * 1024); } while (0)
; #define PG8_MMA(ai, bj, At, Bt) do { __builtin_amdgcn_s_setprio(1); _Pragma("unroll") for (int m = 0; m < 4; ++m) _Pragma("unroll") for (int n = 0; n < 2; ++n) _Pragma("unroll") for (int k = 0; k < 2; ++k) \
;         acc[ai][bj][m][n] = __builtin_amdgcn_mfma_f32_16x16x32_bf16(Bt[n][k], At[m][k], acc[ai][bj][m][n], 0, 0, 0); __builtin_amdgcn_s_setprio(0); } while (0)
; #define PG8_WAIT_V(n) asm volatile("s_waitcnt vmcnt(" #n ")" ::: "memory")
; #define PG8_WAIT_L(n) asm volatile("s_waitcnt lgkmcnt(" #n ")" ::: "memory")
; #define PG8_BAR __builtin_amdgcn_s_barrier()
; #define PG8_SCHED __builtin_amdgcn_sched_barrier(0)
; template <class EpiT>
; __device__ __forceinline__ void gemm_phase(LAS unsigned char* lds, const Gemm g, const StaticOrder& S, const EpiT& E) {
;     ...
;             PG8_LDB(B0, 0, 0); PG8_LDB(B1, 0, 1); PG8_SCHED; PG8_LDA(At, 0, 0); PG8_STAGE(PG8_SA(1, 1), a1 + hstepA, voffA);
;             PG8_WAIT_V(8); PG8_WAIT_L(0); PG8_BAR; PG8_MMA(0, 0, At, B0); PG8_MMA(0, 1, At, B1); PG8_BAR; PG8_SCHED;
;             PG8_LDA(At, 0, 1); PG8_STAGE(PG8_SB(0, 0), b2, voffB); PG8_STAGE(PG8_SB(0, 1), b2 + hstepB, voffB); PG8_STAGE(PG8_SA(0, 0), a2, voffA);
.LBB0_761:
	ds_read_b128 v[156:159], v160
	ds_read_b128 v[164:167], v160 offset:1024
	ds_read_b128 v[170:173], v160 offset:2048
	ds_read_b128 v[174:177], v160 offset:3072
	ds_read_b128 v[178:181], v161
	ds_read_b128 v[182:185], v161 offset:1024
	ds_read_b128 v[186:189], v161 offset:2048
	ds_read_b128 v[190:193], v161 offset:3072
	s_add_u32 s22, s20, 0xfff7c080
	s_addc_u32 s23, s21, -1
	s_cmp_eq_u32 s56, 28
	s_cselect_b32 s25, s5, s23
	s_cselect_b32 s24, s4, s22
	s_cselect_b32 s23, s19, s39
	s_cselect_b32 s22, s18, s8
	v_lshl_add_u64 v[226:227], s[20:21], 0, v[146:147]
	s_add_i32 m0, s40, 0xc000
	ds_read_b128 v[194:197], v162
	ds_read_b128 v[198:201], v162 offset:1024
	ds_read_b128 v[202:205], v162 offset:2048
	ds_read_b128 v[206:209], v162 offset:3072
	ds_read_b128 v[210:213], v162 offset:4096
	ds_read_b128 v[214:217], v162 offset:5120
	ds_read_b128 v[218:221], v162 offset:6144
	ds_read_b128 v[222:225], v162 offset:7168
	global_load_lds_dwordx4 v[226:227], off
	v_lshl_add_u64 v[226:227], s[20:21], 0, v[150:151]
	s_add_i32 m0, s40, 0xe000
	s_nop 0
	global_load_lds_dwordx4 v[226:227], off
	s_waitcnt vmcnt(8)
	s_waitcnt lgkmcnt(0)
	s_barrier
	s_setprio 1
	s_waitcnt lgkmcnt(0)
	v_mfma_f32_16x16x32_bf16 v[124:127], v[156:159], v[194:197], v[124:127]
	v_mfma_f32_16x16x32_bf16 v[124:127], v[164:167], v[198:201], v[124:127]
	v_mfma_f32_16x16x32_bf16 v[108:111], v[156:159], v[202:205], v[108:111]
	v_mfma_f32_16x16x32_bf16 v[108:111], v[164:167], v[206:209], v[108:111]
	v_mfma_f32_16x16x32_bf16 v[92:95], v[156:159], v[210:213], v[92:95]
	v_mfma_f32_16x16x32_bf16 v[92:95], v[164:167], v[214:217], v[92:95]
	v_mfma_f32_16x16x32_bf16 v[76:79], v[156:159], v[218:221], v[76:79]
	v_mfma_f32_16x16x32_bf16 v[76:79], v[164:167], v[222:225], v[76:79]
	v_mfma_f32_16x16x32_bf16 v[120:123], v[170:173], v[194:197], v[120:123]
	v_mfma_f32_16x16x32_bf16 v[120:123], v[174:177], v[198:201], v[120:123]
	v_mfma_f32_16x16x32_bf16 v[104:107], v[170:173], v[202:205], v[104:107]
	v_mfma_f32_16x16x32_bf16 v[104:107], v[174:177], v[206:209], v[104:107]
	v_mfma_f32_16x16x32_bf16 v[88:91], v[170:173], v[210:213], v[88:91]
	v_mfma_f32_16x16x32_bf16 v[88:91], v[174:177], v[214:217], v[88:91]
	v_mfma_f32_16x16x32_bf16 v[72:75], v[170:173], v[218:221], v[72:75]
	v_mfma_f32_16x16x32_bf16 v[72:75], v[174:177], v[222:225], v[72:75]
	s_setprio 0
	s_setprio 1
	v_mfma_f32_16x16x32_bf16 v[116:119], v[178:181], v[194:197], v[116:119]
	v_mfma_f32_16x16x32_bf16 v[116:119], v[182:185], v[198:201], v[116:119]
	v_mfma_f32_16x16x32_bf16 v[100:103], v[178:181], v[202:205], v[100:103]
	v_mfma_f32_16x16x32_bf16 v[100:103], v[182:185], v[206:209], v[100:103]
	v_mfma_f32_16x16x32_bf16 v[84:87], v[178:181], v[210:213], v[84:87]
	v_mfma_f32_16x16x32_bf16 v[84:87], v[182:185], v[214:217], v[84:87]
	v_mfma_f32_16x16x32_bf16 v[68:71], v[178:181], v[218:221], v[68:71]
	v_mfma_f32_16x16x32_bf16 v[68:71], v[182:185], v[222:225], v[68:71]
	v_mfma_f32_16x16x32_bf16 v[112:115], v[186:189], v[194:197], v[112:115]
	v_mfma_f32_16x16x32_bf16 v[112:115], v[190:193], v[198:201], v[112:115]
	v_mfma_f32_16x16x32_bf16 v[96:99], v[186:189], v[202:205], v[96:99]
	v_mfma_f32_16x16x32_bf16 v[96:99], v[190:193], v[206:209], v[96:99]
	v_mfma_f32_16x16x32_bf16 v[80:83], v[186:189], v[210:213], v[80:83]
	v_mfma_f32_16x16x32_bf16 v[80:83], v[190:193], v[214:217], v[80:83]
	v_mfma_f32_16x16x32_bf16 v[64:67], v[186:189], v[218:221], v[64:67]
	v_mfma_f32_16x16x32_bf16 v[64:67], v[190:193], v[222:225], v[64:67]
	s_setprio 0
	s_barrier
.Lrot_761:
	s_add_i32 s57, s49, s37
	v_lshl_add_u64 v[226:227], s[22:23], 0, v[130:131]
	s_mov_b32 m0, s57
	ds_read_b128 v[194:197], v162 offset:16384
	ds_read_b128 v[198:201], v162 offset:17408
	ds_read_b128 v[202:205], v162 offset:18432
	ds_read_b128 v[206:209], v162 offset:19456
	ds_read_b128 v[210:213], v162 offset:20480
	ds_read_b128 v[214:217], v162 offset:21504
	ds_read_b128 v[218:221], v162 offset:22528
	ds_read_b128 v[222:225], v162 offset:23552
	global_load_lds_dwordx4 v[226:227], off
	s_add_i32 m0, s57, 0x2000
	s_add_u32 s58, s22, 0x84000
	v_lshl_add_u64 v[228:229], s[22:23], 0, v[134:135]
	s_addc_u32 s59, s23, 0
	s_add_i32 s57, s50, s37
	global_load_lds_dwordx4 v[228:229], off
	v_lshl_add_u64 v[230:231], s[58:59], 0, v[130:131]
	s_mov_b32 m0, s57
	v_lshl_add_u64 v[232:233], s[24:25], 0, v[132:133]
	global_load_lds_dwordx4 v[230:231], off
	v_lshl_add_u64 v[230:231], s[58:59], 0, v[134:135]
	s_add_i32 m0, s57, 0x2000
	s_nop 0
	global_load_lds_dwordx4 v[230:231], off
	v_lshl_add_u64 v[230:231], s[24:25], 0, v[128:129]
	s_mov_b32 m0, s40
	s_nop 0
	global_load_lds_dwordx4 v[230:231], off
	s_mov_b32 m0, s41
	s_nop 0
	global_load_lds_dwordx4 v[232:233], off
	s_waitcnt vmcnt(8)
	s_waitcnt lgkmcnt(0)
	s_barrier
; #define PG8_STAGE(bufoff, gbase, voff) do { _Pragma("unroll") for (int _i = 0; _i < 2; ++_i) \
;         __builtin_amdgcn_global_load_lds((const unsigned*)((const char*)(gbase) + (voff)[_i]), (LAS unsigned*)(lds + (bufoff) + ldsw + _i * 8192), 16, 0, 0); } while (0)
; #define PG8_LDA(dst, b, h) do { _Pragma("unroll") for (int m = 0; m < 4; ++m) _Pragma("unroll") for (int k = 0; k < 2; ++k) dst[m][k] = *(const LAS bf16x8*)(lds + PG8_SA(b, h) + aoff + m * 2048 + k * 1024); } while (0)
; #define PG8_LDB(dst, b, h) do { _Pragma("unroll") for (int n = 0; n < 2; ++n) _Pragma("unroll") for (int k = 0; k < 2; ++k) dst[n][k] = *(const LAS bf16x8*)(lds + PG8_SB(b, h) + boff + n * 2048 + k * 1024); } while (0)
; #define PG8_MMA(ai, bj, At, Bt) do { __builtin_amdgcn_s_setprio(1); _Pragma("unroll") for (int m = 0; m < 4; ++m) _Pragma("unroll") for (int n = 0; n < 2; ++n) _Pragma("unroll") for (int k = 0; k < 2; ++k) \
;         acc[ai][bj][m][n] = __builtin_amdgcn_mfma_f32_16x16x32_bf16(Bt[n][k], At[m][k], acc[ai][bj][m][n], 0, 0, 0); __builtin_amdgcn_s_setprio(0); } while (0)
; #define PG8_WAIT_V(n) asm volatile("s_waitcnt vmcnt(" #n ")" ::: "memory")
; #define PG8_WAIT_L(n) asm volatile("s_waitcnt lgkmcnt(" #n ")" ::: "memory")
; #define PG8_BAR __builtin_amdgcn_s_barrier()
; #define PG8_SCHED __builtin_amdgcn_sched_barrier(0)
; template <class EpiT>
; __device__ __forceinline__ void gemm_phase(LAS unsigned char* lds, const Gemm g, const StaticOrder& S, const EpiT& E) {
;     ...
;             PG8_WAIT_V(8); PG8_WAIT_L(0); PG8_BAR; PG8_MMA(1, 0, At, B0); PG8_MMA(1, 1, At, B1); PG8_BAR; PG8_SCHED;
;             PG8_LDB(B0, 1, 0); PG8_LDB(B1, 1, 1); PG8_SCHED; PG8_LDA(At, 1, 0); PG8_STAGE(PG8_SA(0, 1), a2 + hstepA, voffA);
;             PG8_WAIT_V(8); PG8_WAIT_L(0); PG8_BAR; PG8_MMA(0, 0, At, B0); PG8_MMA(0, 1, At, B1); PG8_BAR; PG8_SCHED;
	s_setprio 1
	s_waitcnt lgkmcnt(0)
	v_mfma_f32_16x16x32_bf16 v[60:63], v[156:159], v[194:197], v[60:63]
	v_mfma_f32_16x16x32_bf16 v[60:63], v[164:167], v[198:201], v[60:63]
	v_mfma_f32_16x16x32_bf16 v[44:47], v[156:159], v[202:205], v[44:47]
	v_mfma_f32_16x16x32_bf16 v[44:47], v[164:167], v[206:209], v[44:47]
	v_mfma_f32_16x16x32_bf16 v[28:31], v[156:159], v[210:213], v[28:31]
	v_mfma_f32_16x16x32_bf16 v[28:31], v[164:167], v[214:217], v[28:31]
	v_mfma_f32_16x16x32_bf16 v[12:15], v[156:159], v[218:221], v[12:15]
	v_mfma_f32_16x16x32_bf16 v[12:15], v[164:167], v[222:225], v[12:15]
	v_mfma_f32_16x16x32_bf16 v[56:59], v[170:173], v[194:197], v[56:59]
	v_mfma_f32_16x16x32_bf16 v[56:59], v[174:177], v[198:201], v[56:59]
	v_mfma_f32_16x16x32_bf16 v[40:43], v[170:173], v[202:205], v[40:43]
	v_mfma_f32_16x16x32_bf16 v[40:43], v[174:177], v[206:209], v[40:43]
	v_mfma_f32_16x16x32_bf16 v[24:27], v[170:173], v[210:213], v[24:27]
	v_mfma_f32_16x16x32_bf16 v[24:27], v[174:177], v[214:217], v[24:27]
	v_mfma_f32_16x16x32_bf16 v[8:11], v[170:173], v[218:221], v[8:11]
	v_mfma_f32_16x16x32_bf16 v[8:11], v[174:177], v[222:225], v[8:11]
	s_setprio 0
	s_setprio 1
	v_mfma_f32_16x16x32_bf16 v[52:55], v[178:181], v[194:197], v[52:55]
	v_mfma_f32_16x16x32_bf16 v[52:55], v[182:185], v[198:201], v[52:55]
	v_mfma_f32_16x16x32_bf16 v[36:39], v[178:181], v[202:205], v[36:39]
	v_mfma_f32_16x16x32_bf16 v[36:39], v[182:185], v[206:209], v[36:39]
	v_mfma_f32_16x16x32_bf16 v[20:23], v[178:181], v[210:213], v[20:23]
	v_mfma_f32_16x16x32_bf16 v[20:23], v[182:185], v[214:217], v[20:23]
	v_mfma_f32_16x16x32_bf16 v[4:7], v[178:181], v[218:221], v[4:7]
	v_mfma_f32_16x16x32_bf16 v[4:7], v[182:185], v[222:225], v[4:7]
	v_mfma_f32_16x16x32_bf16 v[48:51], v[186:189], v[194:197], v[48:51]
	v_mfma_f32_16x16x32_bf16 v[48:51], v[190:193], v[198:201], v[48:51]
	v_mfma_f32_16x16x32_bf16 v[32:35], v[186:189], v[202:205], v[32:35]
	v_mfma_f32_16x16x32_bf16 v[32:35], v[190:193], v[206:209], v[32:35]
	v_mfma_f32_16x16x32_bf16 v[16:19], v[186:189], v[210:213], v[16:19]
	v_mfma_f32_16x16x32_bf16 v[16:19], v[190:193], v[214:217], v[16:19]
	v_mfma_f32_16x16x32_bf16 v[0:3], v[186:189], v[218:221], v[0:3]
	v_mfma_f32_16x16x32_bf16 v[0:3], v[190:193], v[222:225], v[0:3]
	s_setprio 0
	s_barrier
	s_add_i32 s57, 0, 0x18000
	v_add_u32_e32 v136, s57, v149
	s_add_i32 s58, 0, 0x1c000
	ds_read_b128 v[156:159], v136
	ds_read_b128 v[164:167], v136 offset:1024
	ds_read_b128 v[170:173], v136 offset:2048
	ds_read_b128 v[174:177], v136 offset:3072
	v_add_u32_e32 v136, s58, v149
	ds_read_b128 v[178:181], v136
	ds_read_b128 v[182:185], v136 offset:1024
	ds_read_b128 v[186:189], v136 offset:2048
	ds_read_b128 v[190:193], v136 offset:3072
	s_add_u32 s24, s24, 0x84000
	s_addc_u32 s25, s25, 0
	s_mov_b32 m0, s42
	v_lshl_add_u64 v[234:235], s[24:25], 0, v[128:129]
	ds_read_b128 v[194:197], v162 offset:32768
	ds_read_b128 v[198:201], v162 offset:33792
	ds_read_b128 v[202:205], v162 offset:34816
	ds_read_b128 v[206:209], v162 offset:35840
	ds_read_b128 v[210:213], v162 offset:36864
	ds_read_b128 v[214:217], v162 offset:37888
	ds_read_b128 v[218:221], v162 offset:38912
	ds_read_b128 v[222:225], v162 offset:39936
	global_load_lds_dwordx4 v[234:235], off
	v_lshl_add_u64 v[234:235], s[24:25], 0, v[132:133]
	s_mov_b32 m0, s43
	s_nop 0
	global_load_lds_dwordx4 v[234:235], off
	s_waitcnt vmcnt(8)
	s_waitcnt lgkmcnt(0)
	s_barrier
	s_setprio 1
	s_waitcnt lgkmcnt(0)
	v_mfma_f32_16x16x32_bf16 v[124:127], v[156:159], v[194:197], v[124:127]
	v_mfma_f32_16x16x32_bf16 v[124:127], v[164:167], v[198:201], v[124:127]
	v_mfma_f32_16x16x32_bf16 v[108:111], v[156:159], v[202:205], v[108:111]
	v_mfma_f32_16x16x32_bf16 v[108:111], v[164:167], v[206:209], v[108:111]
	v_mfma_f32_16x16x32_bf16 v[92:95], v[156:159], v[210:213], v[92:95]
	v_mfma_f32_16x16x32_bf16 v[92:95], v[164:167], v[214:217], v[92:95]
	v_mfma_f32_16x16x32_bf16 v[76:79], v[156:159], v[218:221], v[76:79]
	v_mfma_f32_16x16x32_bf16 v[76:79], v[164:167], v[222:225], v[76:79]
	v_mfma_f32_16x16x32_bf16 v[120:123], v[170:173], v[194:197], v[120:123]
	v_mfma_f32_16x16x32_bf16 v[120:123], v[174:177], v[198:201], v[120:123]
	v_mfma_f32_16x16x32_bf16 v[104:107], v[170:173], v[202:205], v[104:107]
	v_mfma_f32_16x16x32_bf16 v[104:107], v[174:177], v[206:209], v[104:107]
	v_mfma_f32_16x16x32_bf16 v[88:91], v[170:173], v[210:213], v[88:91]
	v_mfma_f32_16x16x32_bf16 v[88:91], v[174:177], v[214:217], v[88:91]
	v_mfma_f32_16x16x32_bf16 v[72:75], v[170:173], v[218:221], v[72:75]
	v_mfma_f32_16x16x32_bf16 v[72:75], v[174:177], v[222:225], v[72:75]
	s_setprio 0
	s_setprio 1
	v_mfma_f32_16x16x32_bf16 v[116:119], v[178:181], v[194:197], v[116:119]
	v_mfma_f32_16x16x32_bf16 v[116:119], v[182:185], v[198:201], v[116:119]
	v_mfma_f32_16x16x32_bf16 v[100:103], v[178:181], v[202:205], v[100:103]
	v_mfma_f32_16x16x32_bf16 v[100:103], v[182:185], v[206:209], v[100:103]
	v_mfma_f32_16x16x32_bf16 v[84:87], v[178:181], v[210:213], v[84:87]
	v_mfma_f32_16x16x32_bf16 v[84:87], v[182:185], v[214:217], v[84:87]
	v_mfma_f32_16x16x32_bf16 v[68:71], v[178:181], v[218:221], v[68:71]
	v_mfma_f32_16x16x32_bf16 v[68:71], v[182:185], v[222:225], v[68:71]
	v_mfma_f32_16x16x32_bf16 v[112:115], v[186:189], v[194:197], v[112:115]
	v_mfma_f32_16x16x32_bf16 v[112:115], v[190:193], v[198:201], v[112:115]
	v_mfma_f32_16x16x32_bf16 v[96:99], v[186:189], v[202:205], v[96:99]
	v_mfma_f32_16x16x32_bf16 v[96:99], v[190:193], v[206:209], v[96:99]
	v_mfma_f32_16x16x32_bf16 v[80:83], v[186:189], v[210:213], v[80:83]
	v_mfma_f32_16x16x32_bf16 v[80:83], v[190:193], v[214:217], v[80:83]
	v_mfma_f32_16x16x32_bf16 v[64:67], v[186:189], v[218:221], v[64:67]
	v_mfma_f32_16x16x32_bf16 v[64:67], v[190:193], v[222:225], v[64:67]
	s_setprio 0
	s_barrier
; #define PG8_STAGE(bufoff, gbase, voff) do { _Pragma("unroll") for (int _i = 0; _i < 2; ++_i) \
;         __builtin_amdgcn_global_load_lds((const unsigned*)((const char*)(gbase) + (voff)[_i]), (LAS unsigned*)(lds + (bufoff) + ldsw + _i * 8192), 16, 0, 0); } while (0)
; #define PG8_LDA(dst, b, h) do { _Pragma("unroll") for (int m = 0; m < 4; ++m) _Pragma("unroll") for (int k = 0; k < 2; ++k) dst[m][k] = *(const LAS bf16x8*)(lds + PG8_SA(b, h) + aoff + m * 2048 + k * 1024); } while (0)
; #define PG8_MMA(ai, bj, At, Bt) do { __builtin_amdgcn_s_setprio(1); _Pragma("unroll") for (int m = 0; m < 4; ++m) _Pragma("unroll") for (int n = 0; n < 2; ++n) _Pragma("unroll") for (int k = 0; k < 2; ++k) \
;         acc[ai][bj][m][n] = __builtin_amdgcn_mfma_f32_16x16x32_bf16(Bt[n][k], At[m][k], acc[ai][bj][m][n], 0, 0, 0); __builtin_amdgcn_s_setprio(0); } while (0)
; #define PG8_WAIT_V(n) asm volatile("s_waitcnt vmcnt(" #n ")" ::: "memory")
; #define PG8_WAIT_L(n) asm volatile("s_waitcnt lgkmcnt(" #n ")" ::: "memory")
; #define PG8_BAR __builtin_amdgcn_s_barrier()
; #define PG8_SCHED __builtin_amdgcn_sched_barrier(0)
; template <class EpiT>
; __device__ __forceinline__ void gemm_phase(LAS unsigned char* lds, const Gemm g, const StaticOrder& S, const EpiT& E) {
;     ...
;         for (int t = 0; t < nt; t += 2) {
;     ...
;             PG8_LDA(At, 1, 1); PG8_STAGE(PG8_SB(1, 0), b3, voffB); PG8_STAGE(PG8_SB(1, 1), b3 + hstepB, voffB); PG8_STAGE(PG8_SA(1, 0), a3, voffA);
;             PG8_WAIT_V(8); PG8_WAIT_L(0); PG8_BAR; PG8_MMA(1, 0, At, B0); PG8_MMA(1, 1, At, B1); PG8_BAR; PG8_SCHED;
	s_add_i32 s24, s57, s37
	v_lshl_add_u64 v[226:227], v[226:227], 0, s[14:15]
	s_mov_b32 m0, s24
	ds_read_b128 v[194:197], v162 offset:49152
	ds_read_b128 v[198:201], v162 offset:50176
	ds_read_b128 v[202:205], v162 offset:51200
	ds_read_b128 v[206:209], v162 offset:52224
	ds_read_b128 v[210:213], v162 offset:53248
	ds_read_b128 v[214:217], v162 offset:54272
	ds_read_b128 v[218:221], v162 offset:55296
	ds_read_b128 v[222:225], v162 offset:56320
	global_load_lds_dwordx4 v[226:227], off
	s_add_i32 m0, s24, 0x2000
	s_add_u32 s22, s22, 0x84080
	v_lshl_add_u64 v[226:227], v[228:229], 0, s[14:15]
	s_addc_u32 s23, s23, 0
	s_add_i32 s24, s58, s37
	global_load_lds_dwordx4 v[226:227], off
	v_lshl_add_u64 v[226:227], s[22:23], 0, v[130:131]
	s_mov_b32 m0, s24
	s_nop 0
	global_load_lds_dwordx4 v[226:227], off
	v_lshl_add_u64 v[226:227], s[22:23], 0, v[134:135]
	s_add_i32 m0, s24, 0x2000
	s_nop 0
	global_load_lds_dwordx4 v[226:227], off
	v_lshl_add_u64 v[226:227], v[230:231], 0, s[14:15]
	s_mov_b32 m0, s44
	s_nop 0
	global_load_lds_dwordx4 v[226:227], off
	v_lshl_add_u64 v[226:227], v[232:233], 0, s[14:15]
	s_mov_b32 m0, s45
	s_nop 0
	global_load_lds_dwordx4 v[226:227], off
	s_waitcnt vmcnt(8)
	s_waitcnt lgkmcnt(0)
	s_barrier
	s_setprio 1
	s_waitcnt lgkmcnt(0)
	v_mfma_f32_16x16x32_bf16 v[60:63], v[156:159], v[194:197], v[60:63]
	v_mfma_f32_16x16x32_bf16 v[60:63], v[164:167], v[198:201], v[60:63]
	v_mfma_f32_16x16x32_bf16 v[44:47], v[156:159], v[202:205], v[44:47]
	v_mfma_f32_16x16x32_bf16 v[44:47], v[164:167], v[206:209], v[44:47]
	v_mfma_f32_16x16x32_bf16 v[28:31], v[156:159], v[210:213], v[28:31]
	v_mfma_f32_16x16x32_bf16 v[28:31], v[164:167], v[214:217], v[28:31]
	v_mfma_f32_16x16x32_bf16 v[12:15], v[156:159], v[218:221], v[12:15]
	v_mfma_f32_16x16x32_bf16 v[12:15], v[164:167], v[222:225], v[12:15]
	v_mfma_f32_16x16x32_bf16 v[56:59], v[170:173], v[194:197], v[56:59]
	v_mfma_f32_16x16x32_bf16 v[56:59], v[174:177], v[198:201], v[56:59]
	v_mfma_f32_16x16x32_bf16 v[40:43], v[170:173], v[202:205], v[40:43]
	v_mfma_f32_16x16x32_bf16 v[40:43], v[174:177], v[206:209], v[40:43]
	v_mfma_f32_16x16x32_bf16 v[24:27], v[170:173], v[210:213], v[24:27]
	v_mfma_f32_16x16x32_bf16 v[24:27], v[174:177], v[214:217], v[24:27]
	v_mfma_f32_16x16x32_bf16 v[8:11], v[170:173], v[218:221], v[8:11]
	v_mfma_f32_16x16x32_bf16 v[8:11], v[174:177], v[222:225], v[8:11]
	s_setprio 0
	s_setprio 1
	v_mfma_f32_16x16x32_bf16 v[52:55], v[178:181], v[194:197], v[52:55]
	v_mfma_f32_16x16x32_bf16 v[52:55], v[182:185], v[198:201], v[52:55]
	v_mfma_f32_16x16x32_bf16 v[36:39], v[178:181], v[202:205], v[36:39]
	v_mfma_f32_16x16x32_bf16 v[36:39], v[182:185], v[206:209], v[36:39]
	v_mfma_f32_16x16x32_bf16 v[20:23], v[178:181], v[210:213], v[20:23]
	v_mfma_f32_16x16x32_bf16 v[20:23], v[182:185], v[214:217], v[20:23]
	v_mfma_f32_16x16x32_bf16 v[4:7], v[178:181], v[218:221], v[4:7]
	v_mfma_f32_16x16x32_bf16 v[4:7], v[182:185], v[222:225], v[4:7]
	v_mfma_f32_16x16x32_bf16 v[48:51], v[186:189], v[194:197], v[48:51]
	v_mfma_f32_16x16x32_bf16 v[48:51], v[190:193], v[198:201], v[48:51]
	v_mfma_f32_16x16x32_bf16 v[32:35], v[186:189], v[202:205], v[32:35]
	v_mfma_f32_16x16x32_bf16 v[32:35], v[190:193], v[206:209], v[32:35]
	v_mfma_f32_16x16x32_bf16 v[16:19], v[186:189], v[210:213], v[16:19]
	v_mfma_f32_16x16x32_bf16 v[16:19], v[190:193], v[214:217], v[16:19]
	v_mfma_f32_16x16x32_bf16 v[0:3], v[186:189], v[218:221], v[0:3]
	v_mfma_f32_16x16x32_bf16 v[0:3], v[190:193], v[222:225], v[0:3]
	s_setprio 0
	s_barrier
	s_add_i32 s56, s56, 2
	s_add_u32 s20, s20, 0x100
	s_addc_u32 s21, s21, 0
	s_add_u32 s8, s8, 0x100
	s_addc_u32 s39, s39, 0
	s_cmp_gt_u32 s56, 29
	s_cbranch_scc1 .Lrot_done_761
; #define PG8_STAGE(bufoff, gbase, voff) do { _Pragma("unroll") for (int _i = 0; _i < 2; ++_i) \
;         __builtin_amdgcn_global_load_lds((const unsigned*)((const char*)(gbase) + (voff)[_i]), (LAS unsigned*)(lds + (bufoff) + ldsw + _i * 8192), 16, 0, 0); } while (0)
; #define PG8_LDA(dst, b, h) do { _Pragma("unroll") for (int m = 0; m < 4; ++m) _Pragma("unroll") for (int k = 0; k < 2; ++k) dst[m][k] = *(const LAS bf16x8*)(lds + PG8_SA(b, h) + aoff + m * 2048 + k * 1024); } while (0)
; #define PG8_LDB(dst, b, h) do { _Pragma("unroll") for (int n = 0; n < 2; ++n) _Pragma("unroll") for (int k = 0; k < 2; ++k) dst[n][k] = *(const LAS bf16x8*)(lds + PG8_SB(b, h) + boff + n * 2048 + k * 1024); } while (0)
; #define PG8_MMA(ai, bj, At, Bt) do { __builtin_amdgcn_s_setprio(1); _Pragma("unroll") for (int m = 0; m < 4; ++m) _Pragma("unroll") for (int n = 0; n < 2; ++n) _Pragma("unroll") for (int k = 0; k < 2; ++k) \
;         acc[ai][bj][m][n] = __builtin_amdgcn_mfma_f32_16x16x32_bf16(Bt[n][k], At[m][k], acc[ai][bj][m][n], 0, 0, 0); __builtin_amdgcn_s_setprio(0); } while (0)
; #define PG8_WAIT_V(n) asm volatile("s_waitcnt vmcnt(" #n ")" ::: "memory")
; #define PG8_WAIT_L(n) asm volatile("s_waitcnt lgkmcnt(" #n ")" ::: "memory")
; #define PG8_BAR __builtin_amdgcn_s_barrier()
; #define PG8_SCHED __builtin_amdgcn_sched_barrier(0)
; template <class EpiT>
; __device__ __forceinline__ void gemm_phase(LAS unsigned char* lds, const Gemm g, const StaticOrder& S, const EpiT& E) {
;     ...
;             PG8_LDB(B0, 0, 0); PG8_LDB(B1, 0, 1); PG8_SCHED; PG8_LDA(At, 0, 0); PG8_STAGE(PG8_SA(1, 1), a1 + hstepA, voffA);
;             PG8_WAIT_V(8); PG8_WAIT_L(0); PG8_BAR; PG8_MMA(0, 0, At, B0); PG8_MMA(0, 1, At, B1); PG8_BAR; PG8_SCHED;
	ds_read_b128 v[156:159], v160
	ds_read_b128 v[164:167], v160 offset:1024
	ds_read_b128 v[170:173], v160 offset:2048
	ds_read_b128 v[174:177], v160 offset:3072
	ds_read_b128 v[178:181], v161
	ds_read_b128 v[182:185], v161 offset:1024
	ds_read_b128 v[186:189], v161 offset:2048
	ds_read_b128 v[190:193], v161 offset:3072
	s_add_u32 s22, s20, 0xfff7c080
	s_addc_u32 s23, s21, -1
	s_cmp_eq_u32 s56, 28
	s_cselect_b32 s25, s5, s23
	s_cselect_b32 s24, s4, s22
	s_cselect_b32 s23, s19, s39
	s_cselect_b32 s22, s18, s8
	v_lshl_add_u64 v[226:227], s[20:21], 0, v[146:147]
	s_add_i32 m0, s40, 0xc000
	ds_read_b128 v[194:197], v162
	ds_read_b128 v[198:201], v162 offset:1024
	ds_read_b128 v[202:205], v162 offset:2048
	ds_read_b128 v[206:209], v162 offset:3072
	ds_read_b128 v[210:213], v162 offset:4096
	ds_read_b128 v[214:217], v162 offset:5120
	ds_read_b128 v[218:221], v162 offset:6144
	ds_read_b128 v[222:225], v162 offset:7168
	global_load_lds_dwordx4 v[226:227], off
	v_lshl_add_u64 v[226:227], s[20:21], 0, v[150:151]
	s_add_i32 m0, s40, 0xe000
	s_nop 0
	global_load_lds_dwordx4 v[226:227], off
	s_waitcnt vmcnt(8)
	s_waitcnt lgkmcnt(0)
	s_barrier
	s_setprio 1
	s_waitcnt lgkmcnt(0)
	v_mfma_f32_16x16x32_bf16 v[124:127], v[156:159], v[194:197], v[124:127]
	v_mfma_f32_16x16x32_bf16 v[124:127], v[164:167], v[198:201], v[124:127]
	v_mfma_f32_16x16x32_bf16 v[108:111], v[156:159], v[202:205], v[108:111]
	v_mfma_f32_16x16x32_bf16 v[108:111], v[164:167], v[206:209], v[108:111]
	v_mfma_f32_16x16x32_bf16 v[92:95], v[156:159], v[210:213], v[92:95]
	v_mfma_f32_16x16x32_bf16 v[92:95], v[164:167], v[214:217], v[92:95]
	v_mfma_f32_16x16x32_bf16 v[76:79], v[156:159], v[218:221], v[76:79]
	v_mfma_f32_16x16x32_bf16 v[76:79], v[164:167], v[222:225], v[76:79]
	v_mfma_f32_16x16x32_bf16 v[120:123], v[170:173], v[194:197], v[120:123]
	v_mfma_f32_16x16x32_bf16 v[120:123], v[174:177], v[198:201], v[120:123]
	v_mfma_f32_16x16x32_bf16 v[104:107], v[170:173], v[202:205], v[104:107]
	v_mfma_f32_16x16x32_bf16 v[104:107], v[174:177], v[206:209], v[104:107]
	v_mfma_f32_16x16x32_bf16 v[88:91], v[170:173], v[210:213], v[88:91]
	v_mfma_f32_16x16x32_bf16 v[88:91], v[174:177], v[214:217], v[88:91]
	v_mfma_f32_16x16x32_bf16 v[72:75], v[170:173], v[218:221], v[72:75]
	v_mfma_f32_16x16x32_bf16 v[72:75], v[174:177], v[222:225], v[72:75]
	s_setprio 0
	s_setprio 1
	v_mfma_f32_16x16x32_bf16 v[116:119], v[178:181], v[194:197], v[116:119]
	v_mfma_f32_16x16x32_bf16 v[116:119], v[182:185], v[198:201], v[116:119]
	v_mfma_f32_16x16x32_bf16 v[100:103], v[178:181], v[202:205], v[100:103]
	v_mfma_f32_16x16x32_bf16 v[100:103], v[182:185], v[206:209], v[100:103]
	v_mfma_f32_16x16x32_bf16 v[84:87], v[178:181], v[210:213], v[84:87]
	v_mfma_f32_16x16x32_bf16 v[84:87], v[182:185], v[214:217], v[84:87]
	v_mfma_f32_16x16x32_bf16 v[68:71], v[178:181], v[218:221], v[68:71]
	v_mfma_f32_16x16x32_bf16 v[68:71], v[182:185], v[222:225], v[68:71]
	v_mfma_f32_16x16x32_bf16 v[112:115], v[186:189], v[194:197], v[112:115]
	v_mfma_f32_16x16x32_bf16 v[112:115], v[190:193], v[198:201], v[112:115]
	v_mfma_f32_16x16x32_bf16 v[96:99], v[186:189], v[202:205], v[96:99]
	v_mfma_f32_16x16x32_bf16 v[96:99], v[190:193], v[206:209], v[96:99]
	v_mfma_f32_16x16x32_bf16 v[80:83], v[186:189], v[210:213], v[80:83]
	v_mfma_f32_16x16x32_bf16 v[80:83], v[190:193], v[214:217], v[80:83]
	v_mfma_f32_16x16x32_bf16 v[64:67], v[186:189], v[218:221], v[64:67]
	v_mfma_f32_16x16x32_bf16 v[64:67], v[190:193], v[222:225], v[64:67]
	s_setprio 0
	s_barrier
	s_branch .Lrot_761

; #define PG8_STAGE(bufoff, gbase, voff) do { _Pragma("unroll") for (int _i = 0; _i < 2; ++_i) \
;         __builtin_amdgcn_global_load_lds((const unsigned*)((const char*)(gbase) + (voff)[_i]), (LAS unsigned*)(lds + (bufoff) + ldsw + _i * 8192), 16, 0, 0); } while (0)
; #define PG8_LDA(dst, b, h) do { _Pragma("unroll") for (int m = 0; m < 4; ++m) _Pragma("unroll") for (int k = 0; k < 2; ++k) dst[m][k] = *(const LAS bf16x8*)(lds + PG8_SA(b, h) + aoff + m * 2048 + k * 1024); } while (0)
; #define PG8_LDB(dst, b, h) do { _Pragma("unroll") for (int n = 0; n < 2; ++n) _Pragma("unroll") for (int k = 0; k < 2; ++k) dst[n][k] = *(const LAS bf16x8*)(lds + PG8_SB(b, h) + boff + n * 2048 + k * 1024); } while (0)
; #define PG8_MMA(ai, bj, At, Bt) do { __builtin_amdgcn_s_setprio(1); _Pragma("unroll") for (int m = 0; m < 4; ++m) _Pragma("unroll") for (int n = 0; n < 2; ++n) _Pragma("unroll") for (int k = 0; k < 2; ++k) \
;         acc[ai][bj][m][n] = __builtin_amdgcn_mfma_f32_16x16x32_bf16(Bt[n][k], At[m][k], acc[ai][bj][m][n], 0, 0, 0); __builtin_amdgcn_s_setprio(0); } while (0)
; #define PG8_WAIT_V(n) asm volatile("s_waitcnt vmcnt(" #n ")" ::: "memory")
; #define PG8_WAIT_L(n) asm volatile("s_waitcnt lgkmcnt(" #n ")" ::: "memory")
; #define PG8_BAR __builtin_amdgcn_s_barrier()
; #define PG8_SCHED __builtin_amdgcn_sched_barrier(0)
; template <class EpiT>
; __device__ __forceinline__ void gemm_phase(LAS unsigned char* lds, const Gemm g, const StaticOrder& S, const EpiT& E) {
;     ...
;             PG8_LDB(B0, 0, 0); PG8_LDB(B1, 0, 1); PG8_SCHED; PG8_LDA(At, 0, 0); PG8_STAGE(PG8_SA(1, 1), a1 + hstepA, voffA);
;             PG8_WAIT_V(8); PG8_WAIT_L(0); PG8_BAR; PG8_MMA(0, 0, At, B0); PG8_MMA(0, 1, At, B1); PG8_BAR; PG8_SCHED;
;             PG8_LDA(At, 0, 1); PG8_STAGE(PG8_SB(0, 0), b2, voffB); PG8_STAGE(PG8_SB(0, 1), b2 + hstepB, voffB); PG8_STAGE(PG8_SA(0, 0), a2, voffA);
.LBB0_1032:
	ds_read_b128 v[154:157], v150
	ds_read_b128 v[158:161], v150 offset:1024
	ds_read_b128 v[162:165], v150 offset:2048
	ds_read_b128 v[170:173], v150 offset:3072
	ds_read_b128 v[174:177], v151
	ds_read_b128 v[178:181], v151 offset:1024
	ds_read_b128 v[182:185], v151 offset:2048
	ds_read_b128 v[186:189], v151 offset:3072
	s_add_u32 s20, s18, 0xfff7c080
	s_addc_u32 s21, s19, -1
	s_cmp_eq_u32 s55, 28
	s_cselect_b32 s23, s5, s21
	s_cselect_b32 s22, s4, s20
	s_cselect_b32 s21, s17, s54
	s_cselect_b32 s20, s16, s53
	v_lshl_add_u64 v[166:167], s[18:19], 0, v[138:139]
	s_add_i32 m0, s37, 0xc000
	ds_read_b128 v[190:193], v152
	ds_read_b128 v[194:197], v152 offset:1024
	ds_read_b128 v[198:201], v152 offset:2048
	ds_read_b128 v[202:205], v152 offset:3072
	ds_read_b128 v[206:209], v152 offset:4096
	ds_read_b128 v[210:213], v152 offset:5120
	ds_read_b128 v[214:217], v152 offset:6144
	ds_read_b128 v[218:221], v152 offset:7168
	global_load_lds_dwordx4 v[166:167], off
	v_lshl_add_u64 v[166:167], s[18:19], 0, v[140:141]
	s_add_i32 m0, s37, 0xe000
	s_nop 0
	global_load_lds_dwordx4 v[166:167], off
	s_waitcnt vmcnt(8)
	s_waitcnt lgkmcnt(0)
	s_barrier
	s_setprio 1
	s_waitcnt lgkmcnt(0)
	v_mfma_f32_16x16x32_bf16 v[124:127], v[154:157], v[190:193], v[124:127]
	v_mfma_f32_16x16x32_bf16 v[124:127], v[158:161], v[194:197], v[124:127]
	v_mfma_f32_16x16x32_bf16 v[108:111], v[154:157], v[198:201], v[108:111]
	v_mfma_f32_16x16x32_bf16 v[108:111], v[158:161], v[202:205], v[108:111]
	v_mfma_f32_16x16x32_bf16 v[92:95], v[154:157], v[206:209], v[92:95]
	v_mfma_f32_16x16x32_bf16 v[92:95], v[158:161], v[210:213], v[92:95]
	v_mfma_f32_16x16x32_bf16 v[76:79], v[154:157], v[214:217], v[76:79]
	v_mfma_f32_16x16x32_bf16 v[76:79], v[158:161], v[218:221], v[76:79]
	v_mfma_f32_16x16x32_bf16 v[120:123], v[162:165], v[190:193], v[120:123]
	v_mfma_f32_16x16x32_bf16 v[120:123], v[170:173], v[194:197], v[120:123]
	v_mfma_f32_16x16x32_bf16 v[104:107], v[162:165], v[198:201], v[104:107]
	v_mfma_f32_16x16x32_bf16 v[104:107], v[170:173], v[202:205], v[104:107]
	v_mfma_f32_16x16x32_bf16 v[88:91], v[162:165], v[206:209], v[88:91]
	v_mfma_f32_16x16x32_bf16 v[88:91], v[170:173], v[210:213], v[88:91]
	v_mfma_f32_16x16x32_bf16 v[72:75], v[162:165], v[214:217], v[72:75]
	v_mfma_f32_16x16x32_bf16 v[72:75], v[170:173], v[218:221], v[72:75]
	s_setprio 0
	s_setprio 1
	v_mfma_f32_16x16x32_bf16 v[116:119], v[174:177], v[190:193], v[116:119]
	v_mfma_f32_16x16x32_bf16 v[116:119], v[178:181], v[194:197], v[116:119]
	v_mfma_f32_16x16x32_bf16 v[100:103], v[174:177], v[198:201], v[100:103]
	v_mfma_f32_16x16x32_bf16 v[100:103], v[178:181], v[202:205], v[100:103]
	v_mfma_f32_16x16x32_bf16 v[84:87], v[174:177], v[206:209], v[84:87]
	v_mfma_f32_16x16x32_bf16 v[84:87], v[178:181], v[210:213], v[84:87]
	v_mfma_f32_16x16x32_bf16 v[68:71], v[174:177], v[214:217], v[68:71]
	v_mfma_f32_16x16x32_bf16 v[68:71], v[178:181], v[218:221], v[68:71]
	v_mfma_f32_16x16x32_bf16 v[112:115], v[182:185], v[190:193], v[112:115]
	v_mfma_f32_16x16x32_bf16 v[112:115], v[186:189], v[194:197], v[112:115]
	v_mfma_f32_16x16x32_bf16 v[96:99], v[182:185], v[198:201], v[96:99]
	v_mfma_f32_16x16x32_bf16 v[96:99], v[186:189], v[202:205], v[96:99]
	v_mfma_f32_16x16x32_bf16 v[80:83], v[182:185], v[206:209], v[80:83]
	v_mfma_f32_16x16x32_bf16 v[80:83], v[186:189], v[210:213], v[80:83]
	v_mfma_f32_16x16x32_bf16 v[64:67], v[182:185], v[214:217], v[64:67]
	v_mfma_f32_16x16x32_bf16 v[64:67], v[186:189], v[218:221], v[64:67]
	s_setprio 0
	s_barrier
.Lrot_1032:
	s_add_i32 s56, s46, s36
	v_lshl_add_u64 v[166:167], s[20:21], 0, v[130:131]
	s_mov_b32 m0, s56
	ds_read_b128 v[190:193], v152 offset:16384
	ds_read_b128 v[194:197], v152 offset:17408
	ds_read_b128 v[198:201], v152 offset:18432
	ds_read_b128 v[202:205], v152 offset:19456
	ds_read_b128 v[206:209], v152 offset:20480
	ds_read_b128 v[210:213], v152 offset:21504
	ds_read_b128 v[214:217], v152 offset:22528
	ds_read_b128 v[218:221], v152 offset:23552
	global_load_lds_dwordx4 v[166:167], off
	s_add_i32 m0, s56, 0x2000
	s_add_u32 s56, s20, 0x84000
	v_lshl_add_u64 v[222:223], s[20:21], 0, v[134:135]
	s_addc_u32 s57, s21, 0
	s_add_i32 s58, s47, s36
	global_load_lds_dwordx4 v[222:223], off
	v_lshl_add_u64 v[224:225], s[56:57], 0, v[130:131]
	s_mov_b32 m0, s58
	v_lshl_add_u64 v[226:227], s[22:23], 0, v[132:133]
	global_load_lds_dwordx4 v[224:225], off
	v_lshl_add_u64 v[224:225], s[56:57], 0, v[134:135]
	s_add_i32 m0, s58, 0x2000
	s_nop 0
	global_load_lds_dwordx4 v[224:225], off
	v_lshl_add_u64 v[224:225], s[22:23], 0, v[128:129]
	s_mov_b32 m0, s37
	s_nop 0
	global_load_lds_dwordx4 v[224:225], off
	s_mov_b32 m0, s38
	s_nop 0
	global_load_lds_dwordx4 v[226:227], off
	s_waitcnt vmcnt(8)
	s_waitcnt lgkmcnt(0)
	s_barrier
; #define PG8_STAGE(bufoff, gbase, voff) do { _Pragma("unroll") for (int _i = 0; _i < 2; ++_i) \
;         __builtin_amdgcn_global_load_lds((const unsigned*)((const char*)(gbase) + (voff)[_i]), (LAS unsigned*)(lds + (bufoff) + ldsw + _i * 8192), 16, 0, 0); } while (0)
; #define PG8_LDA(dst, b, h) do { _Pragma("unroll") for (int m = 0; m < 4; ++m) _Pragma("unroll") for (int k = 0; k < 2; ++k) dst[m][k] = *(const LAS bf16x8*)(lds + PG8_SA(b, h) + aoff + m * 2048 + k * 1024); } while (0)
; #define PG8_LDB(dst, b, h) do { _Pragma("unroll") for (int n = 0; n < 2; ++n) _Pragma("unroll") for (int k = 0; k < 2; ++k) dst[n][k] = *(const LAS bf16x8*)(lds + PG8_SB(b, h) + boff + n * 2048 + k * 1024); } while (0)
; #define PG8_MMA(ai, bj, At, Bt) do { __builtin_amdgcn_s_setprio(1); _Pragma("unroll") for (int m = 0; m < 4; ++m) _Pragma("unroll") for (int n = 0; n < 2; ++n) _Pragma("unroll") for (int k = 0; k < 2; ++k) \
;         acc[ai][bj][m][n] = __builtin_amdgcn_mfma_f32_16x16x32_bf16(Bt[n][k], At[m][k], acc[ai][bj][m][n], 0, 0, 0); __builtin_amdgcn_s_setprio(0); } while (0)
; #define PG8_WAIT_V(n) asm volatile("s_waitcnt vmcnt(" #n ")" ::: "memory")
; #define PG8_WAIT_L(n) asm volatile("s_waitcnt lgkmcnt(" #n ")" ::: "memory")
; #define PG8_BAR __builtin_amdgcn_s_barrier()
; #define PG8_SCHED __builtin_amdgcn_sched_barrier(0)
; template <class EpiT>
; __device__ __forceinline__ void gemm_phase(LAS unsigned char* lds, const Gemm g, const StaticOrder& S, const EpiT& E) {
;     ...
;             PG8_WAIT_V(8); PG8_WAIT_L(0); PG8_BAR; PG8_MMA(1, 0, At, B0); PG8_MMA(1, 1, At, B1); PG8_BAR; PG8_SCHED;
;             PG8_LDB(B0, 1, 0); PG8_LDB(B1, 1, 1); PG8_SCHED; PG8_LDA(At, 1, 0); PG8_STAGE(PG8_SA(0, 1), a2 + hstepA, voffA);
;             PG8_WAIT_V(8); PG8_WAIT_L(0); PG8_BAR; PG8_MMA(0, 0, At, B0); PG8_MMA(0, 1, At, B1); PG8_BAR; PG8_SCHED;
	s_setprio 1
	s_waitcnt lgkmcnt(0)
	v_mfma_f32_16x16x32_bf16 v[60:63], v[154:157], v[190:193], v[60:63]
	v_mfma_f32_16x16x32_bf16 v[60:63], v[158:161], v[194:197], v[60:63]
	v_mfma_f32_16x16x32_bf16 v[44:47], v[154:157], v[198:201], v[44:47]
	v_mfma_f32_16x16x32_bf16 v[44:47], v[158:161], v[202:205], v[44:47]
	v_mfma_f32_16x16x32_bf16 v[28:31], v[154:157], v[206:209], v[28:31]
	v_mfma_f32_16x16x32_bf16 v[28:31], v[158:161], v[210:213], v[28:31]
	v_mfma_f32_16x16x32_bf16 v[12:15], v[154:157], v[214:217], v[12:15]
	v_mfma_f32_16x16x32_bf16 v[12:15], v[158:161], v[218:221], v[12:15]
	v_mfma_f32_16x16x32_bf16 v[56:59], v[162:165], v[190:193], v[56:59]
	v_mfma_f32_16x16x32_bf16 v[56:59], v[170:173], v[194:197], v[56:59]
	v_mfma_f32_16x16x32_bf16 v[40:43], v[162:165], v[198:201], v[40:43]
	v_mfma_f32_16x16x32_bf16 v[40:43], v[170:173], v[202:205], v[40:43]
	v_mfma_f32_16x16x32_bf16 v[24:27], v[162:165], v[206:209], v[24:27]
	v_mfma_f32_16x16x32_bf16 v[24:27], v[170:173], v[210:213], v[24:27]
	v_mfma_f32_16x16x32_bf16 v[8:11], v[162:165], v[214:217], v[8:11]
	v_mfma_f32_16x16x32_bf16 v[8:11], v[170:173], v[218:221], v[8:11]
	s_setprio 0
	s_setprio 1
	v_mfma_f32_16x16x32_bf16 v[52:55], v[174:177], v[190:193], v[52:55]
	v_mfma_f32_16x16x32_bf16 v[52:55], v[178:181], v[194:197], v[52:55]
	v_mfma_f32_16x16x32_bf16 v[36:39], v[174:177], v[198:201], v[36:39]
	v_mfma_f32_16x16x32_bf16 v[36:39], v[178:181], v[202:205], v[36:39]
	v_mfma_f32_16x16x32_bf16 v[20:23], v[174:177], v[206:209], v[20:23]
	v_mfma_f32_16x16x32_bf16 v[20:23], v[178:181], v[210:213], v[20:23]
	v_mfma_f32_16x16x32_bf16 v[4:7], v[174:177], v[214:217], v[4:7]
	v_mfma_f32_16x16x32_bf16 v[4:7], v[178:181], v[218:221], v[4:7]
	v_mfma_f32_16x16x32_bf16 v[48:51], v[182:185], v[190:193], v[48:51]
	v_mfma_f32_16x16x32_bf16 v[48:51], v[186:189], v[194:197], v[48:51]
	v_mfma_f32_16x16x32_bf16 v[32:35], v[182:185], v[198:201], v[32:35]
	v_mfma_f32_16x16x32_bf16 v[32:35], v[186:189], v[202:205], v[32:35]
	v_mfma_f32_16x16x32_bf16 v[16:19], v[182:185], v[206:209], v[16:19]
	v_mfma_f32_16x16x32_bf16 v[16:19], v[186:189], v[210:213], v[16:19]
	v_mfma_f32_16x16x32_bf16 v[0:3], v[182:185], v[214:217], v[0:3]
	v_mfma_f32_16x16x32_bf16 v[0:3], v[186:189], v[218:221], v[0:3]
	s_setprio 0
	s_barrier
	s_add_i32 s56, 0, 0x18000
	s_add_i32 s57, 0, 0x1c000
	v_add_u32_e32 v170, s56, v146
	v_add_u32_e32 v186, s57, v146
	ds_read_b128 v[154:157], v170
	ds_read_b128 v[158:161], v170 offset:1024
	ds_read_b128 v[162:165], v170 offset:2048
	ds_read_b128 v[170:173], v170 offset:3072
	ds_read_b128 v[174:177], v186
	ds_read_b128 v[178:181], v186 offset:1024
	ds_read_b128 v[182:185], v186 offset:2048
	ds_read_b128 v[186:189], v186 offset:3072
	s_add_u32 s22, s22, 0x84000
	s_addc_u32 s23, s23, 0
	s_mov_b32 m0, s39
	v_lshl_add_u64 v[228:229], s[22:23], 0, v[128:129]
	ds_read_b128 v[190:193], v152 offset:32768
	ds_read_b128 v[194:197], v152 offset:33792
	ds_read_b128 v[198:201], v152 offset:34816
	ds_read_b128 v[202:205], v152 offset:35840
	ds_read_b128 v[206:209], v152 offset:36864
	ds_read_b128 v[210:213], v152 offset:37888
	ds_read_b128 v[214:217], v152 offset:38912
	ds_read_b128 v[218:221], v152 offset:39936
	global_load_lds_dwordx4 v[228:229], off
	v_lshl_add_u64 v[228:229], s[22:23], 0, v[132:133]
	s_mov_b32 m0, s40
	s_nop 0
	global_load_lds_dwordx4 v[228:229], off
	s_waitcnt vmcnt(8)
	s_waitcnt lgkmcnt(0)
	s_barrier
	s_setprio 1
	s_waitcnt lgkmcnt(0)
	v_mfma_f32_16x16x32_bf16 v[124:127], v[154:157], v[190:193], v[124:127]
	v_mfma_f32_16x16x32_bf16 v[124:127], v[158:161], v[194:197], v[124:127]
	v_mfma_f32_16x16x32_bf16 v[108:111], v[154:157], v[198:201], v[108:111]
	v_mfma_f32_16x16x32_bf16 v[108:111], v[158:161], v[202:205], v[108:111]
	v_mfma_f32_16x16x32_bf16 v[92:95], v[154:157], v[206:209], v[92:95]
	v_mfma_f32_16x16x32_bf16 v[92:95], v[158:161], v[210:213], v[92:95]
	v_mfma_f32_16x16x32_bf16 v[76:79], v[154:157], v[214:217], v[76:79]
	v_mfma_f32_16x16x32_bf16 v[76:79], v[158:161], v[218:221], v[76:79]
	v_mfma_f32_16x16x32_bf16 v[120:123], v[162:165], v[190:193], v[120:123]
	v_mfma_f32_16x16x32_bf16 v[120:123], v[170:173], v[194:197], v[120:123]
	v_mfma_f32_16x16x32_bf16 v[104:107], v[162:165], v[198:201], v[104:107]
	v_mfma_f32_16x16x32_bf16 v[104:107], v[170:173], v[202:205], v[104:107]
	v_mfma_f32_16x16x32_bf16 v[88:91], v[162:165], v[206:209], v[88:91]
	v_mfma_f32_16x16x32_bf16 v[88:91], v[170:173], v[210:213], v[88:91]
	v_mfma_f32_16x16x32_bf16 v[72:75], v[162:165], v[214:217], v[72:75]
	v_mfma_f32_16x16x32_bf16 v[72:75], v[170:173], v[218:221], v[72:75]
	s_setprio 0
	s_setprio 1
	v_mfma_f32_16x16x32_bf16 v[116:119], v[174:177], v[190:193], v[116:119]
	v_mfma_f32_16x16x32_bf16 v[116:119], v[178:181], v[194:197], v[116:119]
	v_mfma_f32_16x16x32_bf16 v[100:103], v[174:177], v[198:201], v[100:103]
	v_mfma_f32_16x16x32_bf16 v[100:103], v[178:181], v[202:205], v[100:103]
	v_mfma_f32_16x16x32_bf16 v[84:87], v[174:177], v[206:209], v[84:87]
	v_mfma_f32_16x16x32_bf16 v[84:87], v[178:181], v[210:213], v[84:87]
	v_mfma_f32_16x16x32_bf16 v[68:71], v[174:177], v[214:217], v[68:71]
	v_mfma_f32_16x16x32_bf16 v[68:71], v[178:181], v[218:221], v[68:71]
	v_mfma_f32_16x16x32_bf16 v[112:115], v[182:185], v[190:193], v[112:115]
	v_mfma_f32_16x16x32_bf16 v[112:115], v[186:189], v[194:197], v[112:115]
	v_mfma_f32_16x16x32_bf16 v[96:99], v[182:185], v[198:201], v[96:99]
	v_mfma_f32_16x16x32_bf16 v[96:99], v[186:189], v[202:205], v[96:99]
	v_mfma_f32_16x16x32_bf16 v[80:83], v[182:185], v[206:209], v[80:83]
	v_mfma_f32_16x16x32_bf16 v[80:83], v[186:189], v[210:213], v[80:83]
	v_mfma_f32_16x16x32_bf16 v[64:67], v[182:185], v[214:217], v[64:67]
	v_mfma_f32_16x16x32_bf16 v[64:67], v[186:189], v[218:221], v[64:67]
	s_setprio 0
	s_barrier
; #define PG8_STAGE(bufoff, gbase, voff) do { _Pragma("unroll") for (int _i = 0; _i < 2; ++_i) \
;         __builtin_amdgcn_global_load_lds((const unsigned*)((const char*)(gbase) + (voff)[_i]), (LAS unsigned*)(lds + (bufoff) + ldsw + _i * 8192), 16, 0, 0); } while (0)
; #define PG8_LDA(dst, b, h) do { _Pragma("unroll") for (int m = 0; m < 4; ++m) _Pragma("unroll") for (int k = 0; k < 2; ++k) dst[m][k] = *(const LAS bf16x8*)(lds + PG8_SA(b, h) + aoff + m * 2048 + k * 1024); } while (0)
; #define PG8_MMA(ai, bj, At, Bt) do { __builtin_amdgcn_s_setprio(1); _Pragma("unroll") for (int m = 0; m < 4; ++m) _Pragma("unroll") for (int n = 0; n < 2; ++n) _Pragma("unroll") for (int k = 0; k < 2; ++k) \
;         acc[ai][bj][m][n] = __builtin_amdgcn_mfma_f32_16x16x32_bf16(Bt[n][k], At[m][k], acc[ai][bj][m][n], 0, 0, 0); __builtin_amdgcn_s_setprio(0); } while (0)
; #define PG8_WAIT_V(n) asm volatile("s_waitcnt vmcnt(" #n ")" ::: "memory")
; #define PG8_WAIT_L(n) asm volatile("s_waitcnt lgkmcnt(" #n ")" ::: "memory")
; #define PG8_BAR __builtin_amdgcn_s_barrier()
; #define PG8_SCHED __builtin_amdgcn_sched_barrier(0)
; template <class EpiT>
; __device__ __forceinline__ void gemm_phase(LAS unsigned char* lds, const Gemm g, const StaticOrder& S, const EpiT& E) {
;     ...
;         for (int t = 0; t < nt; t += 2) {
;     ...
;             PG8_LDA(At, 1, 1); PG8_STAGE(PG8_SB(1, 0), b3, voffB); PG8_STAGE(PG8_SB(1, 1), b3 + hstepB, voffB); PG8_STAGE(PG8_SA(1, 0), a3, voffA);
;             PG8_WAIT_V(8); PG8_WAIT_L(0); PG8_BAR; PG8_MMA(1, 0, At, B0); PG8_MMA(1, 1, At, B1); PG8_BAR; PG8_SCHED;
	s_add_i32 s22, s56, s36
	v_lshl_add_u64 v[166:167], v[166:167], 0, s[12:13]
	s_mov_b32 m0, s22
	ds_read_b128 v[190:193], v152 offset:49152
	ds_read_b128 v[194:197], v152 offset:50176
	ds_read_b128 v[198:201], v152 offset:51200
	ds_read_b128 v[202:205], v152 offset:52224
	ds_read_b128 v[206:209], v152 offset:53248
	ds_read_b128 v[210:213], v152 offset:54272
	ds_read_b128 v[214:217], v152 offset:55296
	ds_read_b128 v[218:221], v152 offset:56320
	global_load_lds_dwordx4 v[166:167], off
	s_add_i32 m0, s22, 0x2000
	s_add_u32 s20, s20, 0x84080
	v_lshl_add_u64 v[166:167], v[222:223], 0, s[12:13]
	s_addc_u32 s21, s21, 0
	s_add_i32 s22, s57, s36
	global_load_lds_dwordx4 v[166:167], off
	v_lshl_add_u64 v[166:167], s[20:21], 0, v[130:131]
	s_mov_b32 m0, s22
	s_nop 0
	global_load_lds_dwordx4 v[166:167], off
	v_lshl_add_u64 v[166:167], s[20:21], 0, v[134:135]
	s_add_i32 m0, s22, 0x2000
	s_nop 0
	global_load_lds_dwordx4 v[166:167], off
	v_lshl_add_u64 v[166:167], v[224:225], 0, s[12:13]
	s_mov_b32 m0, s42
	s_nop 0
	global_load_lds_dwordx4 v[166:167], off
	v_lshl_add_u64 v[166:167], v[226:227], 0, s[12:13]
	s_mov_b32 m0, s43
	s_nop 0
	global_load_lds_dwordx4 v[166:167], off
	s_waitcnt vmcnt(8)
	s_waitcnt lgkmcnt(0)
	s_barrier
	s_setprio 1
	s_waitcnt lgkmcnt(0)
	v_mfma_f32_16x16x32_bf16 v[60:63], v[154:157], v[190:193], v[60:63]
	v_mfma_f32_16x16x32_bf16 v[60:63], v[158:161], v[194:197], v[60:63]
	v_mfma_f32_16x16x32_bf16 v[44:47], v[154:157], v[198:201], v[44:47]
	v_mfma_f32_16x16x32_bf16 v[44:47], v[158:161], v[202:205], v[44:47]
	v_mfma_f32_16x16x32_bf16 v[28:31], v[154:157], v[206:209], v[28:31]
	v_mfma_f32_16x16x32_bf16 v[28:31], v[158:161], v[210:213], v[28:31]
	v_mfma_f32_16x16x32_bf16 v[12:15], v[154:157], v[214:217], v[12:15]
	v_mfma_f32_16x16x32_bf16 v[12:15], v[158:161], v[218:221], v[12:15]
	v_mfma_f32_16x16x32_bf16 v[56:59], v[162:165], v[190:193], v[56:59]
	v_mfma_f32_16x16x32_bf16 v[56:59], v[170:173], v[194:197], v[56:59]
	v_mfma_f32_16x16x32_bf16 v[40:43], v[162:165], v[198:201], v[40:43]
	v_mfma_f32_16x16x32_bf16 v[40:43], v[170:173], v[202:205], v[40:43]
	v_mfma_f32_16x16x32_bf16 v[24:27], v[162:165], v[206:209], v[24:27]
	v_mfma_f32_16x16x32_bf16 v[24:27], v[170:173], v[210:213], v[24:27]
	v_mfma_f32_16x16x32_bf16 v[8:11], v[162:165], v[214:217], v[8:11]
	v_mfma_f32_16x16x32_bf16 v[8:11], v[170:173], v[218:221], v[8:11]
	s_setprio 0
	s_setprio 1
	v_mfma_f32_16x16x32_bf16 v[52:55], v[174:177], v[190:193], v[52:55]
	v_mfma_f32_16x16x32_bf16 v[52:55], v[178:181], v[194:197], v[52:55]
	v_mfma_f32_16x16x32_bf16 v[36:39], v[174:177], v[198:201], v[36:39]
	v_mfma_f32_16x16x32_bf16 v[36:39], v[178:181], v[202:205], v[36:39]
	v_mfma_f32_16x16x32_bf16 v[20:23], v[174:177], v[206:209], v[20:23]
	v_mfma_f32_16x16x32_bf16 v[20:23], v[178:181], v[210:213], v[20:23]
	v_mfma_f32_16x16x32_bf16 v[4:7], v[174:177], v[214:217], v[4:7]
	v_mfma_f32_16x16x32_bf16 v[4:7], v[178:181], v[218:221], v[4:7]
	v_mfma_f32_16x16x32_bf16 v[48:51], v[182:185], v[190:193], v[48:51]
	v_mfma_f32_16x16x32_bf16 v[48:51], v[186:189], v[194:197], v[48:51]
	v_mfma_f32_16x16x32_bf16 v[32:35], v[182:185], v[198:201], v[32:35]
	v_mfma_f32_16x16x32_bf16 v[32:35], v[186:189], v[202:205], v[32:35]
	v_mfma_f32_16x16x32_bf16 v[16:19], v[182:185], v[206:209], v[16:19]
	v_mfma_f32_16x16x32_bf16 v[16:19], v[186:189], v[210:213], v[16:19]
	v_mfma_f32_16x16x32_bf16 v[0:3], v[182:185], v[214:217], v[0:3]
	v_mfma_f32_16x16x32_bf16 v[0:3], v[186:189], v[218:221], v[0:3]
	s_setprio 0
	s_barrier
	s_add_i32 s55, s55, 2
	s_add_u32 s18, s18, 0x100
	s_addc_u32 s19, s19, 0
	s_add_u32 s53, s53, 0x100
	s_addc_u32 s54, s54, 0
	s_cmp_gt_u32 s55, 29
	s_cbranch_scc1 .Lrot_done_1032
; #define PG8_STAGE(bufoff, gbase, voff) do { _Pragma("unroll") for (int _i = 0; _i < 2; ++_i) \
;         __builtin_amdgcn_global_load_lds((const unsigned*)((const char*)(gbase) + (voff)[_i]), (LAS unsigned*)(lds + (bufoff) + ldsw + _i * 8192), 16, 0, 0); } while (0)
; #define PG8_LDA(dst, b, h) do { _Pragma("unroll") for (int m = 0; m < 4; ++m) _Pragma("unroll") for (int k = 0; k < 2; ++k) dst[m][k] = *(const LAS bf16x8*)(lds + PG8_SA(b, h) + aoff + m * 2048 + k * 1024); } while (0)
; #define PG8_LDB(dst, b, h) do { _Pragma("unroll") for (int n = 0; n < 2; ++n) _Pragma("unroll") for (int k = 0; k < 2; ++k) dst[n][k] = *(const LAS bf16x8*)(lds + PG8_SB(b, h) + boff + n * 2048 + k * 1024); } while (0)
; #define PG8_MMA(ai, bj, At, Bt) do { __builtin_amdgcn_s_setprio(1); _Pragma("unroll") for (int m = 0; m < 4; ++m) _Pragma("unroll") for (int n = 0; n < 2; ++n) _Pragma("unroll") for (int k = 0; k < 2; ++k) \
;         acc[ai][bj][m][n] = __builtin_amdgcn_mfma_f32_16x16x32_bf16(Bt[n][k], At[m][k], acc[ai][bj][m][n], 0, 0, 0); __builtin_amdgcn_s_setprio(0); } while (0)
; #define PG8_WAIT_V(n) asm volatile("s_waitcnt vmcnt(" #n ")" ::: "memory")
; #define PG8_WAIT_L(n) asm volatile("s_waitcnt lgkmcnt(" #n ")" ::: "memory")
; #define PG8_BAR __builtin_amdgcn_s_barrier()
; #define PG8_SCHED __builtin_amdgcn_sched_barrier(0)
; template <class EpiT>
; __device__ __forceinline__ void gemm_phase(LAS unsigned char* lds, const Gemm g, const StaticOrder& S, const EpiT& E) {
;     ...
;             PG8_LDB(B0, 0, 0); PG8_LDB(B1, 0, 1); PG8_SCHED; PG8_LDA(At, 0, 0); PG8_STAGE(PG8_SA(1, 1), a1 + hstepA, voffA);
;             PG8_WAIT_V(8); PG8_WAIT_L(0); PG8_BAR; PG8_MMA(0, 0, At, B0); PG8_MMA(0, 1, At, B1); PG8_BAR; PG8_SCHED;
	ds_read_b128 v[154:157], v150
	ds_read_b128 v[158:161], v150 offset:1024
	ds_read_b128 v[162:165], v150 offset:2048
	ds_read_b128 v[170:173], v150 offset:3072
	ds_read_b128 v[174:177], v151
	ds_read_b128 v[178:181], v151 offset:1024
	ds_read_b128 v[182:185], v151 offset:2048
	ds_read_b128 v[186:189], v151 offset:3072
	s_add_u32 s20, s18, 0xfff7c080
	s_addc_u32 s21, s19, -1
	s_cmp_eq_u32 s55, 28
	s_cselect_b32 s23, s5, s21
	s_cselect_b32 s22, s4, s20
	s_cselect_b32 s21, s17, s54
	s_cselect_b32 s20, s16, s53
	v_lshl_add_u64 v[166:167], s[18:19], 0, v[138:139]
	s_add_i32 m0, s37, 0xc000
	ds_read_b128 v[190:193], v152
	ds_read_b128 v[194:197], v152 offset:1024
	ds_read_b128 v[198:201], v152 offset:2048
	ds_read_b128 v[202:205], v152 offset:3072
	ds_read_b128 v[206:209], v152 offset:4096
	ds_read_b128 v[210:213], v152 offset:5120
	ds_read_b128 v[214:217], v152 offset:6144
	ds_read_b128 v[218:221], v152 offset:7168
	global_load_lds_dwordx4 v[166:167], off
	v_lshl_add_u64 v[166:167], s[18:19], 0, v[140:141]
	s_add_i32 m0, s37, 0xe000
	s_nop 0
	global_load_lds_dwordx4 v[166:167], off
	s_waitcnt vmcnt(8)
	s_waitcnt lgkmcnt(0)
	s_barrier
	s_setprio 1
	s_waitcnt lgkmcnt(0)
	v_mfma_f32_16x16x32_bf16 v[124:127], v[154:157], v[190:193], v[124:127]
	v_mfma_f32_16x16x32_bf16 v[124:127], v[158:161], v[194:197], v[124:127]
	v_mfma_f32_16x16x32_bf16 v[108:111], v[154:157], v[198:201], v[108:111]
	v_mfma_f32_16x16x32_bf16 v[108:111], v[158:161], v[202:205], v[108:111]
	v_mfma_f32_16x16x32_bf16 v[92:95], v[154:157], v[206:209], v[92:95]
	v_mfma_f32_16x16x32_bf16 v[92:95], v[158:161], v[210:213], v[92:95]
	v_mfma_f32_16x16x32_bf16 v[76:79], v[154:157], v[214:217], v[76:79]
	v_mfma_f32_16x16x32_bf16 v[76:79], v[158:161], v[218:221], v[76:79]
	v_mfma_f32_16x16x32_bf16 v[120:123], v[162:165], v[190:193], v[120:123]
	v_mfma_f32_16x16x32_bf16 v[120:123], v[170:173], v[194:197], v[120:123]
	v_mfma_f32_16x16x32_bf16 v[104:107], v[162:165], v[198:201], v[104:107]
	v_mfma_f32_16x16x32_bf16 v[104:107], v[170:173], v[202:205], v[104:107]
	v_mfma_f32_16x16x32_bf16 v[88:91], v[162:165], v[206:209], v[88:91]
	v_mfma_f32_16x16x32_bf16 v[88:91], v[170:173], v[210:213], v[88:91]
	v_mfma_f32_16x16x32_bf16 v[72:75], v[162:165], v[214:217], v[72:75]
	v_mfma_f32_16x16x32_bf16 v[72:75], v[170:173], v[218:221], v[72:75]
	s_setprio 0
	s_setprio 1
	v_mfma_f32_16x16x32_bf16 v[116:119], v[174:177], v[190:193], v[116:119]
	v_mfma_f32_16x16x32_bf16 v[116:119], v[178:181], v[194:197], v[116:119]
	v_mfma_f32_16x16x32_bf16 v[100:103], v[174:177], v[198:201], v[100:103]
	v_mfma_f32_16x16x32_bf16 v[100:103], v[178:181], v[202:205], v[100:103]
	v_mfma_f32_16x16x32_bf16 v[84:87], v[174:177], v[206:209], v[84:87]
	v_mfma_f32_16x16x32_bf16 v[84:87], v[178:181], v[210:213], v[84:87]
	v_mfma_f32_16x16x32_bf16 v[68:71], v[174:177], v[214:217], v[68:71]
	v_mfma_f32_16x16x32_bf16 v[68:71], v[178:181], v[218:221], v[68:71]
	v_mfma_f32_16x16x32_bf16 v[112:115], v[182:185], v[190:193], v[112:115]
	v_mfma_f32_16x16x32_bf16 v[112:115], v[186:189], v[194:197], v[112:115]
	v_mfma_f32_16x16x32_bf16 v[96:99], v[182:185], v[198:201], v[96:99]
	v_mfma_f32_16x16x32_bf16 v[96:99], v[186:189], v[202:205], v[96:99]
	v_mfma_f32_16x16x32_bf16 v[80:83], v[182:185], v[206:209], v[80:83]
	v_mfma_f32_16x16x32_bf16 v[80:83], v[186:189], v[210:213], v[80:83]
	v_mfma_f32_16x16x32_bf16 v[64:67], v[182:185], v[214:217], v[64:67]
	v_mfma_f32_16x16x32_bf16 v[64:67], v[186:189], v[218:221], v[64:67]
	s_setprio 0
	s_barrier
	s_branch .Lrot_1032

; #define PG8_STAGE(bufoff, gbase, voff) do { _Pragma("unroll") for (int _i = 0; _i < 2; ++_i) \
;         __builtin_amdgcn_global_load_lds((const unsigned*)((const char*)(gbase) + (voff)[_i]), (LAS unsigned*)(lds + (bufoff) + ldsw + _i * 8192), 16, 0, 0); } while (0)
; #define PG8_LDA(dst, b, h) do { _Pragma("unroll") for (int m = 0; m < 4; ++m) _Pragma("unroll") for (int k = 0; k < 2; ++k) dst[m][k] = *(const LAS bf16x8*)(lds + PG8_SA(b, h) + aoff + m * 2048 + k * 1024); } while (0)
; #define PG8_LDB(dst, b, h) do { _Pragma("unroll") for (int n = 0; n < 2; ++n) _Pragma("unroll") for (int k = 0; k < 2; ++k) dst[n][k] = *(const LAS bf16x8*)(lds + PG8_SB(b, h) + boff + n * 2048 + k * 1024); } while (0)
; #define PG8_MMA(ai, bj, At, Bt) do { __builtin_amdgcn_s_setprio(1); _Pragma("unroll") for (int m = 0; m < 4; ++m) _Pragma("unroll") for (int n = 0; n < 2; ++n) _Pragma("unroll") for (int k = 0; k < 2; ++k) \
;         acc[ai][bj][m][n] = __builtin_amdgcn_mfma_f32_16x16x32_bf16(Bt[n][k], At[m][k], acc[ai][bj][m][n], 0, 0, 0); __builtin_amdgcn_s_setprio(0); } while (0)
; #define PG8_WAIT_V(n) asm volatile("s_waitcnt vmcnt(" #n ")" ::: "memory")
; #define PG8_WAIT_L(n) asm volatile("s_waitcnt lgkmcnt(" #n ")" ::: "memory")
; #define PG8_BAR __builtin_amdgcn_s_barrier()
; #define PG8_SCHED __builtin_amdgcn_sched_barrier(0)
; template <class EpiT>
; __device__ __forceinline__ void gemm_phase(LAS unsigned char* lds, const Gemm g, const StaticOrder& S, const EpiT& E) {
;     ...
;             PG8_LDB(B0, 0, 0); PG8_LDB(B1, 0, 1); PG8_SCHED; PG8_LDA(At, 0, 0); PG8_STAGE(PG8_SA(1, 1), a1 + hstepA, voffA);
;             PG8_WAIT_V(8); PG8_WAIT_L(0); PG8_BAR; PG8_MMA(0, 0, At, B0); PG8_MMA(0, 1, At, B1); PG8_BAR; PG8_SCHED;
;             PG8_LDA(At, 0, 1); PG8_STAGE(PG8_SB(0, 0), b2, voffB); PG8_STAGE(PG8_SB(0, 1), b2 + hstepB, voffB); PG8_STAGE(PG8_SA(0, 0), a2, voffA);
.LBB0_1156:
	ds_read_b128 v[154:157], v150
	ds_read_b128 v[158:161], v150 offset:1024
	ds_read_b128 v[162:165], v150 offset:2048
	ds_read_b128 v[170:173], v150 offset:3072
	ds_read_b128 v[174:177], v151
	ds_read_b128 v[178:181], v151 offset:1024
	ds_read_b128 v[182:185], v151 offset:2048
	ds_read_b128 v[186:189], v151 offset:3072
	s_add_u32 s18, s16, 0xfff7c080
	s_addc_u32 s19, s17, -1
	s_cmp_eq_u32 s53, 28
	s_cselect_b32 s21, s3, s19
	s_cselect_b32 s20, s2, s18
	s_cselect_b32 s19, s15, s52
	s_cselect_b32 s18, s14, s51
	v_lshl_add_u64 v[144:145], s[16:17], 0, v[136:137]
	s_add_i32 m0, s36, 0xc000
	ds_read_b128 v[190:193], v152
	ds_read_b128 v[194:197], v152 offset:1024
	ds_read_b128 v[198:201], v152 offset:2048
	ds_read_b128 v[202:205], v152 offset:3072
	ds_read_b128 v[206:209], v152 offset:4096
	ds_read_b128 v[210:213], v152 offset:5120
	ds_read_b128 v[214:217], v152 offset:6144
	ds_read_b128 v[218:221], v152 offset:7168
	global_load_lds_dwordx4 v[144:145], off
	v_lshl_add_u64 v[144:145], s[16:17], 0, v[138:139]
	s_add_i32 m0, s36, 0xe000
	s_nop 0
	global_load_lds_dwordx4 v[144:145], off
	s_waitcnt vmcnt(8)
	s_waitcnt lgkmcnt(0)
	s_barrier
	s_setprio 1
	s_waitcnt lgkmcnt(0)
	v_mfma_f32_16x16x32_bf16 v[124:127], v[154:157], v[190:193], v[124:127]
	v_mfma_f32_16x16x32_bf16 v[124:127], v[158:161], v[194:197], v[124:127]
	v_mfma_f32_16x16x32_bf16 v[108:111], v[154:157], v[198:201], v[108:111]
	v_mfma_f32_16x16x32_bf16 v[108:111], v[158:161], v[202:205], v[108:111]
	v_mfma_f32_16x16x32_bf16 v[92:95], v[154:157], v[206:209], v[92:95]
	v_mfma_f32_16x16x32_bf16 v[92:95], v[158:161], v[210:213], v[92:95]
	v_mfma_f32_16x16x32_bf16 v[76:79], v[154:157], v[214:217], v[76:79]
	v_mfma_f32_16x16x32_bf16 v[76:79], v[158:161], v[218:221], v[76:79]
	v_mfma_f32_16x16x32_bf16 v[120:123], v[162:165], v[190:193], v[120:123]
	v_mfma_f32_16x16x32_bf16 v[120:123], v[170:173], v[194:197], v[120:123]
	v_mfma_f32_16x16x32_bf16 v[104:107], v[162:165], v[198:201], v[104:107]
	v_mfma_f32_16x16x32_bf16 v[104:107], v[170:173], v[202:205], v[104:107]
	v_mfma_f32_16x16x32_bf16 v[88:91], v[162:165], v[206:209], v[88:91]
	v_mfma_f32_16x16x32_bf16 v[88:91], v[170:173], v[210:213], v[88:91]
	v_mfma_f32_16x16x32_bf16 v[72:75], v[162:165], v[214:217], v[72:75]
	v_mfma_f32_16x16x32_bf16 v[72:75], v[170:173], v[218:221], v[72:75]
	s_setprio 0
	s_setprio 1
	v_mfma_f32_16x16x32_bf16 v[116:119], v[174:177], v[190:193], v[116:119]
	v_mfma_f32_16x16x32_bf16 v[116:119], v[178:181], v[194:197], v[116:119]
	v_mfma_f32_16x16x32_bf16 v[100:103], v[174:177], v[198:201], v[100:103]
	v_mfma_f32_16x16x32_bf16 v[100:103], v[178:181], v[202:205], v[100:103]
	v_mfma_f32_16x16x32_bf16 v[84:87], v[174:177], v[206:209], v[84:87]
	v_mfma_f32_16x16x32_bf16 v[84:87], v[178:181], v[210:213], v[84:87]
	v_mfma_f32_16x16x32_bf16 v[68:71], v[174:177], v[214:217], v[68:71]
	v_mfma_f32_16x16x32_bf16 v[68:71], v[178:181], v[218:221], v[68:71]
	v_mfma_f32_16x16x32_bf16 v[112:115], v[182:185], v[190:193], v[112:115]
	v_mfma_f32_16x16x32_bf16 v[112:115], v[186:189], v[194:197], v[112:115]
	v_mfma_f32_16x16x32_bf16 v[96:99], v[182:185], v[198:201], v[96:99]
	v_mfma_f32_16x16x32_bf16 v[96:99], v[186:189], v[202:205], v[96:99]
	v_mfma_f32_16x16x32_bf16 v[80:83], v[182:185], v[206:209], v[80:83]
	v_mfma_f32_16x16x32_bf16 v[80:83], v[186:189], v[210:213], v[80:83]
	v_mfma_f32_16x16x32_bf16 v[64:67], v[182:185], v[214:217], v[64:67]
	v_mfma_f32_16x16x32_bf16 v[64:67], v[186:189], v[218:221], v[64:67]
	s_setprio 0
	s_barrier
.Lrot_1156:
	s_add_i32 s54, s44, s27
	v_lshl_add_u64 v[144:145], s[18:19], 0, v[132:133]
	s_mov_b32 m0, s54
	ds_read_b128 v[190:193], v152 offset:16384
	ds_read_b128 v[194:197], v152 offset:17408
	ds_read_b128 v[198:201], v152 offset:18432
	ds_read_b128 v[202:205], v152 offset:19456
	ds_read_b128 v[206:209], v152 offset:20480
	ds_read_b128 v[210:213], v152 offset:21504
	ds_read_b128 v[214:217], v152 offset:22528
	ds_read_b128 v[218:221], v152 offset:23552
	global_load_lds_dwordx4 v[144:145], off
	s_add_i32 m0, s54, 0x2000
	s_add_u32 s54, s18, 0x84000
	v_lshl_add_u64 v[166:167], s[18:19], 0, v[128:129]
	s_addc_u32 s55, s19, 0
	s_add_i32 s56, s45, s27
	global_load_lds_dwordx4 v[166:167], off
	v_lshl_add_u64 v[222:223], s[54:55], 0, v[132:133]
	s_mov_b32 m0, s56
	v_lshl_add_u64 v[224:225], s[20:21], 0, v[130:131]
	global_load_lds_dwordx4 v[222:223], off
	v_lshl_add_u64 v[222:223], s[54:55], 0, v[128:129]
	s_add_i32 m0, s56, 0x2000
	s_nop 0
	global_load_lds_dwordx4 v[222:223], off
	v_lshl_add_u64 v[222:223], s[20:21], 0, v[134:135]
	s_mov_b32 m0, s36
	s_nop 0
	global_load_lds_dwordx4 v[222:223], off
	s_mov_b32 m0, s37
	s_nop 0
	global_load_lds_dwordx4 v[224:225], off
	s_waitcnt vmcnt(8)
	s_waitcnt lgkmcnt(0)
	s_barrier
; #define PG8_STAGE(bufoff, gbase, voff) do { _Pragma("unroll") for (int _i = 0; _i < 2; ++_i) \
;         __builtin_amdgcn_global_load_lds((const unsigned*)((const char*)(gbase) + (voff)[_i]), (LAS unsigned*)(lds + (bufoff) + ldsw + _i * 8192), 16, 0, 0); } while (0)
; #define PG8_LDA(dst, b, h) do { _Pragma("unroll") for (int m = 0; m < 4; ++m) _Pragma("unroll") for (int k = 0; k < 2; ++k) dst[m][k] = *(const LAS bf16x8*)(lds + PG8_SA(b, h) + aoff + m * 2048 + k * 1024); } while (0)
; #define PG8_LDB(dst, b, h) do { _Pragma("unroll") for (int n = 0; n < 2; ++n) _Pragma("unroll") for (int k = 0; k < 2; ++k) dst[n][k] = *(const LAS bf16x8*)(lds + PG8_SB(b, h) + boff + n * 2048 + k * 1024); } while (0)
; #define PG8_MMA(ai, bj, At, Bt) do { __builtin_amdgcn_s_setprio(1); _Pragma("unroll") for (int m = 0; m < 4; ++m) _Pragma("unroll") for (int n = 0; n < 2; ++n) _Pragma("unroll") for (int k = 0; k < 2; ++k) \
;         acc[ai][bj][m][n] = __builtin_amdgcn_mfma_f32_16x16x32_bf16(Bt[n][k], At[m][k], acc[ai][bj][m][n], 0, 0, 0); __builtin_amdgcn_s_setprio(0); } while (0)
; #define PG8_WAIT_V(n) asm volatile("s_waitcnt vmcnt(" #n ")" ::: "memory")
; #define PG8_WAIT_L(n) asm volatile("s_waitcnt lgkmcnt(" #n ")" ::: "memory")
; #define PG8_BAR __builtin_amdgcn_s_barrier()
; #define PG8_SCHED __builtin_amdgcn_sched_barrier(0)
; template <class EpiT>
; __device__ __forceinline__ void gemm_phase(LAS unsigned char* lds, const Gemm g, const StaticOrder& S, const EpiT& E) {
;     ...
;             PG8_WAIT_V(8); PG8_WAIT_L(0); PG8_BAR; PG8_MMA(1, 0, At, B0); PG8_MMA(1, 1, At, B1); PG8_BAR; PG8_SCHED;
;             PG8_LDB(B0, 1, 0); PG8_LDB(B1, 1, 1); PG8_SCHED; PG8_LDA(At, 1, 0); PG8_STAGE(PG8_SA(0, 1), a2 + hstepA, voffA);
;             PG8_WAIT_V(8); PG8_WAIT_L(0); PG8_BAR; PG8_MMA(0, 0, At, B0); PG8_MMA(0, 1, At, B1); PG8_BAR; PG8_SCHED;
	s_setprio 1
	s_waitcnt lgkmcnt(0)
	v_mfma_f32_16x16x32_bf16 v[60:63], v[154:157], v[190:193], v[60:63]
	v_mfma_f32_16x16x32_bf16 v[60:63], v[158:161], v[194:197], v[60:63]
	v_mfma_f32_16x16x32_bf16 v[44:47], v[154:157], v[198:201], v[44:47]
	v_mfma_f32_16x16x32_bf16 v[44:47], v[158:161], v[202:205], v[44:47]
	v_mfma_f32_16x16x32_bf16 v[28:31], v[154:157], v[206:209], v[28:31]
	v_mfma_f32_16x16x32_bf16 v[28:31], v[158:161], v[210:213], v[28:31]
	v_mfma_f32_16x16x32_bf16 v[12:15], v[154:157], v[214:217], v[12:15]
	v_mfma_f32_16x16x32_bf16 v[12:15], v[158:161], v[218:221], v[12:15]
	v_mfma_f32_16x16x32_bf16 v[56:59], v[162:165], v[190:193], v[56:59]
	v_mfma_f32_16x16x32_bf16 v[56:59], v[170:173], v[194:197], v[56:59]
	v_mfma_f32_16x16x32_bf16 v[40:43], v[162:165], v[198:201], v[40:43]
	v_mfma_f32_16x16x32_bf16 v[40:43], v[170:173], v[202:205], v[40:43]
	v_mfma_f32_16x16x32_bf16 v[24:27], v[162:165], v[206:209], v[24:27]
	v_mfma_f32_16x16x32_bf16 v[24:27], v[170:173], v[210:213], v[24:27]
	v_mfma_f32_16x16x32_bf16 v[8:11], v[162:165], v[214:217], v[8:11]
	v_mfma_f32_16x16x32_bf16 v[8:11], v[170:173], v[218:221], v[8:11]
	s_setprio 0
	s_setprio 1
	v_mfma_f32_16x16x32_bf16 v[52:55], v[174:177], v[190:193], v[52:55]
	v_mfma_f32_16x16x32_bf16 v[52:55], v[178:181], v[194:197], v[52:55]
	v_mfma_f32_16x16x32_bf16 v[36:39], v[174:177], v[198:201], v[36:39]
	v_mfma_f32_16x16x32_bf16 v[36:39], v[178:181], v[202:205], v[36:39]
	v_mfma_f32_16x16x32_bf16 v[20:23], v[174:177], v[206:209], v[20:23]
	v_mfma_f32_16x16x32_bf16 v[20:23], v[178:181], v[210:213], v[20:23]
	v_mfma_f32_16x16x32_bf16 v[4:7], v[174:177], v[214:217], v[4:7]
	v_mfma_f32_16x16x32_bf16 v[4:7], v[178:181], v[218:221], v[4:7]
	v_mfma_f32_16x16x32_bf16 v[48:51], v[182:185], v[190:193], v[48:51]
	v_mfma_f32_16x16x32_bf16 v[48:51], v[186:189], v[194:197], v[48:51]
	v_mfma_f32_16x16x32_bf16 v[32:35], v[182:185], v[198:201], v[32:35]
	v_mfma_f32_16x16x32_bf16 v[32:35], v[186:189], v[202:205], v[32:35]
	v_mfma_f32_16x16x32_bf16 v[16:19], v[182:185], v[206:209], v[16:19]
	v_mfma_f32_16x16x32_bf16 v[16:19], v[186:189], v[210:213], v[16:19]
	v_mfma_f32_16x16x32_bf16 v[0:3], v[182:185], v[214:217], v[0:3]
	v_mfma_f32_16x16x32_bf16 v[0:3], v[186:189], v[218:221], v[0:3]
	s_setprio 0
	s_barrier
	s_add_i32 s54, 0, 0x18000
	v_add_u32_e32 v153, s54, v147
	s_add_i32 s55, 0, 0x1c000
	ds_read_b128 v[154:157], v153
	ds_read_b128 v[158:161], v153 offset:1024
	ds_read_b128 v[162:165], v153 offset:2048
	ds_read_b128 v[170:173], v153 offset:3072
	v_add_u32_e32 v153, s55, v147
	ds_read_b128 v[174:177], v153
	ds_read_b128 v[178:181], v153 offset:1024
	ds_read_b128 v[182:185], v153 offset:2048
	ds_read_b128 v[186:189], v153 offset:3072
	s_add_u32 s20, s20, 0x84000
	s_addc_u32 s21, s21, 0
	s_mov_b32 m0, s38
	v_lshl_add_u64 v[226:227], s[20:21], 0, v[134:135]
	ds_read_b128 v[190:193], v152 offset:32768
	ds_read_b128 v[194:197], v152 offset:33792
	ds_read_b128 v[198:201], v152 offset:34816
	ds_read_b128 v[202:205], v152 offset:35840
	ds_read_b128 v[206:209], v152 offset:36864
	ds_read_b128 v[210:213], v152 offset:37888
	ds_read_b128 v[214:217], v152 offset:38912
	ds_read_b128 v[218:221], v152 offset:39936
	global_load_lds_dwordx4 v[226:227], off
	v_lshl_add_u64 v[226:227], s[20:21], 0, v[130:131]
	s_mov_b32 m0, s39
	s_nop 0
	global_load_lds_dwordx4 v[226:227], off
	s_waitcnt vmcnt(8)
	s_waitcnt lgkmcnt(0)
	s_barrier
	s_setprio 1
	s_waitcnt lgkmcnt(0)
	v_mfma_f32_16x16x32_bf16 v[124:127], v[154:157], v[190:193], v[124:127]
	v_mfma_f32_16x16x32_bf16 v[124:127], v[158:161], v[194:197], v[124:127]
	v_mfma_f32_16x16x32_bf16 v[108:111], v[154:157], v[198:201], v[108:111]
	v_mfma_f32_16x16x32_bf16 v[108:111], v[158:161], v[202:205], v[108:111]
	v_mfma_f32_16x16x32_bf16 v[92:95], v[154:157], v[206:209], v[92:95]
	v_mfma_f32_16x16x32_bf16 v[92:95], v[158:161], v[210:213], v[92:95]
	v_mfma_f32_16x16x32_bf16 v[76:79], v[154:157], v[214:217], v[76:79]
	v_mfma_f32_16x16x32_bf16 v[76:79], v[158:161], v[218:221], v[76:79]
	v_mfma_f32_16x16x32_bf16 v[120:123], v[162:165], v[190:193], v[120:123]
	v_mfma_f32_16x16x32_bf16 v[120:123], v[170:173], v[194:197], v[120:123]
	v_mfma_f32_16x16x32_bf16 v[104:107], v[162:165], v[198:201], v[104:107]
	v_mfma_f32_16x16x32_bf16 v[104:107], v[170:173], v[202:205], v[104:107]
	v_mfma_f32_16x16x32_bf16 v[88:91], v[162:165], v[206:209], v[88:91]
	v_mfma_f32_16x16x32_bf16 v[88:91], v[170:173], v[210:213], v[88:91]
	v_mfma_f32_16x16x32_bf16 v[72:75], v[162:165], v[214:217], v[72:75]
	v_mfma_f32_16x16x32_bf16 v[72:75], v[170:173], v[218:221], v[72:75]
	s_setprio 0
	s_setprio 1
	v_mfma_f32_16x16x32_bf16 v[116:119], v[174:177], v[190:193], v[116:119]
	v_mfma_f32_16x16x32_bf16 v[116:119], v[178:181], v[194:197], v[116:119]
	v_mfma_f32_16x16x32_bf16 v[100:103], v[174:177], v[198:201], v[100:103]
	v_mfma_f32_16x16x32_bf16 v[100:103], v[178:181], v[202:205], v[100:103]
	v_mfma_f32_16x16x32_bf16 v[84:87], v[174:177], v[206:209], v[84:87]
	v_mfma_f32_16x16x32_bf16 v[84:87], v[178:181], v[210:213], v[84:87]
	v_mfma_f32_16x16x32_bf16 v[68:71], v[174:177], v[214:217], v[68:71]
	v_mfma_f32_16x16x32_bf16 v[68:71], v[178:181], v[218:221], v[68:71]
	v_mfma_f32_16x16x32_bf16 v[112:115], v[182:185], v[190:193], v[112:115]
	v_mfma_f32_16x16x32_bf16 v[112:115], v[186:189], v[194:197], v[112:115]
	v_mfma_f32_16x16x32_bf16 v[96:99], v[182:185], v[198:201], v[96:99]
	v_mfma_f32_16x16x32_bf16 v[96:99], v[186:189], v[202:205], v[96:99]
	v_mfma_f32_16x16x32_bf16 v[80:83], v[182:185], v[206:209], v[80:83]
	v_mfma_f32_16x16x32_bf16 v[80:83], v[186:189], v[210:213], v[80:83]
	v_mfma_f32_16x16x32_bf16 v[64:67], v[182:185], v[214:217], v[64:67]
	v_mfma_f32_16x16x32_bf16 v[64:67], v[186:189], v[218:221], v[64:67]
	s_setprio 0
	s_barrier
; #define PG8_STAGE(bufoff, gbase, voff) do { _Pragma("unroll") for (int _i = 0; _i < 2; ++_i) \
;         __builtin_amdgcn_global_load_lds((const unsigned*)((const char*)(gbase) + (voff)[_i]), (LAS unsigned*)(lds + (bufoff) + ldsw + _i * 8192), 16, 0, 0); } while (0)
; #define PG8_LDA(dst, b, h) do { _Pragma("unroll") for (int m = 0; m < 4; ++m) _Pragma("unroll") for (int k = 0; k < 2; ++k) dst[m][k] = *(const LAS bf16x8*)(lds + PG8_SA(b, h) + aoff + m * 2048 + k * 1024); } while (0)
; #define PG8_MMA(ai, bj, At, Bt) do { __builtin_amdgcn_s_setprio(1); _Pragma("unroll") for (int m = 0; m < 4; ++m) _Pragma("unroll") for (int n = 0; n < 2; ++n) _Pragma("unroll") for (int k = 0; k < 2; ++k) \
;         acc[ai][bj][m][n] = __builtin_amdgcn_mfma_f32_16x16x32_bf16(Bt[n][k], At[m][k], acc[ai][bj][m][n], 0, 0, 0); __builtin_amdgcn_s_setprio(0); } while (0)
; #define PG8_WAIT_V(n) asm volatile("s_waitcnt vmcnt(" #n ")" ::: "memory")
; #define PG8_WAIT_L(n) asm volatile("s_waitcnt lgkmcnt(" #n ")" ::: "memory")
; #define PG8_BAR __builtin_amdgcn_s_barrier()
; #define PG8_SCHED __builtin_amdgcn_sched_barrier(0)
; template <class EpiT>
; __device__ __forceinline__ void gemm_phase(LAS unsigned char* lds, const Gemm g, const StaticOrder& S, const EpiT& E) {
;     ...
;         for (int t = 0; t < nt; t += 2) {
;     ...
;             PG8_LDA(At, 1, 1); PG8_STAGE(PG8_SB(1, 0), b3, voffB); PG8_STAGE(PG8_SB(1, 1), b3 + hstepB, voffB); PG8_STAGE(PG8_SA(1, 0), a3, voffA);
;             PG8_WAIT_V(8); PG8_WAIT_L(0); PG8_BAR; PG8_MMA(1, 0, At, B0); PG8_MMA(1, 1, At, B1); PG8_BAR; PG8_SCHED;
;         }
	s_add_i32 s20, s54, s27
	v_lshl_add_u64 v[144:145], v[144:145], 0, s[10:11]
	s_mov_b32 m0, s20
	ds_read_b128 v[190:193], v152 offset:49152
	ds_read_b128 v[194:197], v152 offset:50176
	ds_read_b128 v[198:201], v152 offset:51200
	ds_read_b128 v[202:205], v152 offset:52224
	ds_read_b128 v[206:209], v152 offset:53248
	ds_read_b128 v[210:213], v152 offset:54272
	ds_read_b128 v[214:217], v152 offset:55296
	ds_read_b128 v[218:221], v152 offset:56320
	global_load_lds_dwordx4 v[144:145], off
	s_add_i32 m0, s20, 0x2000
	s_add_u32 s18, s18, 0x84080
	v_lshl_add_u64 v[144:145], v[166:167], 0, s[10:11]
	s_addc_u32 s19, s19, 0
	s_add_i32 s20, s55, s27
	global_load_lds_dwordx4 v[144:145], off
	v_lshl_add_u64 v[144:145], s[18:19], 0, v[132:133]
	s_mov_b32 m0, s20
	s_nop 0
	global_load_lds_dwordx4 v[144:145], off
	v_lshl_add_u64 v[144:145], s[18:19], 0, v[128:129]
	s_add_i32 m0, s20, 0x2000
	s_nop 0
	global_load_lds_dwordx4 v[144:145], off
	v_lshl_add_u64 v[144:145], v[222:223], 0, s[10:11]
	s_mov_b32 m0, s41
	s_nop 0
	global_load_lds_dwordx4 v[144:145], off
	v_lshl_add_u64 v[144:145], v[224:225], 0, s[10:11]
	s_mov_b32 m0, s42
	s_nop 0
	global_load_lds_dwordx4 v[144:145], off
	s_waitcnt vmcnt(8)
	s_waitcnt lgkmcnt(0)
	s_barrier
	s_setprio 1
	s_waitcnt lgkmcnt(0)
	v_mfma_f32_16x16x32_bf16 v[60:63], v[154:157], v[190:193], v[60:63]
	v_mfma_f32_16x16x32_bf16 v[60:63], v[158:161], v[194:197], v[60:63]
	v_mfma_f32_16x16x32_bf16 v[44:47], v[154:157], v[198:201], v[44:47]
	v_mfma_f32_16x16x32_bf16 v[44:47], v[158:161], v[202:205], v[44:47]
	v_mfma_f32_16x16x32_bf16 v[28:31], v[154:157], v[206:209], v[28:31]
	v_mfma_f32_16x16x32_bf16 v[28:31], v[158:161], v[210:213], v[28:31]
	v_mfma_f32_16x16x32_bf16 v[12:15], v[154:157], v[214:217], v[12:15]
	v_mfma_f32_16x16x32_bf16 v[12:15], v[158:161], v[218:221], v[12:15]
	v_mfma_f32_16x16x32_bf16 v[56:59], v[162:165], v[190:193], v[56:59]
	v_mfma_f32_16x16x32_bf16 v[56:59], v[170:173], v[194:197], v[56:59]
	v_mfma_f32_16x16x32_bf16 v[40:43], v[162:165], v[198:201], v[40:43]
	v_mfma_f32_16x16x32_bf16 v[40:43], v[170:173], v[202:205], v[40:43]
	v_mfma_f32_16x16x32_bf16 v[24:27], v[162:165], v[206:209], v[24:27]
	v_mfma_f32_16x16x32_bf16 v[24:27], v[170:173], v[210:213], v[24:27]
	v_mfma_f32_16x16x32_bf16 v[8:11], v[162:165], v[214:217], v[8:11]
	v_mfma_f32_16x16x32_bf16 v[8:11], v[170:173], v[218:221], v[8:11]
	s_setprio 0
	s_setprio 1
	v_mfma_f32_16x16x32_bf16 v[52:55], v[174:177], v[190:193], v[52:55]
	v_mfma_f32_16x16x32_bf16 v[52:55], v[178:181], v[194:197], v[52:55]
	v_mfma_f32_16x16x32_bf16 v[36:39], v[174:177], v[198:201], v[36:39]
	v_mfma_f32_16x16x32_bf16 v[36:39], v[178:181], v[202:205], v[36:39]
	v_mfma_f32_16x16x32_bf16 v[20:23], v[174:177], v[206:209], v[20:23]
	v_mfma_f32_16x16x32_bf16 v[20:23], v[178:181], v[210:213], v[20:23]
	v_mfma_f32_16x16x32_bf16 v[4:7], v[174:177], v[214:217], v[4:7]
	v_mfma_f32_16x16x32_bf16 v[4:7], v[178:181], v[218:221], v[4:7]
	v_mfma_f32_16x16x32_bf16 v[48:51], v[182:185], v[190:193], v[48:51]
	v_mfma_f32_16x16x32_bf16 v[48:51], v[186:189], v[194:197], v[48:51]
	v_mfma_f32_16x16x32_bf16 v[32:35], v[182:185], v[198:201], v[32:35]
	v_mfma_f32_16x16x32_bf16 v[32:35], v[186:189], v[202:205], v[32:35]
	v_mfma_f32_16x16x32_bf16 v[16:19], v[182:185], v[206:209], v[16:19]
	v_mfma_f32_16x16x32_bf16 v[16:19], v[186:189], v[210:213], v[16:19]
	v_mfma_f32_16x16x32_bf16 v[0:3], v[182:185], v[214:217], v[0:3]
	v_mfma_f32_16x16x32_bf16 v[0:3], v[186:189], v[218:221], v[0:3]
	s_setprio 0
	s_barrier
	s_add_i32 s53, s53, 2
	s_add_u32 s16, s16, 0x100
	s_addc_u32 s17, s17, 0
	s_add_u32 s51, s51, 0x100
	s_addc_u32 s52, s52, 0
	s_cmp_gt_u32 s53, 29
	s_cbranch_scc1 .Lrot_done_1156
; #define PG8_STAGE(bufoff, gbase, voff) do { _Pragma("unroll") for (int _i = 0; _i < 2; ++_i) \
;         __builtin_amdgcn_global_load_lds((const unsigned*)((const char*)(gbase) + (voff)[_i]), (LAS unsigned*)(lds + (bufoff) + ldsw + _i * 8192), 16, 0, 0); } while (0)
; #define PG8_LDA(dst, b, h) do { _Pragma("unroll") for (int m = 0; m < 4; ++m) _Pragma("unroll") for (int k = 0; k < 2; ++k) dst[m][k] = *(const LAS bf16x8*)(lds + PG8_SA(b, h) + aoff + m * 2048 + k * 1024); } while (0)
; #define PG8_LDB(dst, b, h) do { _Pragma("unroll") for (int n = 0; n < 2; ++n) _Pragma("unroll") for (int k = 0; k < 2; ++k) dst[n][k] = *(const LAS bf16x8*)(lds + PG8_SB(b, h) + boff + n * 2048 + k * 1024); } while (0)
; #define PG8_MMA(ai, bj, At, Bt) do { __builtin_amdgcn_s_setprio(1); _Pragma("unroll") for (int m = 0; m < 4; ++m) _Pragma("unroll") for (int n = 0; n < 2; ++n) _Pragma("unroll") for (int k = 0; k < 2; ++k) \
;         acc[ai][bj][m][n] = __builtin_amdgcn_mfma_f32_16x16x32_bf16(Bt[n][k], At[m][k], acc[ai][bj][m][n], 0, 0, 0); __builtin_amdgcn_s_setprio(0); } while (0)
; #define PG8_WAIT_V(n) asm volatile("s_waitcnt vmcnt(" #n ")" ::: "memory")
; #define PG8_WAIT_L(n) asm volatile("s_waitcnt lgkmcnt(" #n ")" ::: "memory")
; #define PG8_BAR __builtin_amdgcn_s_barrier()
; #define PG8_SCHED __builtin_amdgcn_sched_barrier(0)
; template <class EpiT>
; __device__ __forceinline__ void gemm_phase(LAS unsigned char* lds, const Gemm g, const StaticOrder& S, const EpiT& E) {
;     ...
;             const bool last = (t == nt - 2);
;             const char* a1 = cA + (size_t)(t + 1) * kstep;
;             const char* a2 = last ? nA : cA + (size_t)(t + 2) * kstep; const char* b2 = last ? nB : cB + (size_t)(t + 2) * kstep;
;             const char* a3 = a2 + kstep; const char* b3 = b2 + kstep;
;             PG8_LDB(B0, 0, 0); PG8_LDB(B1, 0, 1); PG8_SCHED; PG8_LDA(At, 0, 0); PG8_STAGE(PG8_SA(1, 1), a1 + hstepA, voffA);
;             PG8_WAIT_V(8); PG8_WAIT_L(0); PG8_BAR; PG8_MMA(0, 0, At, B0); PG8_MMA(0, 1, At, B1); PG8_BAR; PG8_SCHED;
	ds_read_b128 v[154:157], v150
	ds_read_b128 v[158:161], v150 offset:1024
	ds_read_b128 v[162:165], v150 offset:2048
	ds_read_b128 v[170:173], v150 offset:3072
	ds_read_b128 v[174:177], v151
	ds_read_b128 v[178:181], v151 offset:1024
	ds_read_b128 v[182:185], v151 offset:2048
	ds_read_b128 v[186:189], v151 offset:3072
	s_add_u32 s18, s16, 0xfff7c080
	s_addc_u32 s19, s17, -1
	s_cmp_eq_u32 s53, 28
	s_cselect_b32 s21, s3, s19
	s_cselect_b32 s20, s2, s18
	s_cselect_b32 s19, s15, s52
	s_cselect_b32 s18, s14, s51
	v_lshl_add_u64 v[144:145], s[16:17], 0, v[136:137]
	s_add_i32 m0, s36, 0xc000
	ds_read_b128 v[190:193], v152
	ds_read_b128 v[194:197], v152 offset:1024
	ds_read_b128 v[198:201], v152 offset:2048
	ds_read_b128 v[202:205], v152 offset:3072
	ds_read_b128 v[206:209], v152 offset:4096
	ds_read_b128 v[210:213], v152 offset:5120
	ds_read_b128 v[214:217], v152 offset:6144
	ds_read_b128 v[218:221], v152 offset:7168
	global_load_lds_dwordx4 v[144:145], off
	v_lshl_add_u64 v[144:145], s[16:17], 0, v[138:139]
	s_add_i32 m0, s36, 0xe000
	s_nop 0
	global_load_lds_dwordx4 v[144:145], off
	s_waitcnt vmcnt(8)
	s_waitcnt lgkmcnt(0)
	s_barrier
	s_setprio 1
	s_waitcnt lgkmcnt(0)
	v_mfma_f32_16x16x32_bf16 v[124:127], v[154:157], v[190:193], v[124:127]
	v_mfma_f32_16x16x32_bf16 v[124:127], v[158:161], v[194:197], v[124:127]
	v_mfma_f32_16x16x32_bf16 v[108:111], v[154:157], v[198:201], v[108:111]
	v_mfma_f32_16x16x32_bf16 v[108:111], v[158:161], v[202:205], v[108:111]
	v_mfma_f32_16x16x32_bf16 v[92:95], v[154:157], v[206:209], v[92:95]
	v_mfma_f32_16x16x32_bf16 v[92:95], v[158:161], v[210:213], v[92:95]
	v_mfma_f32_16x16x32_bf16 v[76:79], v[154:157], v[214:217], v[76:79]
	v_mfma_f32_16x16x32_bf16 v[76:79], v[158:161], v[218:221], v[76:79]
	v_mfma_f32_16x16x32_bf16 v[120:123], v[162:165], v[190:193], v[120:123]
	v_mfma_f32_16x16x32_bf16 v[120:123], v[170:173], v[194:197], v[120:123]
	v_mfma_f32_16x16x32_bf16 v[104:107], v[162:165], v[198:201], v[104:107]
	v_mfma_f32_16x16x32_bf16 v[104:107], v[170:173], v[202:205], v[104:107]
	v_mfma_f32_16x16x32_bf16 v[88:91], v[162:165], v[206:209], v[88:91]
	v_mfma_f32_16x16x32_bf16 v[88:91], v[170:173], v[210:213], v[88:91]
	v_mfma_f32_16x16x32_bf16 v[72:75], v[162:165], v[214:217], v[72:75]
	v_mfma_f32_16x16x32_bf16 v[72:75], v[170:173], v[218:221], v[72:75]
	s_setprio 0
	s_setprio 1
	v_mfma_f32_16x16x32_bf16 v[116:119], v[174:177], v[190:193], v[116:119]
	v_mfma_f32_16x16x32_bf16 v[116:119], v[178:181], v[194:197], v[116:119]
	v_mfma_f32_16x16x32_bf16 v[100:103], v[174:177], v[198:201], v[100:103]
	v_mfma_f32_16x16x32_bf16 v[100:103], v[178:181], v[202:205], v[100:103]
	v_mfma_f32_16x16x32_bf16 v[84:87], v[174:177], v[206:209], v[84:87]
	v_mfma_f32_16x16x32_bf16 v[84:87], v[178:181], v[210:213], v[84:87]
	v_mfma_f32_16x16x32_bf16 v[68:71], v[174:177], v[214:217], v[68:71]
	v_mfma_f32_16x16x32_bf16 v[68:71], v[178:181], v[218:221], v[68:71]
	v_mfma_f32_16x16x32_bf16 v[112:115], v[182:185], v[190:193], v[112:115]
	v_mfma_f32_16x16x32_bf16 v[112:115], v[186:189], v[194:197], v[112:115]
	v_mfma_f32_16x16x32_bf16 v[96:99], v[182:185], v[198:201], v[96:99]
	v_mfma_f32_16x16x32_bf16 v[96:99], v[186:189], v[202:205], v[96:99]
	v_mfma_f32_16x16x32_bf16 v[80:83], v[182:185], v[206:209], v[80:83]
	v_mfma_f32_16x16x32_bf16 v[80:83], v[186:189], v[210:213], v[80:83]
	v_mfma_f32_16x16x32_bf16 v[64:67], v[182:185], v[214:217], v[64:67]
	v_mfma_f32_16x16x32_bf16 v[64:67], v[186:189], v[218:221], v[64:67]
	s_setprio 0
	s_barrier
	s_branch .Lrot_1156

; #define PG8_STAGE(bufoff, gbase, voff) do { _Pragma("unroll") for (int _i = 0; _i < 2; ++_i) \
;         __builtin_amdgcn_global_load_lds((const unsigned*)((const char*)(gbase) + (voff)[_i]), (LAS unsigned*)(lds + (bufoff) + ldsw + _i * 8192), 16, 0, 0); } while (0)
; #define PG8_LDA(dst, b, h) do { _Pragma("unroll") for (int m = 0; m < 4; ++m) _Pragma("unroll") for (int k = 0; k < 2; ++k) dst[m][k] = *(const LAS bf16x8*)(lds + PG8_SA(b, h) + aoff + m * 2048 + k * 1024); } while (0)
; #define PG8_LDB(dst, b, h) do { _Pragma("unroll") for (int n = 0; n < 2; ++n) _Pragma("unroll") for (int k = 0; k < 2; ++k) dst[n][k] = *(const LAS bf16x8*)(lds + PG8_SB(b, h) + boff + n * 2048 + k * 1024); } while (0)
; #define PG8_MMA(ai, bj, At, Bt) do { __builtin_amdgcn_s_setprio(1); _Pragma("unroll") for (int m = 0; m < 4; ++m) _Pragma("unroll") for (int n = 0; n < 2; ++n) _Pragma("unroll") for (int k = 0; k < 2; ++k) \
;         acc[ai][bj][m][n] = __builtin_amdgcn_mfma_f32_16x16x32_bf16(Bt[n][k], At[m][k], acc[ai][bj][m][n], 0, 0, 0); __builtin_amdgcn_s_setprio(0); } while (0)
; #define PG8_WAIT_V(n) asm volatile("s_waitcnt vmcnt(" #n ")" ::: "memory")
; #define PG8_WAIT_L(n) asm volatile("s_waitcnt lgkmcnt(" #n ")" ::: "memory")
; #define PG8_BAR __builtin_amdgcn_s_barrier()
; #define PG8_SCHED __builtin_amdgcn_sched_barrier(0)
; template <class EpiT>
; __device__ __forceinline__ void gemm_phase(LAS unsigned char* lds, const Gemm g, const StaticOrder& S, const EpiT& E) {
;     ...
;             const bool last = (t == nt - 2);
;             const char* a1 = cA + (size_t)(t + 1) * kstep;
;             const char* a2 = last ? nA : cA + (size_t)(t + 2) * kstep; const char* b2 = last ? nB : cB + (size_t)(t + 2) * kstep;
;             const char* a3 = a2 + kstep; const char* b3 = b2 + kstep;
;             PG8_LDB(B0, 0, 0); PG8_LDB(B1, 0, 1); PG8_SCHED; PG8_LDA(At, 0, 0); PG8_STAGE(PG8_SA(1, 1), a1 + hstepA, voffA);
;             PG8_WAIT_V(8); PG8_WAIT_L(0); PG8_BAR; PG8_MMA(0, 0, At, B0); PG8_MMA(0, 1, At, B1); PG8_BAR; PG8_SCHED;
;             PG8_LDA(At, 0, 1); PG8_STAGE(PG8_SB(0, 0), b2, voffB); PG8_STAGE(PG8_SB(0, 1), b2 + hstepB, voffB); PG8_STAGE(PG8_SA(0, 0), a2, voffA);
.LBB0_1235:
	ds_read_b128 v[154:157], v150
	ds_read_b128 v[158:161], v150 offset:1024
	ds_read_b128 v[162:165], v150 offset:2048
	ds_read_b128 v[170:173], v150 offset:3072
	ds_read_b128 v[174:177], v151
	ds_read_b128 v[178:181], v151 offset:1024
	ds_read_b128 v[182:185], v151 offset:2048
	ds_read_b128 v[186:189], v151 offset:3072
	s_add_u32 s20, s18, 0xffe9c080
	s_addc_u32 s21, s19, -1
	s_cmpk_eq_i32 s55, 0x54
	s_cselect_b32 s23, s5, s21
	s_cselect_b32 s22, s4, s20
	s_cselect_b32 s21, s17, s54
	s_cselect_b32 s20, s16, s53
	v_lshl_add_u64 v[166:167], s[18:19], 0, v[138:139]
	s_add_i32 m0, s37, 0xc000
	ds_read_b128 v[190:193], v152
	ds_read_b128 v[194:197], v152 offset:1024
	ds_read_b128 v[198:201], v152 offset:2048
	ds_read_b128 v[202:205], v152 offset:3072
	ds_read_b128 v[206:209], v152 offset:4096
	ds_read_b128 v[210:213], v152 offset:5120
	ds_read_b128 v[214:217], v152 offset:6144
	ds_read_b128 v[218:221], v152 offset:7168
	global_load_lds_dwordx4 v[166:167], off
	v_lshl_add_u64 v[166:167], s[18:19], 0, v[140:141]
	s_add_i32 m0, s37, 0xe000
	s_nop 0
	global_load_lds_dwordx4 v[166:167], off
	s_waitcnt vmcnt(8)
	s_waitcnt lgkmcnt(0)
	s_barrier
	s_setprio 1
	s_waitcnt lgkmcnt(0)
	v_mfma_f32_16x16x32_bf16 v[124:127], v[154:157], v[190:193], v[124:127]
	v_mfma_f32_16x16x32_bf16 v[124:127], v[158:161], v[194:197], v[124:127]
	v_mfma_f32_16x16x32_bf16 v[108:111], v[154:157], v[198:201], v[108:111]
	v_mfma_f32_16x16x32_bf16 v[108:111], v[158:161], v[202:205], v[108:111]
	v_mfma_f32_16x16x32_bf16 v[92:95], v[154:157], v[206:209], v[92:95]
	v_mfma_f32_16x16x32_bf16 v[92:95], v[158:161], v[210:213], v[92:95]
	v_mfma_f32_16x16x32_bf16 v[76:79], v[154:157], v[214:217], v[76:79]
	v_mfma_f32_16x16x32_bf16 v[76:79], v[158:161], v[218:221], v[76:79]
	v_mfma_f32_16x16x32_bf16 v[120:123], v[162:165], v[190:193], v[120:123]
	v_mfma_f32_16x16x32_bf16 v[120:123], v[170:173], v[194:197], v[120:123]
	v_mfma_f32_16x16x32_bf16 v[104:107], v[162:165], v[198:201], v[104:107]
	v_mfma_f32_16x16x32_bf16 v[104:107], v[170:173], v[202:205], v[104:107]
	v_mfma_f32_16x16x32_bf16 v[88:91], v[162:165], v[206:209], v[88:91]
	v_mfma_f32_16x16x32_bf16 v[88:91], v[170:173], v[210:213], v[88:91]
	v_mfma_f32_16x16x32_bf16 v[72:75], v[162:165], v[214:217], v[72:75]
	v_mfma_f32_16x16x32_bf16 v[72:75], v[170:173], v[218:221], v[72:75]
	s_setprio 0
	s_setprio 1
	v_mfma_f32_16x16x32_bf16 v[116:119], v[174:177], v[190:193], v[116:119]
	v_mfma_f32_16x16x32_bf16 v[116:119], v[178:181], v[194:197], v[116:119]
	v_mfma_f32_16x16x32_bf16 v[100:103], v[174:177], v[198:201], v[100:103]
	v_mfma_f32_16x16x32_bf16 v[100:103], v[178:181], v[202:205], v[100:103]
	v_mfma_f32_16x16x32_bf16 v[84:87], v[174:177], v[206:209], v[84:87]
	v_mfma_f32_16x16x32_bf16 v[84:87], v[178:181], v[210:213], v[84:87]
	v_mfma_f32_16x16x32_bf16 v[68:71], v[174:177], v[214:217], v[68:71]
	v_mfma_f32_16x16x32_bf16 v[68:71], v[178:181], v[218:221], v[68:71]
	v_mfma_f32_16x16x32_bf16 v[112:115], v[182:185], v[190:193], v[112:115]
	v_mfma_f32_16x16x32_bf16 v[112:115], v[186:189], v[194:197], v[112:115]
	v_mfma_f32_16x16x32_bf16 v[96:99], v[182:185], v[198:201], v[96:99]
	v_mfma_f32_16x16x32_bf16 v[96:99], v[186:189], v[202:205], v[96:99]
	v_mfma_f32_16x16x32_bf16 v[80:83], v[182:185], v[206:209], v[80:83]
	v_mfma_f32_16x16x32_bf16 v[80:83], v[186:189], v[210:213], v[80:83]
	v_mfma_f32_16x16x32_bf16 v[64:67], v[182:185], v[214:217], v[64:67]
	v_mfma_f32_16x16x32_bf16 v[64:67], v[186:189], v[218:221], v[64:67]
	s_setprio 0
	s_barrier
.Lrot_1235:
	s_add_i32 s56, s46, s36
	v_lshl_add_u64 v[166:167], s[20:21], 0, v[130:131]
	s_mov_b32 m0, s56
	ds_read_b128 v[190:193], v152 offset:16384
	ds_read_b128 v[194:197], v152 offset:17408
	ds_read_b128 v[198:201], v152 offset:18432
	ds_read_b128 v[202:205], v152 offset:19456
	ds_read_b128 v[206:209], v152 offset:20480
	ds_read_b128 v[210:213], v152 offset:21504
	ds_read_b128 v[214:217], v152 offset:22528
	ds_read_b128 v[218:221], v152 offset:23552
	global_load_lds_dwordx4 v[166:167], off
	s_add_i32 m0, s56, 0x2000
	s_add_u32 s56, s20, 0x164000
	v_lshl_add_u64 v[222:223], s[20:21], 0, v[134:135]
	s_addc_u32 s57, s21, 0
	s_add_i32 s58, s47, s36
	global_load_lds_dwordx4 v[222:223], off
	v_lshl_add_u64 v[224:225], s[56:57], 0, v[130:131]
	s_mov_b32 m0, s58
	v_lshl_add_u64 v[226:227], s[22:23], 0, v[132:133]
	global_load_lds_dwordx4 v[224:225], off
	v_lshl_add_u64 v[224:225], s[56:57], 0, v[134:135]
	s_add_i32 m0, s58, 0x2000
	s_nop 0
	global_load_lds_dwordx4 v[224:225], off
	v_lshl_add_u64 v[224:225], s[22:23], 0, v[128:129]
	s_mov_b32 m0, s37
	s_nop 0
	global_load_lds_dwordx4 v[224:225], off
	s_mov_b32 m0, s38
	s_nop 0
	global_load_lds_dwordx4 v[226:227], off
	s_waitcnt vmcnt(8)
	s_waitcnt lgkmcnt(0)
	s_barrier
; #define PG8_STAGE(bufoff, gbase, voff) do { _Pragma("unroll") for (int _i = 0; _i < 2; ++_i) \
;         __builtin_amdgcn_global_load_lds((const unsigned*)((const char*)(gbase) + (voff)[_i]), (LAS unsigned*)(lds + (bufoff) + ldsw + _i * 8192), 16, 0, 0); } while (0)
; #define PG8_LDA(dst, b, h) do { _Pragma("unroll") for (int m = 0; m < 4; ++m) _Pragma("unroll") for (int k = 0; k < 2; ++k) dst[m][k] = *(const LAS bf16x8*)(lds + PG8_SA(b, h) + aoff + m * 2048 + k * 1024); } while (0)
; #define PG8_LDB(dst, b, h) do { _Pragma("unroll") for (int n = 0; n < 2; ++n) _Pragma("unroll") for (int k = 0; k < 2; ++k) dst[n][k] = *(const LAS bf16x8*)(lds + PG8_SB(b, h) + boff + n * 2048 + k * 1024); } while (0)
; #define PG8_MMA(ai, bj, At, Bt) do { __builtin_amdgcn_s_setprio(1); _Pragma("unroll") for (int m = 0; m < 4; ++m) _Pragma("unroll") for (int n = 0; n < 2; ++n) _Pragma("unroll") for (int k = 0; k < 2; ++k) \
;         acc[ai][bj][m][n] = __builtin_amdgcn_mfma_f32_16x16x32_bf16(Bt[n][k], At[m][k], acc[ai][bj][m][n], 0, 0, 0); __builtin_amdgcn_s_setprio(0); } while (0)
; #define PG8_WAIT_V(n) asm volatile("s_waitcnt vmcnt(" #n ")" ::: "memory")
; #define PG8_WAIT_L(n) asm volatile("s_waitcnt lgkmcnt(" #n ")" ::: "memory")
; #define PG8_BAR __builtin_amdgcn_s_barrier()
; #define PG8_SCHED __builtin_amdgcn_sched_barrier(0)
; template <class EpiT>
; __device__ __forceinline__ void gemm_phase(LAS unsigned char* lds, const Gemm g, const StaticOrder& S, const EpiT& E) {
;     ...
;             PG8_WAIT_V(8); PG8_WAIT_L(0); PG8_BAR; PG8_MMA(1, 0, At, B0); PG8_MMA(1, 1, At, B1); PG8_BAR; PG8_SCHED;
;             PG8_LDB(B0, 1, 0); PG8_LDB(B1, 1, 1); PG8_SCHED; PG8_LDA(At, 1, 0); PG8_STAGE(PG8_SA(0, 1), a2 + hstepA, voffA);
;             PG8_WAIT_V(8); PG8_WAIT_L(0); PG8_BAR; PG8_MMA(0, 0, At, B0); PG8_MMA(0, 1, At, B1); PG8_BAR; PG8_SCHED;
	s_setprio 1
	s_waitcnt lgkmcnt(0)
	v_mfma_f32_16x16x32_bf16 v[60:63], v[154:157], v[190:193], v[60:63]
	v_mfma_f32_16x16x32_bf16 v[60:63], v[158:161], v[194:197], v[60:63]
	v_mfma_f32_16x16x32_bf16 v[44:47], v[154:157], v[198:201], v[44:47]
	v_mfma_f32_16x16x32_bf16 v[44:47], v[158:161], v[202:205], v[44:47]
	v_mfma_f32_16x16x32_bf16 v[28:31], v[154:157], v[206:209], v[28:31]
	v_mfma_f32_16x16x32_bf16 v[28:31], v[158:161], v[210:213], v[28:31]
	v_mfma_f32_16x16x32_bf16 v[12:15], v[154:157], v[214:217], v[12:15]
	v_mfma_f32_16x16x32_bf16 v[12:15], v[158:161], v[218:221], v[12:15]
	v_mfma_f32_16x16x32_bf16 v[56:59], v[162:165], v[190:193], v[56:59]
	v_mfma_f32_16x16x32_bf16 v[56:59], v[170:173], v[194:197], v[56:59]
	v_mfma_f32_16x16x32_bf16 v[40:43], v[162:165], v[198:201], v[40:43]
	v_mfma_f32_16x16x32_bf16 v[40:43], v[170:173], v[202:205], v[40:43]
	v_mfma_f32_16x16x32_bf16 v[24:27], v[162:165], v[206:209], v[24:27]
	v_mfma_f32_16x16x32_bf16 v[24:27], v[170:173], v[210:213], v[24:27]
	v_mfma_f32_16x16x32_bf16 v[8:11], v[162:165], v[214:217], v[8:11]
	v_mfma_f32_16x16x32_bf16 v[8:11], v[170:173], v[218:221], v[8:11]
	s_setprio 0
	s_setprio 1
	v_mfma_f32_16x16x32_bf16 v[52:55], v[174:177], v[190:193], v[52:55]
	v_mfma_f32_16x16x32_bf16 v[52:55], v[178:181], v[194:197], v[52:55]
	v_mfma_f32_16x16x32_bf16 v[36:39], v[174:177], v[198:201], v[36:39]
	v_mfma_f32_16x16x32_bf16 v[36:39], v[178:181], v[202:205], v[36:39]
	v_mfma_f32_16x16x32_bf16 v[20:23], v[174:177], v[206:209], v[20:23]
	v_mfma_f32_16x16x32_bf16 v[20:23], v[178:181], v[210:213], v[20:23]
	v_mfma_f32_16x16x32_bf16 v[4:7], v[174:177], v[214:217], v[4:7]
	v_mfma_f32_16x16x32_bf16 v[4:7], v[178:181], v[218:221], v[4:7]
	v_mfma_f32_16x16x32_bf16 v[48:51], v[182:185], v[190:193], v[48:51]
	v_mfma_f32_16x16x32_bf16 v[48:51], v[186:189], v[194:197], v[48:51]
	v_mfma_f32_16x16x32_bf16 v[32:35], v[182:185], v[198:201], v[32:35]
	v_mfma_f32_16x16x32_bf16 v[32:35], v[186:189], v[202:205], v[32:35]
	v_mfma_f32_16x16x32_bf16 v[16:19], v[182:185], v[206:209], v[16:19]
	v_mfma_f32_16x16x32_bf16 v[16:19], v[186:189], v[210:213], v[16:19]
	v_mfma_f32_16x16x32_bf16 v[0:3], v[182:185], v[214:217], v[0:3]
	v_mfma_f32_16x16x32_bf16 v[0:3], v[186:189], v[218:221], v[0:3]
	s_setprio 0
	s_barrier
	s_add_i32 s56, 0, 0x18000
	s_add_i32 s57, 0, 0x1c000
	v_add_u32_e32 v170, s56, v146
	v_add_u32_e32 v186, s57, v146
	ds_read_b128 v[154:157], v170
	ds_read_b128 v[158:161], v170 offset:1024
	ds_read_b128 v[162:165], v170 offset:2048
	ds_read_b128 v[170:173], v170 offset:3072
	ds_read_b128 v[174:177], v186
	ds_read_b128 v[178:181], v186 offset:1024
	ds_read_b128 v[182:185], v186 offset:2048
	ds_read_b128 v[186:189], v186 offset:3072
	s_add_u32 s22, s22, 0x164000
	s_addc_u32 s23, s23, 0
	s_mov_b32 m0, s39
	v_lshl_add_u64 v[228:229], s[22:23], 0, v[128:129]
	ds_read_b128 v[190:193], v152 offset:32768
	ds_read_b128 v[194:197], v152 offset:33792
	ds_read_b128 v[198:201], v152 offset:34816
	ds_read_b128 v[202:205], v152 offset:35840
	ds_read_b128 v[206:209], v152 offset:36864
	ds_read_b128 v[210:213], v152 offset:37888
	ds_read_b128 v[214:217], v152 offset:38912
	ds_read_b128 v[218:221], v152 offset:39936
	global_load_lds_dwordx4 v[228:229], off
	v_lshl_add_u64 v[228:229], s[22:23], 0, v[132:133]
	s_mov_b32 m0, s40
	s_nop 0
	global_load_lds_dwordx4 v[228:229], off
	s_waitcnt vmcnt(8)
	s_waitcnt lgkmcnt(0)
	s_barrier
	s_setprio 1
	s_waitcnt lgkmcnt(0)
	v_mfma_f32_16x16x32_bf16 v[124:127], v[154:157], v[190:193], v[124:127]
	v_mfma_f32_16x16x32_bf16 v[124:127], v[158:161], v[194:197], v[124:127]
	v_mfma_f32_16x16x32_bf16 v[108:111], v[154:157], v[198:201], v[108:111]
	v_mfma_f32_16x16x32_bf16 v[108:111], v[158:161], v[202:205], v[108:111]
	v_mfma_f32_16x16x32_bf16 v[92:95], v[154:157], v[206:209], v[92:95]
	v_mfma_f32_16x16x32_bf16 v[92:95], v[158:161], v[210:213], v[92:95]
	v_mfma_f32_16x16x32_bf16 v[76:79], v[154:157], v[214:217], v[76:79]
	v_mfma_f32_16x16x32_bf16 v[76:79], v[158:161], v[218:221], v[76:79]
	v_mfma_f32_16x16x32_bf16 v[120:123], v[162:165], v[190:193], v[120:123]
	v_mfma_f32_16x16x32_bf16 v[120:123], v[170:173], v[194:197], v[120:123]
	v_mfma_f32_16x16x32_bf16 v[104:107], v[162:165], v[198:201], v[104:107]
	v_mfma_f32_16x16x32_bf16 v[104:107], v[170:173], v[202:205], v[104:107]
	v_mfma_f32_16x16x32_bf16 v[88:91], v[162:165], v[206:209], v[88:91]
	v_mfma_f32_16x16x32_bf16 v[88:91], v[170:173], v[210:213], v[88:91]
	v_mfma_f32_16x16x32_bf16 v[72:75], v[162:165], v[214:217], v[72:75]
	v_mfma_f32_16x16x32_bf16 v[72:75], v[170:173], v[218:221], v[72:75]
	s_setprio 0
	s_setprio 1
	v_mfma_f32_16x16x32_bf16 v[116:119], v[174:177], v[190:193], v[116:119]
	v_mfma_f32_16x16x32_bf16 v[116:119], v[178:181], v[194:197], v[116:119]
	v_mfma_f32_16x16x32_bf16 v[100:103], v[174:177], v[198:201], v[100:103]
	v_mfma_f32_16x16x32_bf16 v[100:103], v[178:181], v[202:205], v[100:103]
	v_mfma_f32_16x16x32_bf16 v[84:87], v[174:177], v[206:209], v[84:87]
	v_mfma_f32_16x16x32_bf16 v[84:87], v[178:181], v[210:213], v[84:87]
	v_mfma_f32_16x16x32_bf16 v[68:71], v[174:177], v[214:217], v[68:71]
	v_mfma_f32_16x16x32_bf16 v[68:71], v[178:181], v[218:221], v[68:71]
	v_mfma_f32_16x16x32_bf16 v[112:115], v[182:185], v[190:193], v[112:115]
	v_mfma_f32_16x16x32_bf16 v[112:115], v[186:189], v[194:197], v[112:115]
	v_mfma_f32_16x16x32_bf16 v[96:99], v[182:185], v[198:201], v[96:99]
	v_mfma_f32_16x16x32_bf16 v[96:99], v[186:189], v[202:205], v[96:99]
	v_mfma_f32_16x16x32_bf16 v[80:83], v[182:185], v[206:209], v[80:83]
	v_mfma_f32_16x16x32_bf16 v[80:83], v[186:189], v[210:213], v[80:83]
	v_mfma_f32_16x16x32_bf16 v[64:67], v[182:185], v[214:217], v[64:67]
	v_mfma_f32_16x16x32_bf16 v[64:67], v[186:189], v[218:221], v[64:67]
	s_setprio 0
	s_barrier
; #define PG8_STAGE(bufoff, gbase, voff) do { _Pragma("unroll") for (int _i = 0; _i < 2; ++_i) \
;         __builtin_amdgcn_global_load_lds((const unsigned*)((const char*)(gbase) + (voff)[_i]), (LAS unsigned*)(lds + (bufoff) + ldsw + _i * 8192), 16, 0, 0); } while (0)
; #define PG8_LDA(dst, b, h) do { _Pragma("unroll") for (int m = 0; m < 4; ++m) _Pragma("unroll") for (int k = 0; k < 2; ++k) dst[m][k] = *(const LAS bf16x8*)(lds + PG8_SA(b, h) + aoff + m * 2048 + k * 1024); } while (0)
; #define PG8_MMA(ai, bj, At, Bt) do { __builtin_amdgcn_s_setprio(1); _Pragma("unroll") for (int m = 0; m < 4; ++m) _Pragma("unroll") for (int n = 0; n < 2; ++n) _Pragma("unroll") for (int k = 0; k < 2; ++k) \
;         acc[ai][bj][m][n] = __builtin_amdgcn_mfma_f32_16x16x32_bf16(Bt[n][k], At[m][k], acc[ai][bj][m][n], 0, 0, 0); __builtin_amdgcn_s_setprio(0); } while (0)
; #define PG8_WAIT_V(n) asm volatile("s_waitcnt vmcnt(" #n ")" ::: "memory")
; #define PG8_WAIT_L(n) asm volatile("s_waitcnt lgkmcnt(" #n ")" ::: "memory")
; #define PG8_BAR __builtin_amdgcn_s_barrier()
; #define PG8_SCHED __builtin_amdgcn_sched_barrier(0)
; template <class EpiT>
; __device__ __forceinline__ void gemm_phase(LAS unsigned char* lds, const Gemm g, const StaticOrder& S, const EpiT& E) {
;     ...
;         for (int t = 0; t < nt; t += 2) {
;     ...
;             PG8_LDA(At, 1, 1); PG8_STAGE(PG8_SB(1, 0), b3, voffB); PG8_STAGE(PG8_SB(1, 1), b3 + hstepB, voffB); PG8_STAGE(PG8_SA(1, 0), a3, voffA);
;             PG8_WAIT_V(8); PG8_WAIT_L(0); PG8_BAR; PG8_MMA(1, 0, At, B0); PG8_MMA(1, 1, At, B1); PG8_BAR; PG8_SCHED;
;         }
	s_add_i32 s22, s56, s36
	v_lshl_add_u64 v[166:167], v[166:167], 0, s[12:13]
	s_mov_b32 m0, s22
	ds_read_b128 v[190:193], v152 offset:49152
	ds_read_b128 v[194:197], v152 offset:50176
	ds_read_b128 v[198:201], v152 offset:51200
	ds_read_b128 v[202:205], v152 offset:52224
	ds_read_b128 v[206:209], v152 offset:53248
	ds_read_b128 v[210:213], v152 offset:54272
	ds_read_b128 v[214:217], v152 offset:55296
	ds_read_b128 v[218:221], v152 offset:56320
	global_load_lds_dwordx4 v[166:167], off
	s_add_i32 m0, s22, 0x2000
	s_add_u32 s20, s20, 0x164080
	v_lshl_add_u64 v[166:167], v[222:223], 0, s[12:13]
	s_addc_u32 s21, s21, 0
	s_add_i32 s22, s57, s36
	global_load_lds_dwordx4 v[166:167], off
	v_lshl_add_u64 v[166:167], s[20:21], 0, v[130:131]
	s_mov_b32 m0, s22
	s_nop 0
	global_load_lds_dwordx4 v[166:167], off
	v_lshl_add_u64 v[166:167], s[20:21], 0, v[134:135]
	s_add_i32 m0, s22, 0x2000
	s_nop 0
	global_load_lds_dwordx4 v[166:167], off
	v_lshl_add_u64 v[166:167], v[224:225], 0, s[12:13]
	s_mov_b32 m0, s42
	s_nop 0
	global_load_lds_dwordx4 v[166:167], off
	v_lshl_add_u64 v[166:167], v[226:227], 0, s[12:13]
	s_mov_b32 m0, s43
	s_nop 0
	global_load_lds_dwordx4 v[166:167], off
	s_waitcnt vmcnt(8)
	s_waitcnt lgkmcnt(0)
	s_barrier
	s_setprio 1
	s_waitcnt lgkmcnt(0)
	v_mfma_f32_16x16x32_bf16 v[60:63], v[154:157], v[190:193], v[60:63]
	v_mfma_f32_16x16x32_bf16 v[60:63], v[158:161], v[194:197], v[60:63]
	v_mfma_f32_16x16x32_bf16 v[44:47], v[154:157], v[198:201], v[44:47]
	v_mfma_f32_16x16x32_bf16 v[44:47], v[158:161], v[202:205], v[44:47]
	v_mfma_f32_16x16x32_bf16 v[28:31], v[154:157], v[206:209], v[28:31]
	v_mfma_f32_16x16x32_bf16 v[28:31], v[158:161], v[210:213], v[28:31]
	v_mfma_f32_16x16x32_bf16 v[12:15], v[154:157], v[214:217], v[12:15]
	v_mfma_f32_16x16x32_bf16 v[12:15], v[158:161], v[218:221], v[12:15]
	v_mfma_f32_16x16x32_bf16 v[56:59], v[162:165], v[190:193], v[56:59]
	v_mfma_f32_16x16x32_bf16 v[56:59], v[170:173], v[194:197], v[56:59]
	v_mfma_f32_16x16x32_bf16 v[40:43], v[162:165], v[198:201], v[40:43]
	v_mfma_f32_16x16x32_bf16 v[40:43], v[170:173], v[202:205], v[40:43]
	v_mfma_f32_16x16x32_bf16 v[24:27], v[162:165], v[206:209], v[24:27]
	v_mfma_f32_16x16x32_bf16 v[24:27], v[170:173], v[210:213], v[24:27]
	v_mfma_f32_16x16x32_bf16 v[8:11], v[162:165], v[214:217], v[8:11]
	v_mfma_f32_16x16x32_bf16 v[8:11], v[170:173], v[218:221], v[8:11]
	s_setprio 0
	s_setprio 1
	v_mfma_f32_16x16x32_bf16 v[52:55], v[174:177], v[190:193], v[52:55]
	v_mfma_f32_16x16x32_bf16 v[52:55], v[178:181], v[194:197], v[52:55]
	v_mfma_f32_16x16x32_bf16 v[36:39], v[174:177], v[198:201], v[36:39]
	v_mfma_f32_16x16x32_bf16 v[36:39], v[178:181], v[202:205], v[36:39]
	v_mfma_f32_16x16x32_bf16 v[20:23], v[174:177], v[206:209], v[20:23]
	v_mfma_f32_16x16x32_bf16 v[20:23], v[178:181], v[210:213], v[20:23]
	v_mfma_f32_16x16x32_bf16 v[4:7], v[174:177], v[214:217], v[4:7]
	v_mfma_f32_16x16x32_bf16 v[4:7], v[178:181], v[218:221], v[4:7]
	v_mfma_f32_16x16x32_bf16 v[48:51], v[182:185], v[190:193], v[48:51]
	v_mfma_f32_16x16x32_bf16 v[48:51], v[186:189], v[194:197], v[48:51]
	v_mfma_f32_16x16x32_bf16 v[32:35], v[182:185], v[198:201], v[32:35]
	v_mfma_f32_16x16x32_bf16 v[32:35], v[186:189], v[202:205], v[32:35]
	v_mfma_f32_16x16x32_bf16 v[16:19], v[182:185], v[206:209], v[16:19]
	v_mfma_f32_16x16x32_bf16 v[16:19], v[186:189], v[210:213], v[16:19]
	v_mfma_f32_16x16x32_bf16 v[0:3], v[182:185], v[214:217], v[0:3]
	v_mfma_f32_16x16x32_bf16 v[0:3], v[186:189], v[218:221], v[0:3]
	s_setprio 0
	s_barrier
	s_add_i32 s55, s55, 2
	s_add_u32 s18, s18, 0x100
	s_addc_u32 s19, s19, 0
	s_add_u32 s53, s53, 0x100
	s_addc_u32 s54, s54, 0
	s_cmpk_gt_u32 s55, 0x55
	s_cbranch_scc1 .Lrot_done_1235
; #define PG8_STAGE(bufoff, gbase, voff) do { _Pragma("unroll") for (int _i = 0; _i < 2; ++_i) \
;         __builtin_amdgcn_global_load_lds((const unsigned*)((const char*)(gbase) + (voff)[_i]), (LAS unsigned*)(lds + (bufoff) + ldsw + _i * 8192), 16, 0, 0); } while (0)
; #define PG8_LDA(dst, b, h) do { _Pragma("unroll") for (int m = 0; m < 4; ++m) _Pragma("unroll") for (int k = 0; k < 2; ++k) dst[m][k] = *(const LAS bf16x8*)(lds + PG8_SA(b, h) + aoff + m * 2048 + k * 1024); } while (0)
; #define PG8_LDB(dst, b, h) do { _Pragma("unroll") for (int n = 0; n < 2; ++n) _Pragma("unroll") for (int k = 0; k < 2; ++k) dst[n][k] = *(const LAS bf16x8*)(lds + PG8_SB(b, h) + boff + n * 2048 + k * 1024); } while (0)
; #define PG8_MMA(ai, bj, At, Bt) do { __builtin_amdgcn_s_setprio(1); _Pragma("unroll") for (int m = 0; m < 4; ++m) _Pragma("unroll") for (int n = 0; n < 2; ++n) _Pragma("unroll") for (int k = 0; k < 2; ++k) \
;         acc[ai][bj][m][n] = __builtin_amdgcn_mfma_f32_16x16x32_bf16(Bt[n][k], At[m][k], acc[ai][bj][m][n], 0, 0, 0); __builtin_amdgcn_s_setprio(0); } while (0)
; #define PG8_WAIT_V(n) asm volatile("s_waitcnt vmcnt(" #n ")" ::: "memory")
; #define PG8_WAIT_L(n) asm volatile("s_waitcnt lgkmcnt(" #n ")" ::: "memory")
; #define PG8_BAR __builtin_amdgcn_s_barrier()
; #define PG8_SCHED __builtin_amdgcn_sched_barrier(0)
; template <class EpiT>
; __device__ __forceinline__ void gemm_phase(LAS unsigned char* lds, const Gemm g, const StaticOrder& S, const EpiT& E) {
;     ...
;             const bool last = (t == nt - 2);
;             const char* a1 = cA + (size_t)(t + 1) * kstep;
;             const char* a2 = last ? nA : cA + (size_t)(t + 2) * kstep; const char* b2 = last ? nB : cB + (size_t)(t + 2) * kstep;
;             const char* a3 = a2 + kstep; const char* b3 = b2 + kstep;
;             PG8_LDB(B0, 0, 0); PG8_LDB(B1, 0, 1); PG8_SCHED; PG8_LDA(At, 0, 0); PG8_STAGE(PG8_SA(1, 1), a1 + hstepA, voffA);
;             PG8_WAIT_V(8); PG8_WAIT_L(0); PG8_BAR; PG8_MMA(0, 0, At, B0); PG8_MMA(0, 1, At, B1); PG8_BAR; PG8_SCHED;
	ds_read_b128 v[154:157], v150
	ds_read_b128 v[158:161], v150 offset:1024
	ds_read_b128 v[162:165], v150 offset:2048
	ds_read_b128 v[170:173], v150 offset:3072
	ds_read_b128 v[174:177], v151
	ds_read_b128 v[178:181], v151 offset:1024
	ds_read_b128 v[182:185], v151 offset:2048
	ds_read_b128 v[186:189], v151 offset:3072
	s_add_u32 s20, s18, 0xffe9c080
	s_addc_u32 s21, s19, -1
	s_cmpk_eq_i32 s55, 0x54
	s_cselect_b32 s23, s5, s21
	s_cselect_b32 s22, s4, s20
	s_cselect_b32 s21, s17, s54
	s_cselect_b32 s20, s16, s53
	v_lshl_add_u64 v[166:167], s[18:19], 0, v[138:139]
	s_add_i32 m0, s37, 0xc000
	ds_read_b128 v[190:193], v152
	ds_read_b128 v[194:197], v152 offset:1024
	ds_read_b128 v[198:201], v152 offset:2048
	ds_read_b128 v[202:205], v152 offset:3072
	ds_read_b128 v[206:209], v152 offset:4096
	ds_read_b128 v[210:213], v152 offset:5120
	ds_read_b128 v[214:217], v152 offset:6144
	ds_read_b128 v[218:221], v152 offset:7168
	global_load_lds_dwordx4 v[166:167], off
	v_lshl_add_u64 v[166:167], s[18:19], 0, v[140:141]
	s_add_i32 m0, s37, 0xe000
	s_nop 0
	global_load_lds_dwordx4 v[166:167], off
	s_waitcnt vmcnt(8)
	s_waitcnt lgkmcnt(0)
	s_barrier
	s_setprio 1
	s_waitcnt lgkmcnt(0)
	v_mfma_f32_16x16x32_bf16 v[124:127], v[154:157], v[190:193], v[124:127]
	v_mfma_f32_16x16x32_bf16 v[124:127], v[158:161], v[194:197], v[124:127]
	v_mfma_f32_16x16x32_bf16 v[108:111], v[154:157], v[198:201], v[108:111]
	v_mfma_f32_16x16x32_bf16 v[108:111], v[158:161], v[202:205], v[108:111]
	v_mfma_f32_16x16x32_bf16 v[92:95], v[154:157], v[206:209], v[92:95]
	v_mfma_f32_16x16x32_bf16 v[92:95], v[158:161], v[210:213], v[92:95]
	v_mfma_f32_16x16x32_bf16 v[76:79], v[154:157], v[214:217], v[76:79]
	v_mfma_f32_16x16x32_bf16 v[76:79], v[158:161], v[218:221], v[76:79]
	v_mfma_f32_16x16x32_bf16 v[120:123], v[162:165], v[190:193], v[120:123]
	v_mfma_f32_16x16x32_bf16 v[120:123], v[170:173], v[194:197], v[120:123]
	v_mfma_f32_16x16x32_bf16 v[104:107], v[162:165], v[198:201], v[104:107]
	v_mfma_f32_16x16x32_bf16 v[104:107], v[170:173], v[202:205], v[104:107]
	v_mfma_f32_16x16x32_bf16 v[88:91], v[162:165], v[206:209], v[88:91]
	v_mfma_f32_16x16x32_bf16 v[88:91], v[170:173], v[210:213], v[88:91]
	v_mfma_f32_16x16x32_bf16 v[72:75], v[162:165], v[214:217], v[72:75]
	v_mfma_f32_16x16x32_bf16 v[72:75], v[170:173], v[218:221], v[72:75]
	s_setprio 0
	s_setprio 1
	v_mfma_f32_16x16x32_bf16 v[116:119], v[174:177], v[190:193], v[116:119]
	v_mfma_f32_16x16x32_bf16 v[116:119], v[178:181], v[194:197], v[116:119]
	v_mfma_f32_16x16x32_bf16 v[100:103], v[174:177], v[198:201], v[100:103]
	v_mfma_f32_16x16x32_bf16 v[100:103], v[178:181], v[202:205], v[100:103]
	v_mfma_f32_16x16x32_bf16 v[84:87], v[174:177], v[206:209], v[84:87]
	v_mfma_f32_16x16x32_bf16 v[84:87], v[178:181], v[210:213], v[84:87]
	v_mfma_f32_16x16x32_bf16 v[68:71], v[174:177], v[214:217], v[68:71]
	v_mfma_f32_16x16x32_bf16 v[68:71], v[178:181], v[218:221], v[68:71]
	v_mfma_f32_16x16x32_bf16 v[112:115], v[182:185], v[190:193], v[112:115]
	v_mfma_f32_16x16x32_bf16 v[112:115], v[186:189], v[194:197], v[112:115]
	v_mfma_f32_16x16x32_bf16 v[96:99], v[182:185], v[198:201], v[96:99]
	v_mfma_f32_16x16x32_bf16 v[96:99], v[186:189], v[202:205], v[96:99]
	v_mfma_f32_16x16x32_bf16 v[80:83], v[182:185], v[206:209], v[80:83]
	v_mfma_f32_16x16x32_bf16 v[80:83], v[186:189], v[210:213], v[80:83]
	v_mfma_f32_16x16x32_bf16 v[64:67], v[182:185], v[214:217], v[64:67]
	v_mfma_f32_16x16x32_bf16 v[64:67], v[186:189], v[218:221], v[64:67]
	s_setprio 0
	s_barrier
	s_branch .Lrot_1235
